# GEMM k-loops: next-stage LDS writes (A and B tiles) woven between the first 32 MFMAs with recomputed lgkmcnt waits
# speedup vs baseline: 1.1159x; 1.0233x over previous
; #define LD_AF(dst, ks_) _Pragma("unroll") for (int i = 0; i < 8; ++i) dst[i] = *(const h8*)(sA + i * 16 * G_LD + (ks_) * 32)
; #define LD_BF(dst, ks_, nh_) _Pragma("unroll") for (int i = 0; i < 4; ++i) dst[i] = *(const h8*)(sB + ((nh_) * 4 + i) * 16 * G_LD + (ks_) * 32)
; #define MMA_BLK(afx, bfx, nh_) _Pragma("unroll") for (int mi = 0; mi < 8; ++mi) _Pragma("unroll") for (int ni = 0; ni < 4; ++ni) mfma16_acc(acc[mi][(nh_) * 4 + ni], bfx[ni], afx[mi])
; template <class Epi>
; __device__ __forceinline__ void gemm_run(const GemmArgs g, Epi epi, char* smem) {
;     ...
;       const hf* sA = sbase + (kt & 1) * G_STAGE + (wm * 128 + fr) * G_LD + fqs;
;       const hf* sB = sbase + (kt & 1) * G_STAGE + (256 + wn * 128 + fr) * G_LD + fqs;
;       hf* st = sbase + ((kt + 1) & 1) * G_STAGE;
;       h8 afA[8], afB[8], bfA[4], bfB[4];
;     ...
;       LD_AF(afA, 0); LD_BF(bfA, 0, 0);
;       if (kt + 1 < nk) {
; #pragma unroll
;         for (int i = 0; i < 8; ++i) *(u4*)(st + (lr + 32 * i) * G_LD + lcw) = ra[i];
;       }
;       __builtin_amdgcn_sched_barrier(0);
;       LD_BF(bfB, 0, 1);
;       MMA_BLK(afA, bfA, 0);
;       __builtin_amdgcn_sched_barrier(0);
;       if (kt + 1 < nk) {
; #pragma unroll
;         for (int i = 0; i < 8; ++i) *(u4*)(st + (256 + lr + 32 * i) * G_LD + lcw) = rb[i];
;       }
;       LD_AF(afB, 1); LD_BF(bfA, 1, 0);
;       MMA_BLK(afA, bfB, 1);
.LBB0_197:
	s_bitcmp1_b32 s11, 0
	s_cselect_b32 s7, 0x12000, 0
	s_add_i32 s7, s7, 16
	v_add3_u32 v56, s7, v100, v109
	v_add3_u32 v94, s7, v101, v109
	ds_read_b128 v[4:7], v56 offset:13824
	ds_read_b128 v[16:19], v94 offset:36864
	ds_read_b128 v[12:15], v94 offset:39168
	ds_read_b128 v[8:11], v94 offset:41472
	ds_read_b128 v[0:3], v94 offset:43776
	ds_read_b128 v[76:79], v56
	ds_read_b128 v[72:75], v56 offset:2304
	ds_read_b128 v[52:55], v56 offset:4608
	ds_read_b128 v[44:47], v56 offset:6912
	ds_read_b128 v[48:51], v56 offset:9216
	ds_read_b128 v[40:43], v56 offset:11520
	ds_read_b128 v[32:35], v56 offset:16128
	s_mov_b32 s6, s11
	s_add_i32 s11, s11, 1
	s_bitcmp1_b32 s11, 0
	s_cselect_b32 s7, 0x12000, 0
	v_add_u32_e32 v20, s7, v99
	v_add_u32_e32 v21, v20, v104
	ds_read_b128 v[178:181], v94 offset:46080
	ds_read_b128 v[88:91], v94 offset:48384
	ds_read_b128 v[84:87], v94 offset:50688
	ds_read_b128 v[80:83], v94 offset:52992
	s_waitcnt lgkmcnt(10)
	v_mfma_f32_16x16x32_f16 a[252:255], v[16:19], v[76:79], a[252:255]
	v_mfma_f32_16x16x32_f16 a[240:243], v[12:15], v[76:79], a[240:243]
	s_waitcnt vmcnt(15)
	ds_write_b128 v21, v[110:113]
	v_mfma_f32_16x16x32_f16 a[232:235], v[8:11], v[76:79], a[232:235]
	v_mfma_f32_16x16x32_f16 a[224:227], v[0:3], v[76:79], a[224:227]
	s_waitcnt vmcnt(13)
	ds_write_b128 v21, v[118:121] offset:4608
	s_waitcnt lgkmcnt(11)
	v_mfma_f32_16x16x32_f16 a[216:219], v[16:19], v[72:75], a[216:219]
	v_mfma_f32_16x16x32_f16 a[208:211], v[12:15], v[72:75], a[208:211]
	s_waitcnt vmcnt(11)
	ds_write_b128 v21, v[126:129] offset:9216
	v_mfma_f32_16x16x32_f16 a[200:203], v[8:11], v[72:75], a[200:203]
	v_mfma_f32_16x16x32_f16 a[192:195], v[0:3], v[72:75], a[192:195]
	s_waitcnt vmcnt(9)
	ds_write_b128 v21, v[138:141] offset:13824
	s_waitcnt lgkmcnt(12)
	v_mfma_f32_16x16x32_f16 a[184:187], v[16:19], v[52:55], a[184:187]
	v_mfma_f32_16x16x32_f16 a[176:179], v[12:15], v[52:55], a[176:179]
	s_waitcnt vmcnt(7)
	ds_write_b128 v21, v[146:149] offset:18432
	v_mfma_f32_16x16x32_f16 a[168:171], v[8:11], v[52:55], a[168:171]
	v_mfma_f32_16x16x32_f16 a[160:163], v[0:3], v[52:55], a[160:163]
	s_waitcnt vmcnt(5)
	ds_write_b128 v21, v[154:157] offset:23040
	s_waitcnt lgkmcnt(13)
	v_mfma_f32_16x16x32_f16 a[152:155], v[16:19], v[44:47], a[152:155]
	v_mfma_f32_16x16x32_f16 a[144:147], v[12:15], v[44:47], a[144:147]
	s_waitcnt vmcnt(3)
	ds_write_b128 v21, v[162:165] offset:27648
	v_mfma_f32_16x16x32_f16 a[136:139], v[8:11], v[44:47], a[136:139]
	v_mfma_f32_16x16x32_f16 a[128:131], v[0:3], v[44:47], a[128:131]
	s_waitcnt vmcnt(1)
	ds_write_b128 v21, v[170:173] offset:32256
	s_waitcnt lgkmcnt(14)
	v_mfma_f32_16x16x32_f16 a[120:123], v[16:19], v[48:51], a[120:123]
	v_mfma_f32_16x16x32_f16 a[112:115], v[12:15], v[48:51], a[112:115]
	ds_write_b128 v21, v[114:117] offset:36864
	v_mfma_f32_16x16x32_f16 a[104:107], v[8:11], v[48:51], a[104:107]
	v_mfma_f32_16x16x32_f16 a[96:99], v[0:3], v[48:51], a[96:99]
	ds_write_b128 v21, v[122:125] offset:41472
	s_waitcnt lgkmcnt(14)
	v_mfma_f32_16x16x32_f16 a[88:91], v[16:19], v[40:43], a[88:91]
	v_mfma_f32_16x16x32_f16 a[80:83], v[12:15], v[40:43], a[80:83]
	ds_write_b128 v21, v[134:137] offset:46080
	v_mfma_f32_16x16x32_f16 a[72:75], v[8:11], v[40:43], a[72:75]
	v_mfma_f32_16x16x32_f16 a[64:67], v[0:3], v[40:43], a[64:67]
	ds_write_b128 v21, v[142:145] offset:50688
	v_mfma_f32_16x16x32_f16 a[56:59], v[16:19], v[4:7], a[56:59]
	v_mfma_f32_16x16x32_f16 a[48:51], v[12:15], v[4:7], a[48:51]
	ds_write_b128 v21, v[150:153] offset:55296
	v_mfma_f32_16x16x32_f16 a[40:43], v[8:11], v[4:7], a[40:43]
	v_mfma_f32_16x16x32_f16 a[32:35], v[0:3], v[4:7], a[32:35]
	ds_write_b128 v21, v[158:161] offset:59904
	s_waitcnt lgkmcnt(14)
	v_mfma_f32_16x16x32_f16 a[24:27], v[16:19], v[32:35], a[24:27]
	v_mfma_f32_16x16x32_f16 a[20:23], v[12:15], v[32:35], a[20:23]
	ds_write_b128 v21, v[166:169] offset:64512
	v_mfma_f32_16x16x32_f16 a[16:19], v[8:11], v[32:35], a[16:19]
	v_mfma_f32_16x16x32_f16 a[8:11], v[0:3], v[32:35], a[8:11]
	v_add_u32_e32 v0, v20, v105
	s_waitcnt vmcnt(0)
	ds_write_b128 v0, v[174:177]
	ds_read_b128 v[36:39], v56 offset:64
	ds_read_b128 v[28:31], v56 offset:2368
	ds_read_b128 v[24:27], v56 offset:4672
	ds_read_b128 v[20:23], v56 offset:6976
	ds_read_b128 v[16:19], v56 offset:9280
	ds_read_b128 v[12:15], v56 offset:11584
	ds_read_b128 v[8:11], v56 offset:13888
	ds_read_b128 v[0:3], v56 offset:16192
	ds_read_b128 v[56:59], v94 offset:36928
	ds_read_b128 v[60:63], v94 offset:39232
	ds_read_b128 v[64:67], v94 offset:41536
	ds_read_b128 v[68:71], v94 offset:43840
	s_cmp_gt_u32 s6, 29
	s_cbranch_scc1 .Lgw0_nl
; #define MMA_BLK(afx, bfx, nh_) _Pragma("unroll") for (int mi = 0; mi < 8; ++mi) _Pragma("unroll") for (int ni = 0; ni < 4; ++ni) mfma16_acc(acc[mi][(nh_) * 4 + ni], bfx[ni], afx[mi])
; template <class Epi>
; __device__ __forceinline__ void gemm_run(const GemmArgs g, Epi epi, char* smem) {
;     ...
;       MMA_BLK(afA, bfB, 1);
;       __builtin_amdgcn_sched_barrier(0);
;       if (kt + 2 < nk) {
;         const int ko = (kt + 2) * 64;
; #pragma unroll
;         for (int i = 0; i < 8; ++i) { ra[i] = __builtin_amdgcn_raw_buffer_load_b128(Ars, aoff, i * astep + ko * 2, 0); rb[i] = __builtin_amdgcn_raw_buffer_load_b128(Brs, boff, i * bstep + ko * 2, 0); }
;       }
	s_waitcnt lgkmcnt(14)
	v_mfma_f32_16x16x32_f16 a[248:251], v[178:181], v[76:79], a[248:251]
	s_waitcnt lgkmcnt(14)
	v_mfma_f32_16x16x32_f16 a[244:247], v[88:91], v[76:79], a[244:247]
	s_waitcnt lgkmcnt(14)
	v_mfma_f32_16x16x32_f16 a[236:239], v[84:87], v[76:79], a[236:239]
	s_add_i32 s12, s9, 0xfff20000
	s_waitcnt lgkmcnt(14)
	v_mfma_f32_16x16x32_f16 a[228:231], v[80:83], v[76:79], a[228:231]
	s_mov_b32 s6, s22
	v_mfma_f32_16x16x32_f16 a[220:223], v[178:181], v[72:75], a[220:223]
	s_mov_b32 s7, s23
	v_mfma_f32_16x16x32_f16 a[212:215], v[88:91], v[72:75], a[212:215]
	buffer_load_dwordx4 v[110:113], v98, s[20:23], s12 offen
	v_mfma_f32_16x16x32_f16 a[204:207], v[84:87], v[72:75], a[204:207]
	buffer_load_dwordx4 v[114:117], v98, s[4:7], s12 offen
	v_mfma_f32_16x16x32_f16 a[196:199], v[80:83], v[72:75], a[196:199]
	s_add_i32 s12, s9, 0xfff40000
	v_mfma_f32_16x16x32_f16 a[188:191], v[178:181], v[52:55], a[188:191]
	buffer_load_dwordx4 v[118:121], v98, s[20:23], s12 offen
	v_mfma_f32_16x16x32_f16 a[180:183], v[88:91], v[52:55], a[180:183]
	buffer_load_dwordx4 v[122:125], v98, s[4:7], s12 offen
	v_mfma_f32_16x16x32_f16 a[172:175], v[84:87], v[52:55], a[172:175]
	s_add_i32 s12, s9, 0xfff60000
	v_mfma_f32_16x16x32_f16 a[164:167], v[80:83], v[52:55], a[164:167]
	buffer_load_dwordx4 v[126:129], v98, s[20:23], s12 offen
	v_mfma_f32_16x16x32_f16 a[156:159], v[178:181], v[44:47], a[156:159]
	buffer_load_dwordx4 v[134:137], v98, s[4:7], s12 offen
	v_mfma_f32_16x16x32_f16 a[148:151], v[88:91], v[44:47], a[148:151]
	s_add_i32 s12, s9, 0xfff80000
	v_mfma_f32_16x16x32_f16 a[140:143], v[84:87], v[44:47], a[140:143]
	buffer_load_dwordx4 v[138:141], v98, s[20:23], s12 offen
	v_mfma_f32_16x16x32_f16 a[132:135], v[80:83], v[44:47], a[132:135]
	buffer_load_dwordx4 v[142:145], v98, s[4:7], s12 offen
	v_mfma_f32_16x16x32_f16 a[124:127], v[178:181], v[48:51], a[124:127]
	s_add_i32 s12, s9, 0xfffa0000
	v_mfma_f32_16x16x32_f16 a[116:119], v[88:91], v[48:51], a[116:119]
	buffer_load_dwordx4 v[146:149], v98, s[20:23], s12 offen
	v_mfma_f32_16x16x32_f16 a[108:111], v[84:87], v[48:51], a[108:111]
	buffer_load_dwordx4 v[150:153], v98, s[4:7], s12 offen
	v_mfma_f32_16x16x32_f16 a[100:103], v[80:83], v[48:51], a[100:103]
	s_add_i32 s12, s9, 0xfffc0000
	v_mfma_f32_16x16x32_f16 a[92:95], v[178:181], v[40:43], a[92:95]
	buffer_load_dwordx4 v[154:157], v98, s[20:23], s12 offen
	v_mfma_f32_16x16x32_f16 a[84:87], v[88:91], v[40:43], a[84:87]
	buffer_load_dwordx4 v[158:161], v98, s[4:7], s12 offen
	v_mfma_f32_16x16x32_f16 a[76:79], v[84:87], v[40:43], a[76:79]
	s_add_i32 s12, s9, 0xfffe0000
	v_mfma_f32_16x16x32_f16 a[68:71], v[80:83], v[40:43], a[68:71]
	buffer_load_dwordx4 v[162:165], v98, s[20:23], s12 offen
	v_mfma_f32_16x16x32_f16 a[60:63], v[178:181], v[4:7], a[60:63]
	buffer_load_dwordx4 v[166:169], v98, s[4:7], s12 offen
	v_mfma_f32_16x16x32_f16 a[52:55], v[88:91], v[4:7], a[52:55]
	buffer_load_dwordx4 v[170:173], v98, s[20:23], s9 offen
	v_mfma_f32_16x16x32_f16 a[44:47], v[84:87], v[4:7], a[44:47]
	buffer_load_dwordx4 v[174:177], v98, s[4:7], s9 offen
	v_mfma_f32_16x16x32_f16 a[36:39], v[80:83], v[4:7], a[36:39]
	v_mfma_f32_16x16x32_f16 a[28:31], v[178:181], v[32:35], a[28:31]
	v_mfma_f32_16x16x32_f16 a[12:15], v[88:91], v[32:35], a[12:15]
	v_mfma_f32_16x16x32_f16 a[4:7], v[84:87], v[32:35], a[4:7]
	v_mfma_f32_16x16x32_f16 a[0:3], v[80:83], v[32:35], a[0:3]
	s_branch .LBB0_196
.Lgw0_nl:
	s_waitcnt lgkmcnt(14)
	v_mfma_f32_16x16x32_f16 a[248:251], v[178:181], v[76:79], a[248:251]
	s_waitcnt lgkmcnt(14)
	v_mfma_f32_16x16x32_f16 a[244:247], v[88:91], v[76:79], a[244:247]
	s_waitcnt lgkmcnt(14)
	v_mfma_f32_16x16x32_f16 a[236:239], v[84:87], v[76:79], a[236:239]
	s_waitcnt lgkmcnt(14)
	v_mfma_f32_16x16x32_f16 a[228:231], v[80:83], v[76:79], a[228:231]
	v_mfma_f32_16x16x32_f16 a[220:223], v[178:181], v[72:75], a[220:223]
	v_mfma_f32_16x16x32_f16 a[212:215], v[88:91], v[72:75], a[212:215]
	v_mfma_f32_16x16x32_f16 a[204:207], v[84:87], v[72:75], a[204:207]
	v_mfma_f32_16x16x32_f16 a[196:199], v[80:83], v[72:75], a[196:199]
	v_mfma_f32_16x16x32_f16 a[188:191], v[178:181], v[52:55], a[188:191]
	v_mfma_f32_16x16x32_f16 a[180:183], v[88:91], v[52:55], a[180:183]
	v_mfma_f32_16x16x32_f16 a[172:175], v[84:87], v[52:55], a[172:175]
	v_mfma_f32_16x16x32_f16 a[164:167], v[80:83], v[52:55], a[164:167]
	v_mfma_f32_16x16x32_f16 a[156:159], v[178:181], v[44:47], a[156:159]
	v_mfma_f32_16x16x32_f16 a[148:151], v[88:91], v[44:47], a[148:151]
	v_mfma_f32_16x16x32_f16 a[140:143], v[84:87], v[44:47], a[140:143]
	v_mfma_f32_16x16x32_f16 a[132:135], v[80:83], v[44:47], a[132:135]
	v_mfma_f32_16x16x32_f16 a[124:127], v[178:181], v[48:51], a[124:127]
	v_mfma_f32_16x16x32_f16 a[116:119], v[88:91], v[48:51], a[116:119]
	v_mfma_f32_16x16x32_f16 a[108:111], v[84:87], v[48:51], a[108:111]
	v_mfma_f32_16x16x32_f16 a[100:103], v[80:83], v[48:51], a[100:103]
	v_mfma_f32_16x16x32_f16 a[92:95], v[178:181], v[40:43], a[92:95]
	v_mfma_f32_16x16x32_f16 a[84:87], v[88:91], v[40:43], a[84:87]
	v_mfma_f32_16x16x32_f16 a[76:79], v[84:87], v[40:43], a[76:79]
	v_mfma_f32_16x16x32_f16 a[68:71], v[80:83], v[40:43], a[68:71]
	v_mfma_f32_16x16x32_f16 a[60:63], v[178:181], v[4:7], a[60:63]
	v_mfma_f32_16x16x32_f16 a[52:55], v[88:91], v[4:7], a[52:55]
	v_mfma_f32_16x16x32_f16 a[44:47], v[84:87], v[4:7], a[44:47]
	v_mfma_f32_16x16x32_f16 a[36:39], v[80:83], v[4:7], a[36:39]
	v_mfma_f32_16x16x32_f16 a[28:31], v[178:181], v[32:35], a[28:31]
	v_mfma_f32_16x16x32_f16 a[12:15], v[88:91], v[32:35], a[12:15]
	v_mfma_f32_16x16x32_f16 a[4:7], v[84:87], v[32:35], a[4:7]
	v_mfma_f32_16x16x32_f16 a[0:3], v[80:83], v[32:35], a[0:3]
	s_branch .LBB0_196

; #define LD_AF(dst, ks_) _Pragma("unroll") for (int i = 0; i < 8; ++i) dst[i] = *(const h8*)(sA + i * 16 * G_LD + (ks_) * 32)
; #define LD_BF(dst, ks_, nh_) _Pragma("unroll") for (int i = 0; i < 4; ++i) dst[i] = *(const h8*)(sB + ((nh_) * 4 + i) * 16 * G_LD + (ks_) * 32)
; #define MMA_BLK(afx, bfx, nh_) _Pragma("unroll") for (int mi = 0; mi < 8; ++mi) _Pragma("unroll") for (int ni = 0; ni < 4; ++ni) mfma16_acc(acc[mi][(nh_) * 4 + ni], bfx[ni], afx[mi])
; template <class Epi>
; __device__ __forceinline__ void gemm_run(const GemmArgs g, Epi epi, char* smem) {
;     ...
;       const hf* sA = sbase + (kt & 1) * G_STAGE + (wm * 128 + fr) * G_LD + fqs;
;       const hf* sB = sbase + (kt & 1) * G_STAGE + (256 + wn * 128 + fr) * G_LD + fqs;
;       hf* st = sbase + ((kt + 1) & 1) * G_STAGE;
;       h8 afA[8], afB[8], bfA[4], bfB[4];
;     ...
;       LD_AF(afA, 0); LD_BF(bfA, 0, 0);
;       if (kt + 1 < nk) {
; #pragma unroll
;         for (int i = 0; i < 8; ++i) *(u4*)(st + (lr + 32 * i) * G_LD + lcw) = ra[i];
;       }
;       __builtin_amdgcn_sched_barrier(0);
;       LD_BF(bfB, 0, 1);
;       MMA_BLK(afA, bfA, 0);
;       __builtin_amdgcn_sched_barrier(0);
;       if (kt + 1 < nk) {
; #pragma unroll
;         for (int i = 0; i < 8; ++i) *(u4*)(st + (256 + lr + 32 * i) * G_LD + lcw) = rb[i];
;       }
;       LD_AF(afB, 1); LD_BF(bfA, 1, 0);
;       MMA_BLK(afA, bfB, 1);
.LBB0_599:
	s_bitcmp1_b32 s17, 0
	s_cselect_b32 s11, 0x12000, 0
	s_add_i32 s11, s11, 16
	v_add3_u32 v56, s11, v96, v104
	v_add3_u32 v106, s11, v97, v104
	ds_read_b128 v[8:11], v56 offset:13824
	ds_read_b128 v[16:19], v106 offset:36864
	ds_read_b128 v[12:15], v106 offset:39168
	ds_read_b128 v[4:7], v106 offset:41472
	ds_read_b128 v[0:3], v106 offset:43776
	ds_read_b128 v[76:79], v56
	ds_read_b128 v[72:75], v56 offset:2304
	ds_read_b128 v[52:55], v56 offset:4608
	ds_read_b128 v[44:47], v56 offset:6912
	ds_read_b128 v[48:51], v56 offset:9216
	ds_read_b128 v[40:43], v56 offset:11520
	ds_read_b128 v[36:39], v56 offset:16128
	s_mov_b32 s10, s17
	s_add_i32 s17, s17, 1
	s_bitcmp1_b32 s17, 0
	s_cselect_b32 s11, 0x12000, 0
	v_add_u32_e32 v20, s11, v94
	v_add_u32_e32 v21, v20, v99
	ds_read_b128 v[174:177], v106 offset:46080
	ds_read_b128 v[88:91], v106 offset:48384
	ds_read_b128 v[84:87], v106 offset:50688
	ds_read_b128 v[80:83], v106 offset:52992
	s_waitcnt lgkmcnt(10)
	v_mfma_f32_16x16x32_f16 a[0:3], v[16:19], v[76:79], a[0:3]
	v_mfma_f32_16x16x32_f16 a[4:7], v[12:15], v[76:79], a[4:7]
	s_waitcnt vmcnt(15)
	ds_write_b128 v21, v[108:111]
	v_mfma_f32_16x16x32_f16 a[8:11], v[4:7], v[76:79], a[8:11]
	v_mfma_f32_16x16x32_f16 a[24:27], v[0:3], v[76:79], a[24:27]
	s_waitcnt vmcnt(13)
	ds_write_b128 v21, v[112:115] offset:4608
	s_waitcnt lgkmcnt(11)
	v_mfma_f32_16x16x32_f16 a[12:15], v[16:19], v[72:75], a[12:15]
	v_mfma_f32_16x16x32_f16 a[16:19], v[12:15], v[72:75], a[16:19]
	s_waitcnt vmcnt(10)
	ds_write_b128 v21, v[116:119] offset:9216
	v_mfma_f32_16x16x32_f16 a[28:31], v[4:7], v[72:75], a[28:31]
	v_mfma_f32_16x16x32_f16 a[44:47], v[0:3], v[72:75], a[44:47]
	s_waitcnt vmcnt(9)
	ds_write_b128 v21, v[128:131] offset:13824
	s_waitcnt lgkmcnt(12)
	v_mfma_f32_16x16x32_f16 a[20:23], v[16:19], v[52:55], a[20:23]
	v_mfma_f32_16x16x32_f16 a[36:39], v[12:15], v[52:55], a[36:39]
	s_waitcnt vmcnt(6)
	ds_write_b128 v21, v[134:137] offset:18432
	v_mfma_f32_16x16x32_f16 a[48:51], v[4:7], v[52:55], a[48:51]
	v_mfma_f32_16x16x32_f16 a[60:63], v[0:3], v[52:55], a[60:63]
	s_waitcnt vmcnt(5)
	ds_write_b128 v21, v[146:149] offset:23040
	s_waitcnt lgkmcnt(13)
	v_mfma_f32_16x16x32_f16 a[32:35], v[16:19], v[44:47], a[32:35]
	v_mfma_f32_16x16x32_f16 a[52:55], v[12:15], v[44:47], a[52:55]
	s_waitcnt vmcnt(3)
	ds_write_b128 v21, v[154:157] offset:27648
	v_mfma_f32_16x16x32_f16 a[64:67], v[4:7], v[44:47], a[64:67]
	v_mfma_f32_16x16x32_f16 a[76:79], v[0:3], v[44:47], a[76:79]
	s_waitcnt vmcnt(1)
	ds_write_b128 v21, v[162:165] offset:32256
	s_waitcnt lgkmcnt(14)
	v_mfma_f32_16x16x32_f16 a[40:43], v[16:19], v[48:51], a[40:43]
	v_mfma_f32_16x16x32_f16 a[68:71], v[12:15], v[48:51], a[68:71]
	s_waitcnt vmcnt(7)
	ds_write_b128 v21, v[120:123] offset:36864
	v_mfma_f32_16x16x32_f16 a[80:83], v[4:7], v[48:51], a[80:83]
	v_mfma_f32_16x16x32_f16 a[92:95], v[0:3], v[48:51], a[92:95]
	s_waitcnt vmcnt(6)
	ds_write_b128 v21, v[124:127] offset:41472
	s_waitcnt lgkmcnt(14)
	v_mfma_f32_16x16x32_f16 a[56:59], v[16:19], v[40:43], a[56:59]
	v_mfma_f32_16x16x32_f16 a[84:87], v[12:15], v[40:43], a[84:87]
	s_waitcnt vmcnt(2)
	ds_write_b128 v21, v[138:141] offset:46080
	v_mfma_f32_16x16x32_f16 a[96:99], v[4:7], v[40:43], a[96:99]
	v_mfma_f32_16x16x32_f16 a[104:107], v[0:3], v[40:43], a[104:107]
	ds_write_b128 v21, v[142:145] offset:50688
	v_mfma_f32_16x16x32_f16 a[72:75], v[16:19], v[8:11], a[72:75]
	v_mfma_f32_16x16x32_f16 a[100:103], v[12:15], v[8:11], a[100:103]
	ds_write_b128 v21, v[150:153] offset:55296
	v_mfma_f32_16x16x32_f16 a[108:111], v[4:7], v[8:11], a[108:111]
	v_mfma_f32_16x16x32_f16 a[124:127], v[0:3], v[8:11], a[124:127]
	ds_write_b128 v21, v[158:161] offset:59904
	s_waitcnt lgkmcnt(14)
	v_mfma_f32_16x16x32_f16 a[88:91], v[16:19], v[36:39], a[88:91]
	v_mfma_f32_16x16x32_f16 a[112:115], v[12:15], v[36:39], a[112:115]
	s_waitcnt vmcnt(1)
	ds_write_b128 v21, v[166:169] offset:64512
	v_mfma_f32_16x16x32_f16 a[116:119], v[4:7], v[36:39], a[116:119]
	v_mfma_f32_16x16x32_f16 a[120:123], v[0:3], v[36:39], a[120:123]
	v_add_u32_e32 v0, v20, v100
	s_waitcnt vmcnt(0)
	ds_write_b128 v0, v[170:173]
	ds_read_b128 v[32:35], v56 offset:64
	ds_read_b128 v[28:31], v56 offset:2368
	ds_read_b128 v[24:27], v56 offset:4672
	ds_read_b128 v[20:23], v56 offset:6976
	ds_read_b128 v[16:19], v56 offset:9280
	ds_read_b128 v[12:15], v56 offset:11584
	ds_read_b128 v[4:7], v56 offset:13888
	ds_read_b128 v[0:3], v56 offset:16192
	ds_read_b128 v[56:59], v106 offset:36928
	ds_read_b128 v[60:63], v106 offset:39232
	ds_read_b128 v[64:67], v106 offset:41536
	ds_read_b128 v[68:71], v106 offset:43840
	s_cmp_gt_u32 s10, 5
	s_cbranch_scc1 .Lgw1_nl
; #define MMA_BLK(afx, bfx, nh_) _Pragma("unroll") for (int mi = 0; mi < 8; ++mi) _Pragma("unroll") for (int ni = 0; ni < 4; ++ni) mfma16_acc(acc[mi][(nh_) * 4 + ni], bfx[ni], afx[mi])
; template <class Epi>
; __device__ __forceinline__ void gemm_run(const GemmArgs g, Epi epi, char* smem) {
;     ...
;       MMA_BLK(afA, bfB, 1);
;       __builtin_amdgcn_sched_barrier(0);
;       if (kt + 2 < nk) {
;         const int ko = (kt + 2) * 64;
; #pragma unroll
;         for (int i = 0; i < 8; ++i) { ra[i] = __builtin_amdgcn_raw_buffer_load_b128(Ars, aoff, i * astep + ko * 2, 0); rb[i] = __builtin_amdgcn_raw_buffer_load_b128(Brs, boff, i * bstep + ko * 2, 0); }
;       }
	s_waitcnt lgkmcnt(14)
	v_mfma_f32_16x16x32_f16 a[132:135], v[174:177], v[76:79], a[132:135]
	s_waitcnt lgkmcnt(14)
	v_mfma_f32_16x16x32_f16 a[136:139], v[88:91], v[76:79], a[136:139]
	s_waitcnt lgkmcnt(14)
	v_mfma_f32_16x16x32_f16 a[144:147], v[84:87], v[76:79], a[144:147]
	s_add_i32 s23, s15, 0xfffac000
	s_waitcnt lgkmcnt(14)
	v_mfma_f32_16x16x32_f16 a[156:159], v[80:83], v[76:79], a[156:159]
	s_mov_b32 s10, s6
	v_mfma_f32_16x16x32_f16 a[140:143], v[174:177], v[72:75], a[140:143]
	s_mov_b32 s11, s7
	v_mfma_f32_16x16x32_f16 a[148:151], v[88:91], v[72:75], a[148:151]
	buffer_load_dwordx4 v[108:111], v92, s[4:7], s23 offen
	v_mfma_f32_16x16x32_f16 a[164:167], v[84:87], v[72:75], a[164:167]
	buffer_load_dwordx4 v[120:123], v93, s[8:11], s23 offen
	v_mfma_f32_16x16x32_f16 a[184:187], v[80:83], v[72:75], a[184:187]
	s_add_i32 s23, s15, 0xfffb8000
	v_mfma_f32_16x16x32_f16 a[152:155], v[174:177], v[52:55], a[152:155]
	s_add_i32 s26, s15, 0xfffbc000
	v_mfma_f32_16x16x32_f16 a[168:171], v[88:91], v[52:55], a[168:171]
	buffer_load_dwordx4 v[112:115], v92, s[4:7], s23 offen
	v_mfma_f32_16x16x32_f16 a[180:183], v[84:87], v[52:55], a[180:183]
	buffer_load_dwordx4 v[138:141], v93, s[8:11], s26 offen
	v_mfma_f32_16x16x32_f16 a[200:203], v[80:83], v[52:55], a[200:203]
	s_add_i32 s23, s15, 0xfffb4000
	v_mfma_f32_16x16x32_f16 a[160:163], v[174:177], v[44:47], a[160:163]
	buffer_load_dwordx4 v[124:127], v93, s[8:11], s23 offen
	v_mfma_f32_16x16x32_f16 a[176:179], v[88:91], v[44:47], a[176:179]
	s_add_i32 s23, s15, 0xfffc4000
	v_mfma_f32_16x16x32_f16 a[196:199], v[84:87], v[44:47], a[196:199]
	s_add_i32 s26, s15, 0xfffd0000
	v_mfma_f32_16x16x32_f16 a[216:219], v[80:83], v[44:47], a[216:219]
	buffer_load_dwordx4 v[116:119], v92, s[4:7], s23 offen
	v_mfma_f32_16x16x32_f16 a[172:175], v[174:177], v[48:51], a[172:175]
	buffer_load_dwordx4 v[128:131], v92, s[4:7], s26 offen
	v_mfma_f32_16x16x32_f16 a[192:195], v[88:91], v[48:51], a[192:195]
	buffer_load_dwordx4 v[142:145], v93, s[8:11], s23 offen
	v_mfma_f32_16x16x32_f16 a[212:215], v[84:87], v[48:51], a[212:215]
	s_add_i32 s26, s15, 0xfffcc000
	v_mfma_f32_16x16x32_f16 a[232:235], v[80:83], v[48:51], a[232:235]
	s_add_i32 s23, s15, 0xfffdc000
	v_mfma_f32_16x16x32_f16 a[188:191], v[174:177], v[40:43], a[188:191]
	buffer_load_dwordx4 v[150:153], v93, s[8:11], s26 offen
	v_mfma_f32_16x16x32_f16 a[208:211], v[88:91], v[40:43], a[208:211]
	s_add_i32 s26, s15, 0xfffe8000
	v_mfma_f32_16x16x32_f16 a[228:231], v[84:87], v[40:43], a[228:231]
	buffer_load_dwordx4 v[134:137], v92, s[4:7], s23 offen
	v_mfma_f32_16x16x32_f16 a[244:247], v[80:83], v[40:43], a[244:247]
	buffer_load_dwordx4 v[146:149], v92, s[4:7], s26 offen
	v_mfma_f32_16x16x32_f16 a[204:207], v[174:177], v[8:11], a[204:207]
	s_add_i32 s26, s15, 0xfffd4000
	v_mfma_f32_16x16x32_f16 a[224:227], v[88:91], v[8:11], a[224:227]
	buffer_load_dwordx4 v[158:161], v93, s[8:11], s26 offen
	v_mfma_f32_16x16x32_f16 a[240:243], v[84:87], v[8:11], a[240:243]
	s_add_i32 s26, s15, 0xffff4000
	v_mfma_f32_16x16x32_f16 a[252:255], v[80:83], v[8:11], a[252:255]
	buffer_load_dwordx4 v[154:157], v92, s[4:7], s26 offen
	v_mfma_f32_16x16x32_f16 a[220:223], v[174:177], v[36:39], a[220:223]
	buffer_load_dwordx4 v[166:169], v93, s[8:11], s23 offen
	v_mfma_f32_16x16x32_f16 a[236:239], v[88:91], v[36:39], a[236:239]
	buffer_load_dwordx4 v[162:165], v92, s[4:7], s15 offen
	v_mfma_f32_16x16x32_f16 a[248:251], v[84:87], v[36:39], a[248:251]
	s_add_i32 s23, s15, 0xfffe4000
	v_mfma_f32_16x16x32_f16 a[128:131], v[80:83], v[36:39], a[128:131]
	buffer_load_dwordx4 v[170:173], v93, s[8:11], s23 offen
	s_branch .LBB0_598
.Lgw1_nl:
	s_waitcnt lgkmcnt(14)
	v_mfma_f32_16x16x32_f16 a[132:135], v[174:177], v[76:79], a[132:135]
	s_waitcnt lgkmcnt(14)
	v_mfma_f32_16x16x32_f16 a[136:139], v[88:91], v[76:79], a[136:139]
	s_waitcnt lgkmcnt(14)
	v_mfma_f32_16x16x32_f16 a[144:147], v[84:87], v[76:79], a[144:147]
	s_waitcnt lgkmcnt(14)
	v_mfma_f32_16x16x32_f16 a[156:159], v[80:83], v[76:79], a[156:159]
	v_mfma_f32_16x16x32_f16 a[140:143], v[174:177], v[72:75], a[140:143]
	v_mfma_f32_16x16x32_f16 a[148:151], v[88:91], v[72:75], a[148:151]
	v_mfma_f32_16x16x32_f16 a[164:167], v[84:87], v[72:75], a[164:167]
	v_mfma_f32_16x16x32_f16 a[184:187], v[80:83], v[72:75], a[184:187]
	v_mfma_f32_16x16x32_f16 a[152:155], v[174:177], v[52:55], a[152:155]
	v_mfma_f32_16x16x32_f16 a[168:171], v[88:91], v[52:55], a[168:171]
	v_mfma_f32_16x16x32_f16 a[180:183], v[84:87], v[52:55], a[180:183]
	v_mfma_f32_16x16x32_f16 a[200:203], v[80:83], v[52:55], a[200:203]
	v_mfma_f32_16x16x32_f16 a[160:163], v[174:177], v[44:47], a[160:163]
	v_mfma_f32_16x16x32_f16 a[176:179], v[88:91], v[44:47], a[176:179]
	v_mfma_f32_16x16x32_f16 a[196:199], v[84:87], v[44:47], a[196:199]
	v_mfma_f32_16x16x32_f16 a[216:219], v[80:83], v[44:47], a[216:219]
	v_mfma_f32_16x16x32_f16 a[172:175], v[174:177], v[48:51], a[172:175]
	v_mfma_f32_16x16x32_f16 a[192:195], v[88:91], v[48:51], a[192:195]
	v_mfma_f32_16x16x32_f16 a[212:215], v[84:87], v[48:51], a[212:215]
	v_mfma_f32_16x16x32_f16 a[232:235], v[80:83], v[48:51], a[232:235]
	v_mfma_f32_16x16x32_f16 a[188:191], v[174:177], v[40:43], a[188:191]
	v_mfma_f32_16x16x32_f16 a[208:211], v[88:91], v[40:43], a[208:211]
	v_mfma_f32_16x16x32_f16 a[228:231], v[84:87], v[40:43], a[228:231]
	v_mfma_f32_16x16x32_f16 a[244:247], v[80:83], v[40:43], a[244:247]
	v_mfma_f32_16x16x32_f16 a[204:207], v[174:177], v[8:11], a[204:207]
	v_mfma_f32_16x16x32_f16 a[224:227], v[88:91], v[8:11], a[224:227]
	v_mfma_f32_16x16x32_f16 a[240:243], v[84:87], v[8:11], a[240:243]
	v_mfma_f32_16x16x32_f16 a[252:255], v[80:83], v[8:11], a[252:255]
	v_mfma_f32_16x16x32_f16 a[220:223], v[174:177], v[36:39], a[220:223]
	v_mfma_f32_16x16x32_f16 a[236:239], v[88:91], v[36:39], a[236:239]
	v_mfma_f32_16x16x32_f16 a[248:251], v[84:87], v[36:39], a[248:251]
	v_mfma_f32_16x16x32_f16 a[128:131], v[80:83], v[36:39], a[128:131]
	s_branch .LBB0_598

; #define LD_AF(dst, ks_) _Pragma("unroll") for (int i = 0; i < 8; ++i) dst[i] = *(const h8*)(sA + i * 16 * G_LD + (ks_) * 32)
; #define LD_BF(dst, ks_, nh_) _Pragma("unroll") for (int i = 0; i < 4; ++i) dst[i] = *(const h8*)(sB + ((nh_) * 4 + i) * 16 * G_LD + (ks_) * 32)
; #define MMA_BLK(afx, bfx, nh_) _Pragma("unroll") for (int mi = 0; mi < 8; ++mi) _Pragma("unroll") for (int ni = 0; ni < 4; ++ni) mfma16_acc(acc[mi][(nh_) * 4 + ni], bfx[ni], afx[mi])
; template <class Epi>
; __device__ __forceinline__ void gemm_run(const GemmArgs g, Epi epi, char* smem) {
;     ...
;       const hf* sA = sbase + (kt & 1) * G_STAGE + (wm * 128 + fr) * G_LD + fqs;
;       const hf* sB = sbase + (kt & 1) * G_STAGE + (256 + wn * 128 + fr) * G_LD + fqs;
;       hf* st = sbase + ((kt + 1) & 1) * G_STAGE;
;       h8 afA[8], afB[8], bfA[4], bfB[4];
;     ...
;       LD_AF(afA, 0); LD_BF(bfA, 0, 0);
;       if (kt + 1 < nk) {
; #pragma unroll
;         for (int i = 0; i < 8; ++i) *(u4*)(st + (lr + 32 * i) * G_LD + lcw) = ra[i];
;       }
;       __builtin_amdgcn_sched_barrier(0);
;       LD_BF(bfB, 0, 1);
;       MMA_BLK(afA, bfA, 0);
;       __builtin_amdgcn_sched_barrier(0);
;       if (kt + 1 < nk) {
; #pragma unroll
;         for (int i = 0; i < 8; ++i) *(u4*)(st + (256 + lr + 32 * i) * G_LD + lcw) = rb[i];
;       }
;       LD_AF(afB, 1); LD_BF(bfA, 1, 0);
;       MMA_BLK(afA, bfB, 1);
.LBB0_631:
	s_bitcmp1_b32 s75, 0
	s_cselect_b32 s11, 0x12000, 0
	s_add_i32 s11, s11, 16
	v_add3_u32 v56, s11, v136, v145
	v_add3_u32 v94, s11, v138, v145
	ds_read_b128 v[4:7], v56 offset:13824
	ds_read_b128 v[16:19], v94 offset:36864
	ds_read_b128 v[12:15], v94 offset:39168
	ds_read_b128 v[8:11], v94 offset:41472
	ds_read_b128 v[0:3], v94 offset:43776
	ds_read_b128 v[76:79], v56
	ds_read_b128 v[72:75], v56 offset:2304
	ds_read_b128 v[52:55], v56 offset:4608
	ds_read_b128 v[44:47], v56 offset:6912
	ds_read_b128 v[48:51], v56 offset:9216
	ds_read_b128 v[40:43], v56 offset:11520
	ds_read_b128 v[32:35], v56 offset:16128
	s_mov_b32 s10, s75
	s_add_i32 s75, s75, 1
	s_bitcmp1_b32 s75, 0
	s_cselect_b32 s11, 0x12000, 0
	v_add_u32_e32 v20, s11, v135
	v_add_u32_e32 v21, v20, v140
	ds_read_b128 v[174:177], v94 offset:46080
	ds_read_b128 v[88:91], v94 offset:48384
	ds_read_b128 v[84:87], v94 offset:50688
	ds_read_b128 v[80:83], v94 offset:52992
	s_waitcnt lgkmcnt(10)
	v_mfma_f32_16x16x32_f16 a[252:255], v[16:19], v[76:79], a[252:255]
	v_mfma_f32_16x16x32_f16 a[248:251], v[12:15], v[76:79], a[248:251]
	s_waitcnt vmcnt(15)
	ds_write_b128 v21, v[96:99]
	v_mfma_f32_16x16x32_f16 a[244:247], v[8:11], v[76:79], a[244:247]
	v_mfma_f32_16x16x32_f16 a[236:239], v[0:3], v[76:79], a[236:239]
	s_waitcnt vmcnt(13)
	ds_write_b128 v21, v[104:107] offset:4608
	s_waitcnt lgkmcnt(11)
	v_mfma_f32_16x16x32_f16 a[220:223], v[16:19], v[72:75], a[220:223]
	v_mfma_f32_16x16x32_f16 a[216:219], v[12:15], v[72:75], a[216:219]
	s_waitcnt vmcnt(11)
	ds_write_b128 v21, v[108:111] offset:9216
	v_mfma_f32_16x16x32_f16 a[212:215], v[8:11], v[72:75], a[212:215]
	v_mfma_f32_16x16x32_f16 a[204:207], v[0:3], v[72:75], a[204:207]
	s_waitcnt vmcnt(9)
	ds_write_b128 v21, v[120:123] offset:13824
	s_waitcnt lgkmcnt(12)
	v_mfma_f32_16x16x32_f16 a[188:191], v[16:19], v[52:55], a[188:191]
	v_mfma_f32_16x16x32_f16 a[184:187], v[12:15], v[52:55], a[184:187]
	s_waitcnt vmcnt(7)
	ds_write_b128 v21, v[124:127] offset:18432
	v_mfma_f32_16x16x32_f16 a[180:183], v[8:11], v[52:55], a[180:183]
	v_mfma_f32_16x16x32_f16 a[172:175], v[0:3], v[52:55], a[172:175]
	s_waitcnt vmcnt(5)
	ds_write_b128 v21, v[150:153] offset:23040
	s_waitcnt lgkmcnt(13)
	v_mfma_f32_16x16x32_f16 a[156:159], v[16:19], v[44:47], a[156:159]
	v_mfma_f32_16x16x32_f16 a[152:155], v[12:15], v[44:47], a[152:155]
	s_waitcnt vmcnt(3)
	ds_write_b128 v21, v[154:157] offset:27648
	v_mfma_f32_16x16x32_f16 a[148:151], v[8:11], v[44:47], a[148:151]
	v_mfma_f32_16x16x32_f16 a[140:143], v[0:3], v[44:47], a[140:143]
	s_waitcnt vmcnt(1)
	ds_write_b128 v21, v[162:165] offset:32256
	s_waitcnt lgkmcnt(14)
	v_mfma_f32_16x16x32_f16 a[124:127], v[16:19], v[48:51], a[124:127]
	v_mfma_f32_16x16x32_f16 a[120:123], v[12:15], v[48:51], a[120:123]
	s_waitcnt vmcnt(7)
	ds_write_b128 v21, v[100:103] offset:36864
	v_mfma_f32_16x16x32_f16 a[116:119], v[8:11], v[48:51], a[116:119]
	v_mfma_f32_16x16x32_f16 a[108:111], v[0:3], v[48:51], a[108:111]
	s_waitcnt vmcnt(6)
	ds_write_b128 v21, v[112:115] offset:41472
	s_waitcnt lgkmcnt(14)
	v_mfma_f32_16x16x32_f16 a[92:95], v[16:19], v[40:43], a[92:95]
	v_mfma_f32_16x16x32_f16 a[88:91], v[12:15], v[40:43], a[88:91]
	s_waitcnt vmcnt(5)
	ds_write_b128 v21, v[116:119] offset:46080
	v_mfma_f32_16x16x32_f16 a[84:87], v[8:11], v[40:43], a[84:87]
	v_mfma_f32_16x16x32_f16 a[76:79], v[0:3], v[40:43], a[76:79]
	s_waitcnt vmcnt(4)
	ds_write_b128 v21, v[128:131] offset:50688
	v_mfma_f32_16x16x32_f16 a[60:63], v[16:19], v[4:7], a[60:63]
	v_mfma_f32_16x16x32_f16 a[56:59], v[12:15], v[4:7], a[56:59]
	s_waitcnt vmcnt(3)
	ds_write_b128 v21, v[146:149] offset:55296
	v_mfma_f32_16x16x32_f16 a[52:55], v[8:11], v[4:7], a[52:55]
	v_mfma_f32_16x16x32_f16 a[44:47], v[0:3], v[4:7], a[44:47]
	s_waitcnt vmcnt(2)
	ds_write_b128 v21, v[158:161] offset:59904
	s_waitcnt lgkmcnt(14)
	v_mfma_f32_16x16x32_f16 a[28:31], v[16:19], v[32:35], a[28:31]
	v_mfma_f32_16x16x32_f16 a[24:27], v[12:15], v[32:35], a[24:27]
	s_waitcnt vmcnt(1)
	ds_write_b128 v21, v[166:169] offset:64512
	v_mfma_f32_16x16x32_f16 a[20:23], v[8:11], v[32:35], a[20:23]
	v_mfma_f32_16x16x32_f16 a[12:15], v[0:3], v[32:35], a[12:15]
	v_add_u32_e32 v0, v20, v141
	s_waitcnt vmcnt(0)
	ds_write_b128 v0, v[170:173]
	ds_read_b128 v[36:39], v56 offset:64
	ds_read_b128 v[28:31], v56 offset:2368
	ds_read_b128 v[24:27], v56 offset:4672
	ds_read_b128 v[20:23], v56 offset:6976
	ds_read_b128 v[16:19], v56 offset:9280
	ds_read_b128 v[12:15], v56 offset:11584
	ds_read_b128 v[8:11], v56 offset:13888
	ds_read_b128 v[0:3], v56 offset:16192
	ds_read_b128 v[56:59], v94 offset:36928
	ds_read_b128 v[60:63], v94 offset:39232
	ds_read_b128 v[64:67], v94 offset:41536
	ds_read_b128 v[68:71], v94 offset:43840
	s_cmp_gt_u32 s10, 9
	s_cbranch_scc1 .Lgw2_nl
; #define MMA_BLK(afx, bfx, nh_) _Pragma("unroll") for (int mi = 0; mi < 8; ++mi) _Pragma("unroll") for (int ni = 0; ni < 4; ++ni) mfma16_acc(acc[mi][(nh_) * 4 + ni], bfx[ni], afx[mi])
; template <class Epi>
; __device__ __forceinline__ void gemm_run(const GemmArgs g, Epi epi, char* smem) {
;     ...
;       MMA_BLK(afA, bfB, 1);
;       __builtin_amdgcn_sched_barrier(0);
;       if (kt + 2 < nk) {
;         const int ko = (kt + 2) * 64;
; #pragma unroll
;         for (int i = 0; i < 8; ++i) { ra[i] = __builtin_amdgcn_raw_buffer_load_b128(Ars, aoff, i * astep + ko * 2, 0); rb[i] = __builtin_amdgcn_raw_buffer_load_b128(Brs, boff, i * bstep + ko * 2, 0); }
;       }
	s_waitcnt lgkmcnt(14)
	v_mfma_f32_16x16x32_f16 a[240:243], v[174:177], v[76:79], a[240:243]
	s_waitcnt lgkmcnt(14)
	v_mfma_f32_16x16x32_f16 a[232:235], v[88:91], v[76:79], a[232:235]
	s_waitcnt lgkmcnt(14)
	v_mfma_f32_16x16x32_f16 a[228:231], v[84:87], v[76:79], a[228:231]
	s_add_i32 s76, s74, 0xfffac000
	s_waitcnt lgkmcnt(14)
	v_mfma_f32_16x16x32_f16 a[224:227], v[80:83], v[76:79], a[224:227]
	s_mov_b32 s10, s6
	v_mfma_f32_16x16x32_f16 a[208:211], v[174:177], v[72:75], a[208:211]
	s_mov_b32 s11, s7
	v_mfma_f32_16x16x32_f16 a[200:203], v[88:91], v[72:75], a[200:203]
	buffer_load_dwordx4 v[96:99], v134, s[4:7], s76 offen
	v_mfma_f32_16x16x32_f16 a[196:199], v[84:87], v[72:75], a[196:199]
	buffer_load_dwordx4 v[100:103], v134, s[8:11], s76 offen
	v_mfma_f32_16x16x32_f16 a[192:195], v[80:83], v[72:75], a[192:195]
	s_add_i32 s76, s74, 0xfffb8000
	v_mfma_f32_16x16x32_f16 a[176:179], v[174:177], v[52:55], a[176:179]
	buffer_load_dwordx4 v[104:107], v134, s[4:7], s76 offen
	v_mfma_f32_16x16x32_f16 a[168:171], v[88:91], v[52:55], a[168:171]
	buffer_load_dwordx4 v[112:115], v134, s[8:11], s76 offen
	v_mfma_f32_16x16x32_f16 a[164:167], v[84:87], v[52:55], a[164:167]
	s_add_i32 s76, s74, 0xfffc4000
	v_mfma_f32_16x16x32_f16 a[160:163], v[80:83], v[52:55], a[160:163]
	buffer_load_dwordx4 v[108:111], v134, s[4:7], s76 offen
	v_mfma_f32_16x16x32_f16 a[144:147], v[174:177], v[44:47], a[144:147]
	buffer_load_dwordx4 v[116:119], v134, s[8:11], s76 offen
	v_mfma_f32_16x16x32_f16 a[136:139], v[88:91], v[44:47], a[136:139]
	s_add_i32 s76, s74, 0xfffd0000
	v_mfma_f32_16x16x32_f16 a[132:135], v[84:87], v[44:47], a[132:135]
	buffer_load_dwordx4 v[120:123], v134, s[4:7], s76 offen
	v_mfma_f32_16x16x32_f16 a[128:131], v[80:83], v[44:47], a[128:131]
	buffer_load_dwordx4 v[128:131], v134, s[8:11], s76 offen
	v_mfma_f32_16x16x32_f16 a[112:115], v[174:177], v[48:51], a[112:115]
	s_add_i32 s76, s74, 0xfffdc000
	v_mfma_f32_16x16x32_f16 a[104:107], v[88:91], v[48:51], a[104:107]
	buffer_load_dwordx4 v[124:127], v134, s[4:7], s76 offen
	v_mfma_f32_16x16x32_f16 a[100:103], v[84:87], v[48:51], a[100:103]
	buffer_load_dwordx4 v[146:149], v134, s[8:11], s76 offen
	v_mfma_f32_16x16x32_f16 a[96:99], v[80:83], v[48:51], a[96:99]
	s_add_i32 s76, s74, 0xfffe8000
	v_mfma_f32_16x16x32_f16 a[80:83], v[174:177], v[40:43], a[80:83]
	buffer_load_dwordx4 v[150:153], v134, s[4:7], s76 offen
	v_mfma_f32_16x16x32_f16 a[72:75], v[88:91], v[40:43], a[72:75]
	buffer_load_dwordx4 v[158:161], v134, s[8:11], s76 offen
	v_mfma_f32_16x16x32_f16 a[68:71], v[84:87], v[40:43], a[68:71]
	s_add_i32 s76, s74, 0xffff4000
	v_mfma_f32_16x16x32_f16 a[64:67], v[80:83], v[40:43], a[64:67]
	buffer_load_dwordx4 v[154:157], v134, s[4:7], s76 offen
	v_mfma_f32_16x16x32_f16 a[48:51], v[174:177], v[4:7], a[48:51]
	buffer_load_dwordx4 v[166:169], v134, s[8:11], s76 offen
	v_mfma_f32_16x16x32_f16 a[40:43], v[88:91], v[4:7], a[40:43]
	buffer_load_dwordx4 v[162:165], v134, s[4:7], s74 offen
	v_mfma_f32_16x16x32_f16 a[36:39], v[84:87], v[4:7], a[36:39]
	buffer_load_dwordx4 v[170:173], v134, s[8:11], s74 offen
	v_mfma_f32_16x16x32_f16 a[32:35], v[80:83], v[4:7], a[32:35]
	v_mfma_f32_16x16x32_f16 a[16:19], v[174:177], v[32:35], a[16:19]
	v_mfma_f32_16x16x32_f16 a[8:11], v[88:91], v[32:35], a[8:11]
	v_mfma_f32_16x16x32_f16 a[4:7], v[84:87], v[32:35], a[4:7]
	v_mfma_f32_16x16x32_f16 a[0:3], v[80:83], v[32:35], a[0:3]
	s_branch .LBB0_630
.Lgw2_nl:
	s_waitcnt lgkmcnt(14)
	v_mfma_f32_16x16x32_f16 a[240:243], v[174:177], v[76:79], a[240:243]
	s_waitcnt lgkmcnt(14)
	v_mfma_f32_16x16x32_f16 a[232:235], v[88:91], v[76:79], a[232:235]
	s_waitcnt lgkmcnt(14)
	v_mfma_f32_16x16x32_f16 a[228:231], v[84:87], v[76:79], a[228:231]
	s_waitcnt lgkmcnt(14)
	v_mfma_f32_16x16x32_f16 a[224:227], v[80:83], v[76:79], a[224:227]
	v_mfma_f32_16x16x32_f16 a[208:211], v[174:177], v[72:75], a[208:211]
	v_mfma_f32_16x16x32_f16 a[200:203], v[88:91], v[72:75], a[200:203]
	v_mfma_f32_16x16x32_f16 a[196:199], v[84:87], v[72:75], a[196:199]
	v_mfma_f32_16x16x32_f16 a[192:195], v[80:83], v[72:75], a[192:195]
	v_mfma_f32_16x16x32_f16 a[176:179], v[174:177], v[52:55], a[176:179]
	v_mfma_f32_16x16x32_f16 a[168:171], v[88:91], v[52:55], a[168:171]
	v_mfma_f32_16x16x32_f16 a[164:167], v[84:87], v[52:55], a[164:167]
	v_mfma_f32_16x16x32_f16 a[160:163], v[80:83], v[52:55], a[160:163]
	v_mfma_f32_16x16x32_f16 a[144:147], v[174:177], v[44:47], a[144:147]
	v_mfma_f32_16x16x32_f16 a[136:139], v[88:91], v[44:47], a[136:139]
	v_mfma_f32_16x16x32_f16 a[132:135], v[84:87], v[44:47], a[132:135]
	v_mfma_f32_16x16x32_f16 a[128:131], v[80:83], v[44:47], a[128:131]
	v_mfma_f32_16x16x32_f16 a[112:115], v[174:177], v[48:51], a[112:115]
	v_mfma_f32_16x16x32_f16 a[104:107], v[88:91], v[48:51], a[104:107]
	v_mfma_f32_16x16x32_f16 a[100:103], v[84:87], v[48:51], a[100:103]
	v_mfma_f32_16x16x32_f16 a[96:99], v[80:83], v[48:51], a[96:99]
	v_mfma_f32_16x16x32_f16 a[80:83], v[174:177], v[40:43], a[80:83]
	v_mfma_f32_16x16x32_f16 a[72:75], v[88:91], v[40:43], a[72:75]
	v_mfma_f32_16x16x32_f16 a[68:71], v[84:87], v[40:43], a[68:71]
	v_mfma_f32_16x16x32_f16 a[64:67], v[80:83], v[40:43], a[64:67]
	v_mfma_f32_16x16x32_f16 a[48:51], v[174:177], v[4:7], a[48:51]
	v_mfma_f32_16x16x32_f16 a[40:43], v[88:91], v[4:7], a[40:43]
	v_mfma_f32_16x16x32_f16 a[36:39], v[84:87], v[4:7], a[36:39]
	v_mfma_f32_16x16x32_f16 a[32:35], v[80:83], v[4:7], a[32:35]
	v_mfma_f32_16x16x32_f16 a[16:19], v[174:177], v[32:35], a[16:19]
	v_mfma_f32_16x16x32_f16 a[8:11], v[88:91], v[32:35], a[8:11]
	v_mfma_f32_16x16x32_f16 a[4:7], v[84:87], v[32:35], a[4:7]
	v_mfma_f32_16x16x32_f16 a[0:3], v[80:83], v[32:35], a[0:3]
	s_branch .LBB0_630

; #define LD_AF(dst, ks_) _Pragma("unroll") for (int i = 0; i < 8; ++i) dst[i] = *(const h8*)(sA + i * 16 * G_LD + (ks_) * 32)
; #define LD_BF(dst, ks_, nh_) _Pragma("unroll") for (int i = 0; i < 4; ++i) dst[i] = *(const h8*)(sB + ((nh_) * 4 + i) * 16 * G_LD + (ks_) * 32)
; #define MMA_BLK(afx, bfx, nh_) _Pragma("unroll") for (int mi = 0; mi < 8; ++mi) _Pragma("unroll") for (int ni = 0; ni < 4; ++ni) mfma16_acc(acc[mi][(nh_) * 4 + ni], bfx[ni], afx[mi])
; template <class Epi>
; __device__ __forceinline__ void gemm_run(const GemmArgs g, Epi epi, char* smem) {
;     ...
;       const hf* sA = sbase + (kt & 1) * G_STAGE + (wm * 128 + fr) * G_LD + fqs;
;       const hf* sB = sbase + (kt & 1) * G_STAGE + (256 + wn * 128 + fr) * G_LD + fqs;
;       hf* st = sbase + ((kt + 1) & 1) * G_STAGE;
;       h8 afA[8], afB[8], bfA[4], bfB[4];
;     ...
;       LD_AF(afA, 0); LD_BF(bfA, 0, 0);
;       if (kt + 1 < nk) {
; #pragma unroll
;         for (int i = 0; i < 8; ++i) *(u4*)(st + (lr + 32 * i) * G_LD + lcw) = ra[i];
;       }
;       __builtin_amdgcn_sched_barrier(0);
;       LD_BF(bfB, 0, 1);
;       MMA_BLK(afA, bfA, 0);
;       __builtin_amdgcn_sched_barrier(0);
;       if (kt + 1 < nk) {
; #pragma unroll
;         for (int i = 0; i < 8; ++i) *(u4*)(st + (256 + lr + 32 * i) * G_LD + lcw) = rb[i];
;       }
;       LD_AF(afB, 1); LD_BF(bfA, 1, 0);
;       MMA_BLK(afA, bfB, 1);
.LBB0_648:
	s_bitcmp1_b32 s21, 0
	s_cselect_b32 s15, 0x12000, 0
	s_add_i32 s15, s15, 16
	v_add3_u32 v56, s15, v95, v103
	v_add3_u32 v104, s15, v96, v103
	ds_read_b128 v[4:7], v56 offset:13824
	ds_read_b128 v[16:19], v104 offset:36864
	ds_read_b128 v[12:15], v104 offset:39168
	ds_read_b128 v[8:11], v104 offset:41472
	ds_read_b128 v[0:3], v104 offset:43776
	ds_read_b128 v[76:79], v56
	ds_read_b128 v[72:75], v56 offset:2304
	ds_read_b128 v[52:55], v56 offset:4608
	ds_read_b128 v[44:47], v56 offset:6912
	ds_read_b128 v[48:51], v56 offset:9216
	ds_read_b128 v[40:43], v56 offset:11520
	ds_read_b128 v[32:35], v56 offset:16128
	s_mov_b32 s14, s21
	s_add_i32 s21, s21, 1
	s_bitcmp1_b32 s21, 0
	s_cselect_b32 s15, 0x12000, 0
	v_add_u32_e32 v20, s15, v93
	v_add_u32_e32 v21, v20, v98
	ds_read_b128 v[174:177], v104 offset:46080
	ds_read_b128 v[88:91], v104 offset:48384
	ds_read_b128 v[84:87], v104 offset:50688
	ds_read_b128 v[80:83], v104 offset:52992
	s_waitcnt lgkmcnt(10)
	v_mfma_f32_16x16x32_f16 a[252:255], v[16:19], v[76:79], a[252:255]
	v_mfma_f32_16x16x32_f16 a[248:251], v[12:15], v[76:79], a[248:251]
	s_waitcnt vmcnt(15)
	ds_write_b128 v21, v[106:109]
	v_mfma_f32_16x16x32_f16 a[244:247], v[8:11], v[76:79], a[244:247]
	v_mfma_f32_16x16x32_f16 a[240:243], v[0:3], v[76:79], a[240:243]
	s_waitcnt vmcnt(13)
	ds_write_b128 v21, v[114:117] offset:4608
	s_waitcnt lgkmcnt(11)
	v_mfma_f32_16x16x32_f16 a[220:223], v[16:19], v[72:75], a[220:223]
	v_mfma_f32_16x16x32_f16 a[216:219], v[12:15], v[72:75], a[216:219]
	s_waitcnt vmcnt(11)
	ds_write_b128 v21, v[118:121] offset:9216
	v_mfma_f32_16x16x32_f16 a[212:215], v[8:11], v[72:75], a[212:215]
	v_mfma_f32_16x16x32_f16 a[208:211], v[0:3], v[72:75], a[208:211]
	s_waitcnt vmcnt(9)
	ds_write_b128 v21, v[134:137] offset:13824
	s_waitcnt lgkmcnt(12)
	v_mfma_f32_16x16x32_f16 a[188:191], v[16:19], v[52:55], a[188:191]
	v_mfma_f32_16x16x32_f16 a[184:187], v[12:15], v[52:55], a[184:187]
	s_waitcnt vmcnt(7)
	ds_write_b128 v21, v[138:141] offset:18432
	v_mfma_f32_16x16x32_f16 a[180:183], v[8:11], v[52:55], a[180:183]
	v_mfma_f32_16x16x32_f16 a[176:179], v[0:3], v[52:55], a[176:179]
	s_waitcnt vmcnt(5)
	ds_write_b128 v21, v[150:153] offset:23040
	s_waitcnt lgkmcnt(13)
	v_mfma_f32_16x16x32_f16 a[156:159], v[16:19], v[44:47], a[156:159]
	v_mfma_f32_16x16x32_f16 a[152:155], v[12:15], v[44:47], a[152:155]
	s_waitcnt vmcnt(3)
	ds_write_b128 v21, v[154:157] offset:27648
	v_mfma_f32_16x16x32_f16 a[148:151], v[8:11], v[44:47], a[148:151]
	v_mfma_f32_16x16x32_f16 a[144:147], v[0:3], v[44:47], a[144:147]
	s_waitcnt vmcnt(1)
	ds_write_b128 v21, v[162:165] offset:32256
	s_waitcnt lgkmcnt(14)
	v_mfma_f32_16x16x32_f16 a[124:127], v[16:19], v[48:51], a[124:127]
	v_mfma_f32_16x16x32_f16 a[120:123], v[12:15], v[48:51], a[120:123]
	s_waitcnt vmcnt(7)
	ds_write_b128 v21, v[110:113] offset:36864
	v_mfma_f32_16x16x32_f16 a[116:119], v[8:11], v[48:51], a[116:119]
	v_mfma_f32_16x16x32_f16 a[112:115], v[0:3], v[48:51], a[112:115]
	s_waitcnt vmcnt(6)
	ds_write_b128 v21, v[122:125] offset:41472
	s_waitcnt lgkmcnt(14)
	v_mfma_f32_16x16x32_f16 a[92:95], v[16:19], v[40:43], a[92:95]
	v_mfma_f32_16x16x32_f16 a[88:91], v[12:15], v[40:43], a[88:91]
	s_waitcnt vmcnt(5)
	ds_write_b128 v21, v[126:129] offset:46080
	v_mfma_f32_16x16x32_f16 a[84:87], v[8:11], v[40:43], a[84:87]
	v_mfma_f32_16x16x32_f16 a[80:83], v[0:3], v[40:43], a[80:83]
	s_waitcnt vmcnt(4)
	ds_write_b128 v21, v[142:145] offset:50688
	v_mfma_f32_16x16x32_f16 a[60:63], v[16:19], v[4:7], a[60:63]
	v_mfma_f32_16x16x32_f16 a[56:59], v[12:15], v[4:7], a[56:59]
	s_waitcnt vmcnt(3)
	ds_write_b128 v21, v[146:149] offset:55296
	v_mfma_f32_16x16x32_f16 a[52:55], v[8:11], v[4:7], a[52:55]
	v_mfma_f32_16x16x32_f16 a[48:51], v[0:3], v[4:7], a[48:51]
	s_waitcnt vmcnt(2)
	ds_write_b128 v21, v[158:161] offset:59904
	s_waitcnt lgkmcnt(14)
	v_mfma_f32_16x16x32_f16 a[28:31], v[16:19], v[32:35], a[28:31]
	v_mfma_f32_16x16x32_f16 a[24:27], v[12:15], v[32:35], a[24:27]
	s_waitcnt vmcnt(1)
	ds_write_b128 v21, v[166:169] offset:64512
	v_mfma_f32_16x16x32_f16 a[20:23], v[8:11], v[32:35], a[20:23]
	v_mfma_f32_16x16x32_f16 a[16:19], v[0:3], v[32:35], a[16:19]
	v_add_u32_e32 v0, v20, v99
	s_waitcnt vmcnt(0)
	ds_write_b128 v0, v[170:173]
	ds_read_b128 v[36:39], v56 offset:64
	ds_read_b128 v[28:31], v56 offset:2368
	ds_read_b128 v[24:27], v56 offset:4672
	ds_read_b128 v[20:23], v56 offset:6976
	ds_read_b128 v[16:19], v56 offset:9280
	ds_read_b128 v[12:15], v56 offset:11584
	ds_read_b128 v[8:11], v56 offset:13888
	ds_read_b128 v[0:3], v56 offset:16192
	ds_read_b128 v[56:59], v104 offset:36928
	ds_read_b128 v[60:63], v104 offset:39232
	ds_read_b128 v[64:67], v104 offset:41536
	ds_read_b128 v[68:71], v104 offset:43840
	s_cmp_gt_u32 s14, 13
	s_cbranch_scc1 .Lgw3_nl
; #define MMA_BLK(afx, bfx, nh_) _Pragma("unroll") for (int mi = 0; mi < 8; ++mi) _Pragma("unroll") for (int ni = 0; ni < 4; ++ni) mfma16_acc(acc[mi][(nh_) * 4 + ni], bfx[ni], afx[mi])
; template <class Epi>
; __device__ __forceinline__ void gemm_run(const GemmArgs g, Epi epi, char* smem) {
;     ...
;       MMA_BLK(afA, bfB, 1);
;       __builtin_amdgcn_sched_barrier(0);
;       if (kt + 2 < nk) {
;         const int ko = (kt + 2) * 64;
; #pragma unroll
;         for (int i = 0; i < 8; ++i) { ra[i] = __builtin_amdgcn_raw_buffer_load_b128(Ars, aoff, i * astep + ko * 2, 0); rb[i] = __builtin_amdgcn_raw_buffer_load_b128(Brs, boff, i * bstep + ko * 2, 0); }
;       }
	s_waitcnt lgkmcnt(14)
	v_mfma_f32_16x16x32_f16 a[236:239], v[174:177], v[76:79], a[236:239]
	s_waitcnt lgkmcnt(14)
	v_mfma_f32_16x16x32_f16 a[232:235], v[88:91], v[76:79], a[232:235]
	s_waitcnt lgkmcnt(14)
	v_mfma_f32_16x16x32_f16 a[228:231], v[84:87], v[76:79], a[228:231]
	s_add_i32 s23, s3, 0xfff90000
	s_waitcnt lgkmcnt(14)
	v_mfma_f32_16x16x32_f16 a[224:227], v[80:83], v[76:79], a[224:227]
	s_mov_b32 s14, s10
	v_mfma_f32_16x16x32_f16 a[204:207], v[174:177], v[72:75], a[204:207]
	s_mov_b32 s15, s11
	v_mfma_f32_16x16x32_f16 a[200:203], v[88:91], v[72:75], a[200:203]
	buffer_load_dwordx4 v[106:109], v92, s[8:11], s23 offen
	v_mfma_f32_16x16x32_f16 a[196:199], v[84:87], v[72:75], a[196:199]
	buffer_load_dwordx4 v[110:113], v92, s[12:15], s23 offen
	v_mfma_f32_16x16x32_f16 a[192:195], v[80:83], v[72:75], a[192:195]
	s_add_i32 s23, s3, 0xfffa0000
	v_mfma_f32_16x16x32_f16 a[172:175], v[174:177], v[52:55], a[172:175]
	buffer_load_dwordx4 v[114:117], v92, s[8:11], s23 offen
	v_mfma_f32_16x16x32_f16 a[168:171], v[88:91], v[52:55], a[168:171]
	buffer_load_dwordx4 v[122:125], v92, s[12:15], s23 offen
	v_mfma_f32_16x16x32_f16 a[164:167], v[84:87], v[52:55], a[164:167]
	s_add_i32 s23, s3, 0xfffb0000
	v_mfma_f32_16x16x32_f16 a[160:163], v[80:83], v[52:55], a[160:163]
	buffer_load_dwordx4 v[118:121], v92, s[8:11], s23 offen
	v_mfma_f32_16x16x32_f16 a[140:143], v[174:177], v[44:47], a[140:143]
	buffer_load_dwordx4 v[126:129], v92, s[12:15], s23 offen
	v_mfma_f32_16x16x32_f16 a[136:139], v[88:91], v[44:47], a[136:139]
	s_add_i32 s23, s3, 0xfffc0000
	v_mfma_f32_16x16x32_f16 a[132:135], v[84:87], v[44:47], a[132:135]
	buffer_load_dwordx4 v[134:137], v92, s[8:11], s23 offen
	v_mfma_f32_16x16x32_f16 a[128:131], v[80:83], v[44:47], a[128:131]
	buffer_load_dwordx4 v[142:145], v92, s[12:15], s23 offen
	v_mfma_f32_16x16x32_f16 a[108:111], v[174:177], v[48:51], a[108:111]
	s_add_i32 s23, s3, 0xfffd0000
	v_mfma_f32_16x16x32_f16 a[104:107], v[88:91], v[48:51], a[104:107]
	buffer_load_dwordx4 v[138:141], v92, s[8:11], s23 offen
	v_mfma_f32_16x16x32_f16 a[100:103], v[84:87], v[48:51], a[100:103]
	buffer_load_dwordx4 v[146:149], v92, s[12:15], s23 offen
	v_mfma_f32_16x16x32_f16 a[96:99], v[80:83], v[48:51], a[96:99]
	s_add_i32 s23, s3, 0xfffe0000
	v_mfma_f32_16x16x32_f16 a[76:79], v[174:177], v[40:43], a[76:79]
	buffer_load_dwordx4 v[150:153], v92, s[8:11], s23 offen
	v_mfma_f32_16x16x32_f16 a[72:75], v[88:91], v[40:43], a[72:75]
	buffer_load_dwordx4 v[158:161], v92, s[12:15], s23 offen
	v_mfma_f32_16x16x32_f16 a[68:71], v[84:87], v[40:43], a[68:71]
	s_add_i32 s23, s3, 0xffff0000
	v_mfma_f32_16x16x32_f16 a[64:67], v[80:83], v[40:43], a[64:67]
	buffer_load_dwordx4 v[154:157], v92, s[8:11], s23 offen
	v_mfma_f32_16x16x32_f16 a[44:47], v[174:177], v[4:7], a[44:47]
	buffer_load_dwordx4 v[166:169], v92, s[12:15], s23 offen
	v_mfma_f32_16x16x32_f16 a[40:43], v[88:91], v[4:7], a[40:43]
	buffer_load_dwordx4 v[162:165], v92, s[8:11], s3 offen
	v_mfma_f32_16x16x32_f16 a[36:39], v[84:87], v[4:7], a[36:39]
	buffer_load_dwordx4 v[170:173], v92, s[12:15], s3 offen
	v_mfma_f32_16x16x32_f16 a[32:35], v[80:83], v[4:7], a[32:35]
	v_mfma_f32_16x16x32_f16 a[12:15], v[174:177], v[32:35], a[12:15]
	v_mfma_f32_16x16x32_f16 a[8:11], v[88:91], v[32:35], a[8:11]
	v_mfma_f32_16x16x32_f16 a[4:7], v[84:87], v[32:35], a[4:7]
	v_mfma_f32_16x16x32_f16 a[0:3], v[80:83], v[32:35], a[0:3]
	s_branch .LBB0_647
.Lgw3_nl:
	s_waitcnt lgkmcnt(14)
	v_mfma_f32_16x16x32_f16 a[236:239], v[174:177], v[76:79], a[236:239]
	s_waitcnt lgkmcnt(14)
	v_mfma_f32_16x16x32_f16 a[232:235], v[88:91], v[76:79], a[232:235]
	s_waitcnt lgkmcnt(14)
	v_mfma_f32_16x16x32_f16 a[228:231], v[84:87], v[76:79], a[228:231]
	s_waitcnt lgkmcnt(14)
	v_mfma_f32_16x16x32_f16 a[224:227], v[80:83], v[76:79], a[224:227]
	v_mfma_f32_16x16x32_f16 a[204:207], v[174:177], v[72:75], a[204:207]
	v_mfma_f32_16x16x32_f16 a[200:203], v[88:91], v[72:75], a[200:203]
	v_mfma_f32_16x16x32_f16 a[196:199], v[84:87], v[72:75], a[196:199]
	v_mfma_f32_16x16x32_f16 a[192:195], v[80:83], v[72:75], a[192:195]
	v_mfma_f32_16x16x32_f16 a[172:175], v[174:177], v[52:55], a[172:175]
	v_mfma_f32_16x16x32_f16 a[168:171], v[88:91], v[52:55], a[168:171]
	v_mfma_f32_16x16x32_f16 a[164:167], v[84:87], v[52:55], a[164:167]
	v_mfma_f32_16x16x32_f16 a[160:163], v[80:83], v[52:55], a[160:163]
	v_mfma_f32_16x16x32_f16 a[140:143], v[174:177], v[44:47], a[140:143]
	v_mfma_f32_16x16x32_f16 a[136:139], v[88:91], v[44:47], a[136:139]
	v_mfma_f32_16x16x32_f16 a[132:135], v[84:87], v[44:47], a[132:135]
	v_mfma_f32_16x16x32_f16 a[128:131], v[80:83], v[44:47], a[128:131]
	v_mfma_f32_16x16x32_f16 a[108:111], v[174:177], v[48:51], a[108:111]
	v_mfma_f32_16x16x32_f16 a[104:107], v[88:91], v[48:51], a[104:107]
	v_mfma_f32_16x16x32_f16 a[100:103], v[84:87], v[48:51], a[100:103]
	v_mfma_f32_16x16x32_f16 a[96:99], v[80:83], v[48:51], a[96:99]
	v_mfma_f32_16x16x32_f16 a[76:79], v[174:177], v[40:43], a[76:79]
	v_mfma_f32_16x16x32_f16 a[72:75], v[88:91], v[40:43], a[72:75]
	v_mfma_f32_16x16x32_f16 a[68:71], v[84:87], v[40:43], a[68:71]
	v_mfma_f32_16x16x32_f16 a[64:67], v[80:83], v[40:43], a[64:67]
	v_mfma_f32_16x16x32_f16 a[44:47], v[174:177], v[4:7], a[44:47]
	v_mfma_f32_16x16x32_f16 a[40:43], v[88:91], v[4:7], a[40:43]
	v_mfma_f32_16x16x32_f16 a[36:39], v[84:87], v[4:7], a[36:39]
	v_mfma_f32_16x16x32_f16 a[32:35], v[80:83], v[4:7], a[32:35]
	v_mfma_f32_16x16x32_f16 a[12:15], v[174:177], v[32:35], a[12:15]
	v_mfma_f32_16x16x32_f16 a[8:11], v[88:91], v[32:35], a[8:11]
	v_mfma_f32_16x16x32_f16 a[4:7], v[84:87], v[32:35], a[4:7]
	v_mfma_f32_16x16x32_f16 a[0:3], v[80:83], v[32:35], a[0:3]
	s_branch .LBB0_647

; #define LD_AF(dst, ks_) _Pragma("unroll") for (int i = 0; i < 8; ++i) dst[i] = *(const h8*)(sA + i * 16 * G_LD + (ks_) * 32)
; #define LD_BF(dst, ks_, nh_) _Pragma("unroll") for (int i = 0; i < 4; ++i) dst[i] = *(const h8*)(sB + ((nh_) * 4 + i) * 16 * G_LD + (ks_) * 32)
; #define MMA_BLK(afx, bfx, nh_) _Pragma("unroll") for (int mi = 0; mi < 8; ++mi) _Pragma("unroll") for (int ni = 0; ni < 4; ++ni) mfma16_acc(acc[mi][(nh_) * 4 + ni], bfx[ni], afx[mi])
; template <class Epi>
; __device__ __forceinline__ void gemm_run(const GemmArgs g, Epi epi, char* smem) {
;     ...
;       const hf* sA = sbase + (kt & 1) * G_STAGE + (wm * 128 + fr) * G_LD + fqs;
;       const hf* sB = sbase + (kt & 1) * G_STAGE + (256 + wn * 128 + fr) * G_LD + fqs;
;       hf* st = sbase + ((kt + 1) & 1) * G_STAGE;
;       h8 afA[8], afB[8], bfA[4], bfB[4];
;     ...
;       LD_AF(afA, 0); LD_BF(bfA, 0, 0);
;       if (kt + 1 < nk) {
; #pragma unroll
;         for (int i = 0; i < 8; ++i) *(u4*)(st + (lr + 32 * i) * G_LD + lcw) = ra[i];
;       }
;       __builtin_amdgcn_sched_barrier(0);
;       LD_BF(bfB, 0, 1);
;       MMA_BLK(afA, bfA, 0);
;       __builtin_amdgcn_sched_barrier(0);
;       if (kt + 1 < nk) {
; #pragma unroll
;         for (int i = 0; i < 8; ++i) *(u4*)(st + (256 + lr + 32 * i) * G_LD + lcw) = rb[i];
;       }
;       LD_AF(afB, 1); LD_BF(bfA, 1, 0);
;       MMA_BLK(afA, bfB, 1);
.LBB0_921:
	s_bitcmp1_b32 s21, 0
	s_cselect_b32 s11, 0x12000, 0
	s_add_i32 s11, s11, 16
	v_add3_u32 v56, s11, v131, v141
	v_add3_u32 v92, s11, v134, v141
	ds_read_b128 v[0:3], v56 offset:13824
	ds_read_b128 v[16:19], v92 offset:36864
	ds_read_b128 v[12:15], v92 offset:39168
	ds_read_b128 v[8:11], v92 offset:41472
	ds_read_b128 v[4:7], v92 offset:43776
	ds_read_b128 v[76:79], v56
	ds_read_b128 v[72:75], v56 offset:2304
	ds_read_b128 v[52:55], v56 offset:4608
	ds_read_b128 v[40:43], v56 offset:6912
	ds_read_b128 v[48:51], v56 offset:9216
	ds_read_b128 v[36:39], v56 offset:11520
	ds_read_b128 v[20:23], v56 offset:16128
	s_mov_b32 s10, s21
	s_add_i32 s21, s21, 1
	s_bitcmp1_b32 s21, 0
	s_cselect_b32 s11, 0x12000, 0
	v_add_u32_e32 v24, s11, v129
	v_add_u32_e32 v25, v24, v136
	ds_read_b128 v[174:177], v92 offset:46080
	ds_read_b128 v[88:91], v92 offset:48384
	ds_read_b128 v[84:87], v92 offset:50688
	ds_read_b128 v[80:83], v92 offset:52992
	s_waitcnt lgkmcnt(10)
	v_mfma_f32_16x16x32_f16 a[208:211], v[16:19], v[76:79], a[208:211]
	v_mfma_f32_16x16x32_f16 a[200:203], v[12:15], v[76:79], a[200:203]
	s_waitcnt vmcnt(15)
	ds_write_b128 v25, v[94:97]
	v_mfma_f32_16x16x32_f16 a[196:199], v[8:11], v[76:79], a[196:199]
	v_mfma_f32_16x16x32_f16 a[192:195], v[4:7], v[76:79], a[192:195]
	s_waitcnt vmcnt(13)
	ds_write_b128 v25, v[102:105] offset:4608
	s_waitcnt lgkmcnt(11)
	v_mfma_f32_16x16x32_f16 a[188:191], v[16:19], v[72:75], a[188:191]
	v_mfma_f32_16x16x32_f16 a[184:187], v[12:15], v[72:75], a[184:187]
	s_waitcnt vmcnt(11)
	ds_write_b128 v25, v[106:109] offset:9216
	v_mfma_f32_16x16x32_f16 a[180:183], v[8:11], v[72:75], a[180:183]
	v_mfma_f32_16x16x32_f16 a[176:179], v[4:7], v[72:75], a[176:179]
	s_waitcnt vmcnt(9)
	ds_write_b128 v25, v[118:121] offset:13824
	s_waitcnt lgkmcnt(12)
	v_mfma_f32_16x16x32_f16 a[156:159], v[16:19], v[52:55], a[156:159]
	v_mfma_f32_16x16x32_f16 a[152:155], v[12:15], v[52:55], a[152:155]
	s_waitcnt vmcnt(7)
	ds_write_b128 v25, v[122:125] offset:18432
	v_mfma_f32_16x16x32_f16 a[148:151], v[8:11], v[52:55], a[148:151]
	v_mfma_f32_16x16x32_f16 a[144:147], v[4:7], v[52:55], a[144:147]
	s_waitcnt vmcnt(5)
	ds_write_b128 v25, v[150:153] offset:23040
	s_waitcnt lgkmcnt(13)
	v_mfma_f32_16x16x32_f16 a[124:127], v[16:19], v[40:43], a[124:127]
	v_mfma_f32_16x16x32_f16 a[120:123], v[12:15], v[40:43], a[120:123]
	s_waitcnt vmcnt(3)
	ds_write_b128 v25, v[154:157] offset:27648
	v_mfma_f32_16x16x32_f16 a[116:119], v[8:11], v[40:43], a[116:119]
	v_mfma_f32_16x16x32_f16 a[112:115], v[4:7], v[40:43], a[112:115]
	s_waitcnt vmcnt(1)
	ds_write_b128 v25, v[162:165] offset:32256
	s_waitcnt lgkmcnt(14)
	v_mfma_f32_16x16x32_f16 a[92:95], v[16:19], v[48:51], a[92:95]
	v_mfma_f32_16x16x32_f16 a[88:91], v[12:15], v[48:51], a[88:91]
	s_waitcnt vmcnt(7)
	ds_write_b128 v25, v[98:101] offset:36864
	v_mfma_f32_16x16x32_f16 a[84:87], v[8:11], v[48:51], a[84:87]
	v_mfma_f32_16x16x32_f16 a[80:83], v[4:7], v[48:51], a[80:83]
	s_waitcnt vmcnt(6)
	ds_write_b128 v25, v[110:113] offset:41472
	s_waitcnt lgkmcnt(14)
	v_mfma_f32_16x16x32_f16 a[60:63], v[16:19], v[36:39], a[60:63]
	v_mfma_f32_16x16x32_f16 a[56:59], v[12:15], v[36:39], a[56:59]
	s_waitcnt vmcnt(5)
	ds_write_b128 v25, v[114:117] offset:46080
	v_mfma_f32_16x16x32_f16 a[52:55], v[8:11], v[36:39], a[52:55]
	v_mfma_f32_16x16x32_f16 a[48:51], v[4:7], v[36:39], a[48:51]
	s_waitcnt vmcnt(4)
	ds_write_b128 v25, v[142:145] offset:50688
	v_mfma_f32_16x16x32_f16 a[32:35], v[16:19], v[0:3], a[32:35]
	v_mfma_f32_16x16x32_f16 a[28:31], v[12:15], v[0:3], a[28:31]
	s_waitcnt vmcnt(3)
	ds_write_b128 v25, v[146:149] offset:55296
	v_mfma_f32_16x16x32_f16 a[24:27], v[8:11], v[0:3], a[24:27]
	v_mfma_f32_16x16x32_f16 a[20:23], v[4:7], v[0:3], a[20:23]
	s_waitcnt vmcnt(2)
	ds_write_b128 v25, v[158:161] offset:59904
	s_waitcnt lgkmcnt(14)
	v_mfma_f32_16x16x32_f16 a[12:15], v[16:19], v[20:23], a[12:15]
	v_mfma_f32_16x16x32_f16 a[8:11], v[12:15], v[20:23], a[8:11]
	s_waitcnt vmcnt(1)
	ds_write_b128 v25, v[166:169] offset:64512
	v_mfma_f32_16x16x32_f16 a[4:7], v[8:11], v[20:23], a[4:7]
	v_mfma_f32_16x16x32_f16 a[0:3], v[4:7], v[20:23], a[0:3]
	v_add_u32_e32 v4, v24, v137
	s_waitcnt vmcnt(0)
	ds_write_b128 v4, v[170:173]
	ds_read_b128 v[44:47], v56 offset:64
	ds_read_b128 v[32:35], v56 offset:2368
	ds_read_b128 v[28:31], v56 offset:4672
	ds_read_b128 v[24:27], v56 offset:6976
	ds_read_b128 v[16:19], v56 offset:9280
	ds_read_b128 v[12:15], v56 offset:11584
	ds_read_b128 v[8:11], v56 offset:13888
	ds_read_b128 v[4:7], v56 offset:16192
	ds_read_b128 v[56:59], v92 offset:36928
	ds_read_b128 v[60:63], v92 offset:39232
	ds_read_b128 v[64:67], v92 offset:41536
	ds_read_b128 v[68:71], v92 offset:43840
	s_cmp_gt_u32 s10, 29
	s_cbranch_scc1 .Lgw4_nl
; #define MMA_BLK(afx, bfx, nh_) _Pragma("unroll") for (int mi = 0; mi < 8; ++mi) _Pragma("unroll") for (int ni = 0; ni < 4; ++ni) mfma16_acc(acc[mi][(nh_) * 4 + ni], bfx[ni], afx[mi])
; template <class Epi>
; __device__ __forceinline__ void gemm_run(const GemmArgs g, Epi epi, char* smem) {
;     ...
;       MMA_BLK(afA, bfB, 1);
;       __builtin_amdgcn_sched_barrier(0);
;       if (kt + 2 < nk) {
;         const int ko = (kt + 2) * 64;
; #pragma unroll
;         for (int i = 0; i < 8; ++i) { ra[i] = __builtin_amdgcn_raw_buffer_load_b128(Ars, aoff, i * astep + ko * 2, 0); rb[i] = __builtin_amdgcn_raw_buffer_load_b128(Brs, boff, i * bstep + ko * 2, 0); }
;       }
	s_waitcnt lgkmcnt(14)
	v_mfma_f32_16x16x32_f16 a[240:243], v[174:177], v[76:79], a[240:243]
	s_waitcnt lgkmcnt(14)
	v_mfma_f32_16x16x32_f16 a[252:255], v[88:91], v[76:79], a[252:255]
	s_waitcnt lgkmcnt(14)
	v_mfma_f32_16x16x32_f16 a[248:251], v[84:87], v[76:79], a[248:251]
	s_add_i32 s78, s19, 0xfff20000
	s_waitcnt lgkmcnt(14)
	v_mfma_f32_16x16x32_f16 a[244:247], v[80:83], v[76:79], a[244:247]
	s_mov_b32 s10, s6
	v_mfma_f32_16x16x32_f16 a[236:239], v[174:177], v[72:75], a[236:239]
	s_mov_b32 s11, s7
	v_mfma_f32_16x16x32_f16 a[232:235], v[88:91], v[72:75], a[232:235]
	buffer_load_dwordx4 v[94:97], v128, s[4:7], s78 offen
	v_mfma_f32_16x16x32_f16 a[228:231], v[84:87], v[72:75], a[228:231]
	buffer_load_dwordx4 v[98:101], v128, s[8:11], s78 offen
	v_mfma_f32_16x16x32_f16 a[224:227], v[80:83], v[72:75], a[224:227]
	s_add_i32 s78, s19, 0xfff40000
	v_mfma_f32_16x16x32_f16 a[220:223], v[174:177], v[52:55], a[220:223]
	buffer_load_dwordx4 v[102:105], v128, s[4:7], s78 offen
	v_mfma_f32_16x16x32_f16 a[216:219], v[88:91], v[52:55], a[216:219]
	buffer_load_dwordx4 v[110:113], v128, s[8:11], s78 offen
	v_mfma_f32_16x16x32_f16 a[212:215], v[84:87], v[52:55], a[212:215]
	s_add_i32 s78, s19, 0xfff60000
	v_mfma_f32_16x16x32_f16 a[204:207], v[80:83], v[52:55], a[204:207]
	buffer_load_dwordx4 v[106:109], v128, s[4:7], s78 offen
	v_mfma_f32_16x16x32_f16 a[172:175], v[174:177], v[40:43], a[172:175]
	buffer_load_dwordx4 v[114:117], v128, s[8:11], s78 offen
	v_mfma_f32_16x16x32_f16 a[168:171], v[88:91], v[40:43], a[168:171]
	s_add_i32 s78, s19, 0xfff80000
	v_mfma_f32_16x16x32_f16 a[164:167], v[84:87], v[40:43], a[164:167]
	buffer_load_dwordx4 v[118:121], v128, s[4:7], s78 offen
	v_mfma_f32_16x16x32_f16 a[160:163], v[80:83], v[40:43], a[160:163]
	buffer_load_dwordx4 v[142:145], v128, s[8:11], s78 offen
	v_mfma_f32_16x16x32_f16 a[140:143], v[174:177], v[48:51], a[140:143]
	s_add_i32 s78, s19, 0xfffa0000
	v_mfma_f32_16x16x32_f16 a[136:139], v[88:91], v[48:51], a[136:139]
	buffer_load_dwordx4 v[122:125], v128, s[4:7], s78 offen
	v_mfma_f32_16x16x32_f16 a[132:135], v[84:87], v[48:51], a[132:135]
	buffer_load_dwordx4 v[146:149], v128, s[8:11], s78 offen
	v_mfma_f32_16x16x32_f16 a[128:131], v[80:83], v[48:51], a[128:131]
	s_add_i32 s78, s19, 0xfffc0000
	v_mfma_f32_16x16x32_f16 a[108:111], v[174:177], v[36:39], a[108:111]
	buffer_load_dwordx4 v[150:153], v128, s[4:7], s78 offen
	v_mfma_f32_16x16x32_f16 a[104:107], v[88:91], v[36:39], a[104:107]
	buffer_load_dwordx4 v[158:161], v128, s[8:11], s78 offen
	v_mfma_f32_16x16x32_f16 a[100:103], v[84:87], v[36:39], a[100:103]
	s_add_i32 s78, s19, 0xfffe0000
	v_mfma_f32_16x16x32_f16 a[96:99], v[80:83], v[36:39], a[96:99]
	buffer_load_dwordx4 v[154:157], v128, s[4:7], s78 offen
	v_mfma_f32_16x16x32_f16 a[76:79], v[174:177], v[0:3], a[76:79]
	buffer_load_dwordx4 v[166:169], v128, s[8:11], s78 offen
	v_mfma_f32_16x16x32_f16 a[72:75], v[88:91], v[0:3], a[72:75]
	buffer_load_dwordx4 v[162:165], v128, s[4:7], s19 offen
	v_mfma_f32_16x16x32_f16 a[68:71], v[84:87], v[0:3], a[68:71]
	buffer_load_dwordx4 v[170:173], v128, s[8:11], s19 offen
	v_mfma_f32_16x16x32_f16 a[64:67], v[80:83], v[0:3], a[64:67]
	v_mfma_f32_16x16x32_f16 a[44:47], v[174:177], v[20:23], a[44:47]
	v_mfma_f32_16x16x32_f16 a[40:43], v[88:91], v[20:23], a[40:43]
	v_mfma_f32_16x16x32_f16 a[36:39], v[84:87], v[20:23], a[36:39]
	v_mfma_f32_16x16x32_f16 a[16:19], v[80:83], v[20:23], a[16:19]
	s_branch .LBB0_920
.Lgw4_nl:
	s_waitcnt lgkmcnt(14)
	v_mfma_f32_16x16x32_f16 a[240:243], v[174:177], v[76:79], a[240:243]
	s_waitcnt lgkmcnt(14)
	v_mfma_f32_16x16x32_f16 a[252:255], v[88:91], v[76:79], a[252:255]
	s_waitcnt lgkmcnt(14)
	v_mfma_f32_16x16x32_f16 a[248:251], v[84:87], v[76:79], a[248:251]
	s_waitcnt lgkmcnt(14)
	v_mfma_f32_16x16x32_f16 a[244:247], v[80:83], v[76:79], a[244:247]
	v_mfma_f32_16x16x32_f16 a[236:239], v[174:177], v[72:75], a[236:239]
	v_mfma_f32_16x16x32_f16 a[232:235], v[88:91], v[72:75], a[232:235]
	v_mfma_f32_16x16x32_f16 a[228:231], v[84:87], v[72:75], a[228:231]
	v_mfma_f32_16x16x32_f16 a[224:227], v[80:83], v[72:75], a[224:227]
	v_mfma_f32_16x16x32_f16 a[220:223], v[174:177], v[52:55], a[220:223]
	v_mfma_f32_16x16x32_f16 a[216:219], v[88:91], v[52:55], a[216:219]
	v_mfma_f32_16x16x32_f16 a[212:215], v[84:87], v[52:55], a[212:215]
	v_mfma_f32_16x16x32_f16 a[204:207], v[80:83], v[52:55], a[204:207]
	v_mfma_f32_16x16x32_f16 a[172:175], v[174:177], v[40:43], a[172:175]
	v_mfma_f32_16x16x32_f16 a[168:171], v[88:91], v[40:43], a[168:171]
	v_mfma_f32_16x16x32_f16 a[164:167], v[84:87], v[40:43], a[164:167]
	v_mfma_f32_16x16x32_f16 a[160:163], v[80:83], v[40:43], a[160:163]
	v_mfma_f32_16x16x32_f16 a[140:143], v[174:177], v[48:51], a[140:143]
	v_mfma_f32_16x16x32_f16 a[136:139], v[88:91], v[48:51], a[136:139]
	v_mfma_f32_16x16x32_f16 a[132:135], v[84:87], v[48:51], a[132:135]
	v_mfma_f32_16x16x32_f16 a[128:131], v[80:83], v[48:51], a[128:131]
	v_mfma_f32_16x16x32_f16 a[108:111], v[174:177], v[36:39], a[108:111]
	v_mfma_f32_16x16x32_f16 a[104:107], v[88:91], v[36:39], a[104:107]
	v_mfma_f32_16x16x32_f16 a[100:103], v[84:87], v[36:39], a[100:103]
	v_mfma_f32_16x16x32_f16 a[96:99], v[80:83], v[36:39], a[96:99]
	v_mfma_f32_16x16x32_f16 a[76:79], v[174:177], v[0:3], a[76:79]
	v_mfma_f32_16x16x32_f16 a[72:75], v[88:91], v[0:3], a[72:75]
	v_mfma_f32_16x16x32_f16 a[68:71], v[84:87], v[0:3], a[68:71]
	v_mfma_f32_16x16x32_f16 a[64:67], v[80:83], v[0:3], a[64:67]
	v_mfma_f32_16x16x32_f16 a[44:47], v[174:177], v[20:23], a[44:47]
	v_mfma_f32_16x16x32_f16 a[40:43], v[88:91], v[20:23], a[40:43]
	v_mfma_f32_16x16x32_f16 a[36:39], v[84:87], v[20:23], a[36:39]
	v_mfma_f32_16x16x32_f16 a[16:19], v[80:83], v[20:23], a[16:19]
	s_branch .LBB0_920

; #define LD_AF(dst, ks_) _Pragma("unroll") for (int i = 0; i < 8; ++i) dst[i] = *(const h8*)(sA + i * 16 * G_LD + (ks_) * 32)
; #define LD_BF(dst, ks_, nh_) _Pragma("unroll") for (int i = 0; i < 4; ++i) dst[i] = *(const h8*)(sB + ((nh_) * 4 + i) * 16 * G_LD + (ks_) * 32)
; #define MMA_BLK(afx, bfx, nh_) _Pragma("unroll") for (int mi = 0; mi < 8; ++mi) _Pragma("unroll") for (int ni = 0; ni < 4; ++ni) mfma16_acc(acc[mi][(nh_) * 4 + ni], bfx[ni], afx[mi])
; template <class Epi>
; __device__ __forceinline__ void gemm_run(const GemmArgs g, Epi epi, char* smem) {
;     ...
;       const hf* sA = sbase + (kt & 1) * G_STAGE + (wm * 128 + fr) * G_LD + fqs;
;       const hf* sB = sbase + (kt & 1) * G_STAGE + (256 + wn * 128 + fr) * G_LD + fqs;
;       hf* st = sbase + ((kt + 1) & 1) * G_STAGE;
;       h8 afA[8], afB[8], bfA[4], bfB[4];
;     ...
;       LD_AF(afA, 0); LD_BF(bfA, 0, 0);
;       if (kt + 1 < nk) {
; #pragma unroll
;         for (int i = 0; i < 8; ++i) *(u4*)(st + (lr + 32 * i) * G_LD + lcw) = ra[i];
;       }
;       __builtin_amdgcn_sched_barrier(0);
;       LD_BF(bfB, 0, 1);
;       MMA_BLK(afA, bfA, 0);
;       __builtin_amdgcn_sched_barrier(0);
;       if (kt + 1 < nk) {
; #pragma unroll
;         for (int i = 0; i < 8; ++i) *(u4*)(st + (256 + lr + 32 * i) * G_LD + lcw) = rb[i];
;       }
;       LD_AF(afB, 1); LD_BF(bfA, 1, 0);
;       MMA_BLK(afA, bfB, 1);
.LBB0_950:
	s_bitcmp1_b32 s19, 0
	s_cselect_b32 s11, 0x12000, 0
	s_add_i32 s11, s11, 16
	v_add3_u32 v56, s11, v94, v105
	v_add3_u32 v106, s11, v96, v105
	ds_read_b128 v[0:3], v56 offset:13824
	ds_read_b128 v[16:19], v106 offset:36864
	ds_read_b128 v[12:15], v106 offset:39168
	ds_read_b128 v[8:11], v106 offset:41472
	ds_read_b128 v[4:7], v106 offset:43776
	ds_read_b128 v[76:79], v56
	ds_read_b128 v[72:75], v56 offset:2304
	ds_read_b128 v[52:55], v56 offset:4608
	ds_read_b128 v[40:43], v56 offset:6912
	ds_read_b128 v[48:51], v56 offset:9216
	ds_read_b128 v[36:39], v56 offset:11520
	ds_read_b128 v[20:23], v56 offset:16128
	s_mov_b32 s10, s19
	s_add_i32 s19, s19, 1
	s_bitcmp1_b32 s19, 0
	s_cselect_b32 s11, 0x12000, 0
	v_add_u32_e32 v24, s11, v93
	v_add_u32_e32 v25, v24, v98
	ds_read_b128 v[174:177], v106 offset:46080
	ds_read_b128 v[88:91], v106 offset:48384
	ds_read_b128 v[84:87], v106 offset:50688
	ds_read_b128 v[80:83], v106 offset:52992
	s_waitcnt lgkmcnt(10)
	v_mfma_f32_16x16x32_f16 a[120:123], v[16:19], v[76:79], a[120:123]
	v_mfma_f32_16x16x32_f16 a[116:119], v[12:15], v[76:79], a[116:119]
	s_waitcnt vmcnt(15)
	ds_write_b128 v25, v[108:111]
	v_mfma_f32_16x16x32_f16 a[112:115], v[8:11], v[76:79], a[112:115]
	v_mfma_f32_16x16x32_f16 a[160:163], v[4:7], v[76:79], a[160:163]
	s_waitcnt vmcnt(13)
	ds_write_b128 v25, v[116:119] offset:4608
	s_waitcnt lgkmcnt(11)
	v_mfma_f32_16x16x32_f16 a[152:155], v[16:19], v[72:75], a[152:155]
	v_mfma_f32_16x16x32_f16 a[148:151], v[12:15], v[72:75], a[148:151]
	s_waitcnt vmcnt(11)
	ds_write_b128 v25, v[120:123] offset:9216
	v_mfma_f32_16x16x32_f16 a[144:147], v[8:11], v[72:75], a[144:147]
	v_mfma_f32_16x16x32_f16 a[136:139], v[4:7], v[72:75], a[136:139]
	s_waitcnt vmcnt(9)
	ds_write_b128 v25, v[134:137] offset:13824
	s_waitcnt lgkmcnt(12)
	v_mfma_f32_16x16x32_f16 a[108:111], v[16:19], v[52:55], a[108:111]
	v_mfma_f32_16x16x32_f16 a[104:107], v[12:15], v[52:55], a[104:107]
	s_waitcnt vmcnt(7)
	ds_write_b128 v25, v[138:141] offset:18432
	v_mfma_f32_16x16x32_f16 a[100:103], v[8:11], v[52:55], a[100:103]
	v_mfma_f32_16x16x32_f16 a[92:95], v[4:7], v[52:55], a[92:95]
	s_waitcnt vmcnt(5)
	ds_write_b128 v25, v[150:153] offset:23040
	s_waitcnt lgkmcnt(13)
	v_mfma_f32_16x16x32_f16 a[80:83], v[16:19], v[40:43], a[80:83]
	v_mfma_f32_16x16x32_f16 a[76:79], v[12:15], v[40:43], a[76:79]
	s_waitcnt vmcnt(3)
	ds_write_b128 v25, v[154:157] offset:27648
	v_mfma_f32_16x16x32_f16 a[72:75], v[8:11], v[40:43], a[72:75]
	v_mfma_f32_16x16x32_f16 a[68:71], v[4:7], v[40:43], a[68:71]
	s_waitcnt vmcnt(1)
	ds_write_b128 v25, v[162:165] offset:32256
	s_waitcnt lgkmcnt(14)
	v_mfma_f32_16x16x32_f16 a[64:67], v[16:19], v[48:51], a[64:67]
	v_mfma_f32_16x16x32_f16 a[60:63], v[12:15], v[48:51], a[60:63]
	s_waitcnt vmcnt(7)
	ds_write_b128 v25, v[112:115] offset:36864
	v_mfma_f32_16x16x32_f16 a[56:59], v[8:11], v[48:51], a[56:59]
	v_mfma_f32_16x16x32_f16 a[52:55], v[4:7], v[48:51], a[52:55]
	s_waitcnt vmcnt(6)
	ds_write_b128 v25, v[124:127] offset:41472
	s_waitcnt lgkmcnt(14)
	v_mfma_f32_16x16x32_f16 a[44:47], v[16:19], v[36:39], a[44:47]
	v_mfma_f32_16x16x32_f16 a[40:43], v[12:15], v[36:39], a[40:43]
	s_waitcnt vmcnt(5)
	ds_write_b128 v25, v[128:131] offset:46080
	v_mfma_f32_16x16x32_f16 a[36:39], v[8:11], v[36:39], a[36:39]
	v_mfma_f32_16x16x32_f16 a[32:35], v[4:7], v[36:39], a[32:35]
	s_waitcnt vmcnt(4)
	ds_write_b128 v25, v[142:145] offset:50688
	v_mfma_f32_16x16x32_f16 a[28:31], v[16:19], v[0:3], a[28:31]
	v_mfma_f32_16x16x32_f16 a[24:27], v[12:15], v[0:3], a[24:27]
	s_waitcnt vmcnt(3)
	ds_write_b128 v25, v[146:149] offset:55296
	v_mfma_f32_16x16x32_f16 a[20:23], v[8:11], v[0:3], a[20:23]
	v_mfma_f32_16x16x32_f16 a[16:19], v[4:7], v[0:3], a[16:19]
	s_waitcnt vmcnt(2)
	ds_write_b128 v25, v[158:161] offset:59904
	s_waitcnt lgkmcnt(14)
	v_mfma_f32_16x16x32_f16 a[12:15], v[16:19], v[20:23], a[12:15]
	v_mfma_f32_16x16x32_f16 a[8:11], v[12:15], v[20:23], a[8:11]
	s_waitcnt vmcnt(1)
	ds_write_b128 v25, v[166:169] offset:64512
	v_mfma_f32_16x16x32_f16 a[4:7], v[8:11], v[20:23], a[4:7]
	v_mfma_f32_16x16x32_f16 a[0:3], v[4:7], v[20:23], a[0:3]
	v_add_u32_e32 v4, v24, v99
	s_waitcnt vmcnt(0)
	ds_write_b128 v4, v[170:173]
	ds_read_b128 v[44:47], v56 offset:64
	ds_read_b128 v[32:35], v56 offset:2368
	ds_read_b128 v[28:31], v56 offset:4672
	ds_read_b128 v[24:27], v56 offset:6976
	ds_read_b128 v[16:19], v56 offset:9280
	ds_read_b128 v[12:15], v56 offset:11584
	ds_read_b128 v[8:11], v56 offset:13888
	ds_read_b128 v[4:7], v56 offset:16192
	ds_read_b128 v[56:59], v106 offset:36928
	ds_read_b128 v[60:63], v106 offset:39232
	ds_read_b128 v[64:67], v106 offset:41536
	ds_read_b128 v[68:71], v106 offset:43840
	s_cmp_gt_u32 s10, 29
	s_cbranch_scc1 .Lgw5_nl
; #define MMA_BLK(afx, bfx, nh_) _Pragma("unroll") for (int mi = 0; mi < 8; ++mi) _Pragma("unroll") for (int ni = 0; ni < 4; ++ni) mfma16_acc(acc[mi][(nh_) * 4 + ni], bfx[ni], afx[mi])
; template <class Epi>
; __device__ __forceinline__ void gemm_run(const GemmArgs g, Epi epi, char* smem) {
;     ...
;       MMA_BLK(afA, bfB, 1);
;       __builtin_amdgcn_sched_barrier(0);
;       if (kt + 2 < nk) {
;         const int ko = (kt + 2) * 64;
; #pragma unroll
;         for (int i = 0; i < 8; ++i) { ra[i] = __builtin_amdgcn_raw_buffer_load_b128(Ars, aoff, i * astep + ko * 2, 0); rb[i] = __builtin_amdgcn_raw_buffer_load_b128(Brs, boff, i * bstep + ko * 2, 0); }
;       }
	s_waitcnt lgkmcnt(14)
	v_mfma_f32_16x16x32_f16 a[252:255], v[174:177], v[76:79], a[252:255]
	s_waitcnt lgkmcnt(14)
	v_mfma_f32_16x16x32_f16 a[248:251], v[88:91], v[76:79], a[248:251]
	s_waitcnt lgkmcnt(14)
	v_mfma_f32_16x16x32_f16 a[244:247], v[84:87], v[76:79], a[244:247]
	s_add_i32 s75, s17, 0xfff20000
	s_waitcnt lgkmcnt(14)
	v_mfma_f32_16x16x32_f16 a[240:243], v[80:83], v[76:79], a[240:243]
	s_mov_b32 s10, s6
	v_mfma_f32_16x16x32_f16 a[236:239], v[174:177], v[72:75], a[236:239]
	s_mov_b32 s11, s7
	v_mfma_f32_16x16x32_f16 a[232:235], v[88:91], v[72:75], a[232:235]
	buffer_load_dwordx4 v[108:111], v92, s[4:7], s75 offen
	v_mfma_f32_16x16x32_f16 a[228:231], v[84:87], v[72:75], a[228:231]
	buffer_load_dwordx4 v[112:115], v92, s[8:11], s75 offen
	v_mfma_f32_16x16x32_f16 a[224:227], v[80:83], v[72:75], a[224:227]
	s_add_i32 s75, s17, 0xfff40000
	v_mfma_f32_16x16x32_f16 a[220:223], v[174:177], v[52:55], a[220:223]
	buffer_load_dwordx4 v[116:119], v92, s[4:7], s75 offen
	v_mfma_f32_16x16x32_f16 a[216:219], v[88:91], v[52:55], a[216:219]
	buffer_load_dwordx4 v[124:127], v92, s[8:11], s75 offen
	v_mfma_f32_16x16x32_f16 a[212:215], v[84:87], v[52:55], a[212:215]
	s_add_i32 s75, s17, 0xfff60000
	v_mfma_f32_16x16x32_f16 a[208:211], v[80:83], v[52:55], a[208:211]
	buffer_load_dwordx4 v[120:123], v92, s[4:7], s75 offen
	v_mfma_f32_16x16x32_f16 a[204:207], v[174:177], v[40:43], a[204:207]
	buffer_load_dwordx4 v[128:131], v92, s[8:11], s75 offen
	v_mfma_f32_16x16x32_f16 a[200:203], v[88:91], v[40:43], a[200:203]
	s_add_i32 s75, s17, 0xfff80000
	v_mfma_f32_16x16x32_f16 a[196:199], v[84:87], v[40:43], a[196:199]
	buffer_load_dwordx4 v[134:137], v92, s[4:7], s75 offen
	v_mfma_f32_16x16x32_f16 a[192:195], v[80:83], v[40:43], a[192:195]
	buffer_load_dwordx4 v[142:145], v92, s[8:11], s75 offen
	v_mfma_f32_16x16x32_f16 a[188:191], v[174:177], v[48:51], a[188:191]
	s_add_i32 s75, s17, 0xfffa0000
	v_mfma_f32_16x16x32_f16 a[184:187], v[88:91], v[48:51], a[184:187]
	buffer_load_dwordx4 v[138:141], v92, s[4:7], s75 offen
	v_mfma_f32_16x16x32_f16 a[180:183], v[84:87], v[48:51], a[180:183]
	buffer_load_dwordx4 v[146:149], v92, s[8:11], s75 offen
	v_mfma_f32_16x16x32_f16 a[176:179], v[80:83], v[48:51], a[176:179]
	s_add_i32 s75, s17, 0xfffc0000
	v_mfma_f32_16x16x32_f16 a[172:175], v[174:177], v[36:39], a[172:175]
	buffer_load_dwordx4 v[150:153], v92, s[4:7], s75 offen
	v_mfma_f32_16x16x32_f16 a[168:171], v[88:91], v[36:39], a[168:171]
	buffer_load_dwordx4 v[158:161], v92, s[8:11], s75 offen
	v_mfma_f32_16x16x32_f16 a[164:167], v[84:87], v[36:39], a[164:167]
	s_add_i32 s75, s17, 0xfffe0000
	v_mfma_f32_16x16x32_f16 a[156:159], v[80:83], v[36:39], a[156:159]
	buffer_load_dwordx4 v[154:157], v92, s[4:7], s75 offen
	v_mfma_f32_16x16x32_f16 a[140:143], v[174:177], v[0:3], a[140:143]
	buffer_load_dwordx4 v[166:169], v92, s[8:11], s75 offen
	v_mfma_f32_16x16x32_f16 a[132:135], v[88:91], v[0:3], a[132:135]
	buffer_load_dwordx4 v[162:165], v92, s[4:7], s17 offen
	v_mfma_f32_16x16x32_f16 a[128:131], v[84:87], v[0:3], a[128:131]
	buffer_load_dwordx4 v[170:173], v92, s[8:11], s17 offen
	v_mfma_f32_16x16x32_f16 a[124:127], v[80:83], v[0:3], a[124:127]
	v_mfma_f32_16x16x32_f16 a[96:99], v[174:177], v[20:23], a[96:99]
	v_mfma_f32_16x16x32_f16 a[88:91], v[88:91], v[20:23], a[88:91]
	v_mfma_f32_16x16x32_f16 a[84:87], v[84:87], v[20:23], a[84:87]
	v_mfma_f32_16x16x32_f16 a[48:51], v[80:83], v[20:23], a[48:51]
	s_branch .LBB0_949
.Lgw5_nl:
	s_waitcnt lgkmcnt(14)
	v_mfma_f32_16x16x32_f16 a[252:255], v[174:177], v[76:79], a[252:255]
	s_waitcnt lgkmcnt(14)
	v_mfma_f32_16x16x32_f16 a[248:251], v[88:91], v[76:79], a[248:251]
	s_waitcnt lgkmcnt(14)
	v_mfma_f32_16x16x32_f16 a[244:247], v[84:87], v[76:79], a[244:247]
	s_waitcnt lgkmcnt(14)
	v_mfma_f32_16x16x32_f16 a[240:243], v[80:83], v[76:79], a[240:243]
	v_mfma_f32_16x16x32_f16 a[236:239], v[174:177], v[72:75], a[236:239]
	v_mfma_f32_16x16x32_f16 a[232:235], v[88:91], v[72:75], a[232:235]
	v_mfma_f32_16x16x32_f16 a[228:231], v[84:87], v[72:75], a[228:231]
	v_mfma_f32_16x16x32_f16 a[224:227], v[80:83], v[72:75], a[224:227]
	v_mfma_f32_16x16x32_f16 a[220:223], v[174:177], v[52:55], a[220:223]
	v_mfma_f32_16x16x32_f16 a[216:219], v[88:91], v[52:55], a[216:219]
	v_mfma_f32_16x16x32_f16 a[212:215], v[84:87], v[52:55], a[212:215]
	v_mfma_f32_16x16x32_f16 a[208:211], v[80:83], v[52:55], a[208:211]
	v_mfma_f32_16x16x32_f16 a[204:207], v[174:177], v[40:43], a[204:207]
	v_mfma_f32_16x16x32_f16 a[200:203], v[88:91], v[40:43], a[200:203]
	v_mfma_f32_16x16x32_f16 a[196:199], v[84:87], v[40:43], a[196:199]
	v_mfma_f32_16x16x32_f16 a[192:195], v[80:83], v[40:43], a[192:195]
	v_mfma_f32_16x16x32_f16 a[188:191], v[174:177], v[48:51], a[188:191]
	v_mfma_f32_16x16x32_f16 a[184:187], v[88:91], v[48:51], a[184:187]
	v_mfma_f32_16x16x32_f16 a[180:183], v[84:87], v[48:51], a[180:183]
	v_mfma_f32_16x16x32_f16 a[176:179], v[80:83], v[48:51], a[176:179]
	v_mfma_f32_16x16x32_f16 a[172:175], v[174:177], v[36:39], a[172:175]
	v_mfma_f32_16x16x32_f16 a[168:171], v[88:91], v[36:39], a[168:171]
	v_mfma_f32_16x16x32_f16 a[164:167], v[84:87], v[36:39], a[164:167]
	v_mfma_f32_16x16x32_f16 a[156:159], v[80:83], v[36:39], a[156:159]
	v_mfma_f32_16x16x32_f16 a[140:143], v[174:177], v[0:3], a[140:143]
	v_mfma_f32_16x16x32_f16 a[132:135], v[88:91], v[0:3], a[132:135]
	v_mfma_f32_16x16x32_f16 a[128:131], v[84:87], v[0:3], a[128:131]
	v_mfma_f32_16x16x32_f16 a[124:127], v[80:83], v[0:3], a[124:127]
	v_mfma_f32_16x16x32_f16 a[96:99], v[174:177], v[20:23], a[96:99]
	v_mfma_f32_16x16x32_f16 a[88:91], v[88:91], v[20:23], a[88:91]
	v_mfma_f32_16x16x32_f16 a[84:87], v[84:87], v[20:23], a[84:87]
	v_mfma_f32_16x16x32_f16 a[48:51], v[80:83], v[20:23], a[48:51]
	s_branch .LBB0_949

; #define LD_AF(dst, ks_) _Pragma("unroll") for (int i = 0; i < 8; ++i) dst[i] = *(const h8*)(sA + i * 16 * G_LD + (ks_) * 32)
; #define LD_BF(dst, ks_, nh_) _Pragma("unroll") for (int i = 0; i < 4; ++i) dst[i] = *(const h8*)(sB + ((nh_) * 4 + i) * 16 * G_LD + (ks_) * 32)
; #define MMA_BLK(afx, bfx, nh_) _Pragma("unroll") for (int mi = 0; mi < 8; ++mi) _Pragma("unroll") for (int ni = 0; ni < 4; ++ni) mfma16_acc(acc[mi][(nh_) * 4 + ni], bfx[ni], afx[mi])
; template <class Epi>
; __device__ __forceinline__ void gemm_run(const GemmArgs g, Epi epi, char* smem) {
;     ...
;     for (int kt = 0; kt < nk; ++kt) {
;       const hf* sA = sbase + (kt & 1) * G_STAGE + (wm * 128 + fr) * G_LD + fqs;
;       const hf* sB = sbase + (kt & 1) * G_STAGE + (256 + wn * 128 + fr) * G_LD + fqs;
;       hf* st = sbase + ((kt + 1) & 1) * G_STAGE;
;       h8 afA[8], afB[8], bfA[4], bfB[4];
;     ...
;       LD_AF(afA, 0); LD_BF(bfA, 0, 0);
;       if (kt + 1 < nk) {
; #pragma unroll
;         for (int i = 0; i < 8; ++i) *(u4*)(st + (lr + 32 * i) * G_LD + lcw) = ra[i];
;       }
;       __builtin_amdgcn_sched_barrier(0);
;       LD_BF(bfB, 0, 1);
;       MMA_BLK(afA, bfA, 0);
;       __builtin_amdgcn_sched_barrier(0);
;       if (kt + 1 < nk) {
; #pragma unroll
;         for (int i = 0; i < 8; ++i) *(u4*)(st + (256 + lr + 32 * i) * G_LD + lcw) = rb[i];
;       }
;       LD_AF(afB, 1); LD_BF(bfA, 1, 0);
;       MMA_BLK(afA, bfB, 1);
.LBB0_1002:
	s_bitcmp1_b32 s85, 0
	s_cselect_b32 s11, 0x12000, 0
	s_add_i32 s11, s11, 16
	v_add3_u32 v56, s11, v133, v141
	v_add3_u32 v92, s11, v134, v141
	ds_read_b128 v[4:7], v56 offset:13824
	ds_read_b128 v[16:19], v92 offset:36864
	ds_read_b128 v[12:15], v92 offset:39168
	ds_read_b128 v[8:11], v92 offset:41472
	ds_read_b128 v[0:3], v92 offset:43776
	ds_read_b128 v[76:79], v56
	ds_read_b128 v[72:75], v56 offset:2304
	ds_read_b128 v[52:55], v56 offset:4608
	ds_read_b128 v[44:47], v56 offset:6912
	ds_read_b128 v[48:51], v56 offset:9216
	ds_read_b128 v[40:43], v56 offset:11520
	ds_read_b128 v[32:35], v56 offset:16128
	s_mov_b32 s10, s85
	s_add_i32 s85, s85, 1
	s_bitcmp1_b32 s85, 0
	s_cselect_b32 s11, 0x12000, 0
	v_add_u32_e32 v20, s11, v131
	v_add_u32_e32 v21, v20, v136
	ds_read_b128 v[170:173], v92 offset:46080
	ds_read_b128 v[88:91], v92 offset:48384
	ds_read_b128 v[84:87], v92 offset:50688
	ds_read_b128 v[80:83], v92 offset:52992
	s_waitcnt lgkmcnt(10)
	v_mfma_f32_16x16x32_f16 a[204:207], v[16:19], v[76:79], a[204:207]
	v_mfma_f32_16x16x32_f16 a[200:203], v[12:15], v[76:79], a[200:203]
	s_waitcnt vmcnt(15)
	ds_write_b128 v21, v[94:97]
	v_mfma_f32_16x16x32_f16 a[196:199], v[8:11], v[76:79], a[196:199]
	v_mfma_f32_16x16x32_f16 a[188:191], v[0:3], v[76:79], a[188:191]
	s_waitcnt vmcnt(13)
	ds_write_b128 v21, v[102:105] offset:4608
	s_waitcnt lgkmcnt(11)
	v_mfma_f32_16x16x32_f16 a[192:195], v[16:19], v[72:75], a[192:195]
	v_mfma_f32_16x16x32_f16 a[184:187], v[12:15], v[72:75], a[184:187]
	s_waitcnt vmcnt(11)
	ds_write_b128 v21, v[106:109] offset:9216
	v_mfma_f32_16x16x32_f16 a[180:183], v[8:11], v[72:75], a[180:183]
	v_mfma_f32_16x16x32_f16 a[176:179], v[0:3], v[72:75], a[176:179]
	s_waitcnt vmcnt(9)
	ds_write_b128 v21, v[118:121] offset:13824
	s_waitcnt lgkmcnt(12)
	v_mfma_f32_16x16x32_f16 a[156:159], v[16:19], v[52:55], a[156:159]
	v_mfma_f32_16x16x32_f16 a[152:155], v[12:15], v[52:55], a[152:155]
	s_waitcnt vmcnt(7)
	ds_write_b128 v21, v[122:125] offset:18432
	v_mfma_f32_16x16x32_f16 a[148:151], v[8:11], v[52:55], a[148:151]
	v_mfma_f32_16x16x32_f16 a[144:147], v[0:3], v[52:55], a[144:147]
	s_waitcnt vmcnt(5)
	ds_write_b128 v21, v[146:149] offset:23040
	s_waitcnt lgkmcnt(13)
	v_mfma_f32_16x16x32_f16 a[124:127], v[16:19], v[44:47], a[124:127]
	v_mfma_f32_16x16x32_f16 a[120:123], v[12:15], v[44:47], a[120:123]
	s_waitcnt vmcnt(3)
	ds_write_b128 v21, v[150:153] offset:27648
	v_mfma_f32_16x16x32_f16 a[116:119], v[8:11], v[44:47], a[116:119]
	v_mfma_f32_16x16x32_f16 a[112:115], v[0:3], v[44:47], a[112:115]
	s_waitcnt vmcnt(1)
	ds_write_b128 v21, v[158:161] offset:32256
	s_waitcnt lgkmcnt(14)
	v_mfma_f32_16x16x32_f16 a[92:95], v[16:19], v[48:51], a[92:95]
	v_mfma_f32_16x16x32_f16 a[88:91], v[12:15], v[48:51], a[88:91]
	s_waitcnt vmcnt(7)
	ds_write_b128 v21, v[98:101] offset:36864
	v_mfma_f32_16x16x32_f16 a[84:87], v[8:11], v[48:51], a[84:87]
	v_mfma_f32_16x16x32_f16 a[80:83], v[0:3], v[48:51], a[80:83]
	s_waitcnt vmcnt(6)
	ds_write_b128 v21, v[110:113] offset:41472
	s_waitcnt lgkmcnt(14)
	v_mfma_f32_16x16x32_f16 a[60:63], v[16:19], v[40:43], a[60:63]
	v_mfma_f32_16x16x32_f16 a[56:59], v[12:15], v[40:43], a[56:59]
	s_waitcnt vmcnt(5)
	ds_write_b128 v21, v[114:117] offset:46080
	v_mfma_f32_16x16x32_f16 a[52:55], v[8:11], v[40:43], a[52:55]
	v_mfma_f32_16x16x32_f16 a[48:51], v[0:3], v[40:43], a[48:51]
	s_waitcnt vmcnt(4)
	ds_write_b128 v21, v[126:129] offset:50688
	v_mfma_f32_16x16x32_f16 a[32:35], v[16:19], v[4:7], a[32:35]
	v_mfma_f32_16x16x32_f16 a[28:31], v[12:15], v[4:7], a[28:31]
	s_waitcnt vmcnt(3)
	ds_write_b128 v21, v[142:145] offset:55296
	v_mfma_f32_16x16x32_f16 a[24:27], v[8:11], v[4:7], a[24:27]
	v_mfma_f32_16x16x32_f16 a[20:23], v[0:3], v[4:7], a[20:23]
	s_waitcnt vmcnt(2)
	ds_write_b128 v21, v[154:157] offset:59904
	s_waitcnt lgkmcnt(14)
	v_mfma_f32_16x16x32_f16 a[12:15], v[16:19], v[32:35], a[12:15]
	v_mfma_f32_16x16x32_f16 a[8:11], v[12:15], v[32:35], a[8:11]
	s_waitcnt vmcnt(1)
	ds_write_b128 v21, v[162:165] offset:64512
	v_mfma_f32_16x16x32_f16 a[4:7], v[8:11], v[32:35], a[4:7]
	v_mfma_f32_16x16x32_f16 a[0:3], v[0:3], v[32:35], a[0:3]
	v_add_u32_e32 v0, v20, v137
	s_waitcnt vmcnt(0)
	ds_write_b128 v0, v[166:169]
	ds_read_b128 v[36:39], v56 offset:64
	ds_read_b128 v[28:31], v56 offset:2368
	ds_read_b128 v[24:27], v56 offset:4672
	ds_read_b128 v[20:23], v56 offset:6976
	ds_read_b128 v[16:19], v56 offset:9280
	ds_read_b128 v[12:15], v56 offset:11584
	ds_read_b128 v[8:11], v56 offset:13888
	ds_read_b128 v[0:3], v56 offset:16192
	ds_read_b128 v[56:59], v92 offset:36928
	ds_read_b128 v[60:63], v92 offset:39232
	ds_read_b128 v[64:67], v92 offset:41536
	ds_read_b128 v[68:71], v92 offset:43840
	s_cmpk_gt_u32 s10, 0x55
	s_cbranch_scc1 .Lgw6_nl
; #define MMA_BLK(afx, bfx, nh_) _Pragma("unroll") for (int mi = 0; mi < 8; ++mi) _Pragma("unroll") for (int ni = 0; ni < 4; ++ni) mfma16_acc(acc[mi][(nh_) * 4 + ni], bfx[ni], afx[mi])
; template <class Epi>
; __device__ __forceinline__ void gemm_run(const GemmArgs g, Epi epi, char* smem) {
;     ...
;       MMA_BLK(afA, bfB, 1);
;       __builtin_amdgcn_sched_barrier(0);
;       if (kt + 2 < nk) {
;         const int ko = (kt + 2) * 64;
; #pragma unroll
;         for (int i = 0; i < 8; ++i) { ra[i] = __builtin_amdgcn_raw_buffer_load_b128(Ars, aoff, i * astep + ko * 2, 0); rb[i] = __builtin_amdgcn_raw_buffer_load_b128(Brs, boff, i * bstep + ko * 2, 0); }
;       }
	s_waitcnt lgkmcnt(14)
	v_mfma_f32_16x16x32_f16 a[240:243], v[170:173], v[76:79], a[240:243]
	s_waitcnt lgkmcnt(14)
	v_mfma_f32_16x16x32_f16 a[252:255], v[88:91], v[76:79], a[252:255]
	s_waitcnt lgkmcnt(14)
	v_mfma_f32_16x16x32_f16 a[248:251], v[84:87], v[76:79], a[248:251]
	s_add_i32 s86, s84, 0xffd98000
	s_waitcnt lgkmcnt(14)
	v_mfma_f32_16x16x32_f16 a[244:247], v[80:83], v[76:79], a[244:247]
	s_mov_b32 s10, s6
	v_mfma_f32_16x16x32_f16 a[236:239], v[170:173], v[72:75], a[236:239]
	s_mov_b32 s11, s7
	v_mfma_f32_16x16x32_f16 a[232:235], v[88:91], v[72:75], a[232:235]
	buffer_load_dwordx4 v[94:97], v130, s[4:7], s86 offen
	v_mfma_f32_16x16x32_f16 a[228:231], v[84:87], v[72:75], a[228:231]
	buffer_load_dwordx4 v[98:101], v130, s[8:11], s86 offen
	v_mfma_f32_16x16x32_f16 a[224:227], v[80:83], v[72:75], a[224:227]
	s_add_i32 s86, s84, 0xffdf0000
	v_mfma_f32_16x16x32_f16 a[220:223], v[170:173], v[52:55], a[220:223]
	buffer_load_dwordx4 v[102:105], v130, s[4:7], s86 offen
	v_mfma_f32_16x16x32_f16 a[216:219], v[88:91], v[52:55], a[216:219]
	buffer_load_dwordx4 v[110:113], v130, s[8:11], s86 offen
	v_mfma_f32_16x16x32_f16 a[212:215], v[84:87], v[52:55], a[212:215]
	s_add_i32 s86, s84, 0xffe48000
	v_mfma_f32_16x16x32_f16 a[208:211], v[80:83], v[52:55], a[208:211]
	buffer_load_dwordx4 v[106:109], v130, s[4:7], s86 offen
	v_mfma_f32_16x16x32_f16 a[172:175], v[170:173], v[44:47], a[172:175]
	buffer_load_dwordx4 v[114:117], v130, s[8:11], s86 offen
	v_mfma_f32_16x16x32_f16 a[168:171], v[88:91], v[44:47], a[168:171]
	s_add_i32 s86, s84, 0xffea0000
	v_mfma_f32_16x16x32_f16 a[164:167], v[84:87], v[44:47], a[164:167]
	buffer_load_dwordx4 v[118:121], v130, s[4:7], s86 offen
	v_mfma_f32_16x16x32_f16 a[160:163], v[80:83], v[44:47], a[160:163]
	buffer_load_dwordx4 v[126:129], v130, s[8:11], s86 offen
	v_mfma_f32_16x16x32_f16 a[140:143], v[170:173], v[48:51], a[140:143]
	s_add_i32 s86, s84, 0xffef8000
	v_mfma_f32_16x16x32_f16 a[136:139], v[88:91], v[48:51], a[136:139]
	buffer_load_dwordx4 v[122:125], v130, s[4:7], s86 offen
	v_mfma_f32_16x16x32_f16 a[132:135], v[84:87], v[48:51], a[132:135]
	buffer_load_dwordx4 v[142:145], v130, s[8:11], s86 offen
	v_mfma_f32_16x16x32_f16 a[128:131], v[80:83], v[48:51], a[128:131]
	s_add_i32 s86, s84, 0xfff50000
	v_mfma_f32_16x16x32_f16 a[108:111], v[170:173], v[40:43], a[108:111]
	buffer_load_dwordx4 v[146:149], v130, s[4:7], s86 offen
	v_mfma_f32_16x16x32_f16 a[104:107], v[88:91], v[40:43], a[104:107]
	buffer_load_dwordx4 v[154:157], v130, s[8:11], s86 offen
	v_mfma_f32_16x16x32_f16 a[100:103], v[84:87], v[40:43], a[100:103]
	s_add_i32 s86, s84, 0xfffa8000
	v_mfma_f32_16x16x32_f16 a[96:99], v[80:83], v[40:43], a[96:99]
	buffer_load_dwordx4 v[150:153], v130, s[4:7], s86 offen
	v_mfma_f32_16x16x32_f16 a[76:79], v[170:173], v[4:7], a[76:79]
	buffer_load_dwordx4 v[162:165], v130, s[8:11], s86 offen
	v_mfma_f32_16x16x32_f16 a[72:75], v[88:91], v[4:7], a[72:75]
	buffer_load_dwordx4 v[158:161], v130, s[4:7], s84 offen
	v_mfma_f32_16x16x32_f16 a[68:71], v[84:87], v[4:7], a[68:71]
	buffer_load_dwordx4 v[166:169], v130, s[8:11], s84 offen
	v_mfma_f32_16x16x32_f16 a[64:67], v[80:83], v[4:7], a[64:67]
	v_mfma_f32_16x16x32_f16 a[44:47], v[170:173], v[32:35], a[44:47]
	v_mfma_f32_16x16x32_f16 a[40:43], v[88:91], v[32:35], a[40:43]
	v_mfma_f32_16x16x32_f16 a[36:39], v[84:87], v[32:35], a[36:39]
	v_mfma_f32_16x16x32_f16 a[16:19], v[80:83], v[32:35], a[16:19]
	s_branch .LBB0_1001
.Lgw6_nl:
	s_waitcnt lgkmcnt(14)
	v_mfma_f32_16x16x32_f16 a[240:243], v[170:173], v[76:79], a[240:243]
	s_waitcnt lgkmcnt(14)
	v_mfma_f32_16x16x32_f16 a[252:255], v[88:91], v[76:79], a[252:255]
	s_waitcnt lgkmcnt(14)
	v_mfma_f32_16x16x32_f16 a[248:251], v[84:87], v[76:79], a[248:251]
	s_waitcnt lgkmcnt(14)
	v_mfma_f32_16x16x32_f16 a[244:247], v[80:83], v[76:79], a[244:247]
	v_mfma_f32_16x16x32_f16 a[236:239], v[170:173], v[72:75], a[236:239]
	v_mfma_f32_16x16x32_f16 a[232:235], v[88:91], v[72:75], a[232:235]
	v_mfma_f32_16x16x32_f16 a[228:231], v[84:87], v[72:75], a[228:231]
	v_mfma_f32_16x16x32_f16 a[224:227], v[80:83], v[72:75], a[224:227]
	v_mfma_f32_16x16x32_f16 a[220:223], v[170:173], v[52:55], a[220:223]
	v_mfma_f32_16x16x32_f16 a[216:219], v[88:91], v[52:55], a[216:219]
	v_mfma_f32_16x16x32_f16 a[212:215], v[84:87], v[52:55], a[212:215]
	v_mfma_f32_16x16x32_f16 a[208:211], v[80:83], v[52:55], a[208:211]
	v_mfma_f32_16x16x32_f16 a[172:175], v[170:173], v[44:47], a[172:175]
	v_mfma_f32_16x16x32_f16 a[168:171], v[88:91], v[44:47], a[168:171]
	v_mfma_f32_16x16x32_f16 a[164:167], v[84:87], v[44:47], a[164:167]
	v_mfma_f32_16x16x32_f16 a[160:163], v[80:83], v[44:47], a[160:163]
	v_mfma_f32_16x16x32_f16 a[140:143], v[170:173], v[48:51], a[140:143]
	v_mfma_f32_16x16x32_f16 a[136:139], v[88:91], v[48:51], a[136:139]
	v_mfma_f32_16x16x32_f16 a[132:135], v[84:87], v[48:51], a[132:135]
	v_mfma_f32_16x16x32_f16 a[128:131], v[80:83], v[48:51], a[128:131]
	v_mfma_f32_16x16x32_f16 a[108:111], v[170:173], v[40:43], a[108:111]
	v_mfma_f32_16x16x32_f16 a[104:107], v[88:91], v[40:43], a[104:107]
	v_mfma_f32_16x16x32_f16 a[100:103], v[84:87], v[40:43], a[100:103]
	v_mfma_f32_16x16x32_f16 a[96:99], v[80:83], v[40:43], a[96:99]
	v_mfma_f32_16x16x32_f16 a[76:79], v[170:173], v[4:7], a[76:79]
	v_mfma_f32_16x16x32_f16 a[72:75], v[88:91], v[4:7], a[72:75]
	v_mfma_f32_16x16x32_f16 a[68:71], v[84:87], v[4:7], a[68:71]
	v_mfma_f32_16x16x32_f16 a[64:67], v[80:83], v[4:7], a[64:67]
	v_mfma_f32_16x16x32_f16 a[44:47], v[170:173], v[32:35], a[44:47]
	v_mfma_f32_16x16x32_f16 a[40:43], v[88:91], v[32:35], a[40:43]
	v_mfma_f32_16x16x32_f16 a[36:39], v[84:87], v[32:35], a[36:39]
	v_mfma_f32_16x16x32_f16 a[16:19], v[80:83], v[32:35], a[16:19]
	s_branch .LBB0_1001

; #define LD_AF(dst, ks_) _Pragma("unroll") for (int i = 0; i < 8; ++i) dst[i] = *(const h8*)(sA + i * 16 * G_LD + (ks_) * 32)
; #define LD_BF(dst, ks_, nh_) _Pragma("unroll") for (int i = 0; i < 4; ++i) dst[i] = *(const h8*)(sB + ((nh_) * 4 + i) * 16 * G_LD + (ks_) * 32)
; #define MMA_BLK(afx, bfx, nh_) _Pragma("unroll") for (int mi = 0; mi < 8; ++mi) _Pragma("unroll") for (int ni = 0; ni < 4; ++ni) mfma16_acc(acc[mi][(nh_) * 4 + ni], bfx[ni], afx[mi])
; template <class Epi>
; __device__ __forceinline__ void gemm_run(const GemmArgs g, Epi epi, char* smem) {
;     ...
;     for (int kt = 0; kt < nk; ++kt) {
;       const hf* sA = sbase + (kt & 1) * G_STAGE + (wm * 128 + fr) * G_LD + fqs;
;       const hf* sB = sbase + (kt & 1) * G_STAGE + (256 + wn * 128 + fr) * G_LD + fqs;
;       hf* st = sbase + ((kt + 1) & 1) * G_STAGE;
;       h8 afA[8], afB[8], bfA[4], bfB[4];
;     ...
;       LD_AF(afA, 0); LD_BF(bfA, 0, 0);
;       if (kt + 1 < nk) {
; #pragma unroll
;         for (int i = 0; i < 8; ++i) *(u4*)(st + (lr + 32 * i) * G_LD + lcw) = ra[i];
;       }
;       __builtin_amdgcn_sched_barrier(0);
;       LD_BF(bfB, 0, 1);
;       MMA_BLK(afA, bfA, 0);
;       __builtin_amdgcn_sched_barrier(0);
;       if (kt + 1 < nk) {
; #pragma unroll
;         for (int i = 0; i < 8; ++i) *(u4*)(st + (256 + lr + 32 * i) * G_LD + lcw) = rb[i];
;       }
;       LD_AF(afB, 1); LD_BF(bfA, 1, 0);
;       MMA_BLK(afA, bfB, 1);
.LBB0_1008:
	s_bitcmp1_b32 s23, 0
	s_cselect_b32 s15, 0x12000, 0
	s_add_i32 s15, s15, 16
	v_add3_u32 v56, s15, v94, v105
	v_add3_u32 v106, s15, v96, v105
	ds_read_b128 v[4:7], v56 offset:13824
	ds_read_b128 v[16:19], v106 offset:36864
	ds_read_b128 v[12:15], v106 offset:39168
	ds_read_b128 v[8:11], v106 offset:41472
	ds_read_b128 v[0:3], v106 offset:43776
	ds_read_b128 v[76:79], v56
	ds_read_b128 v[72:75], v56 offset:2304
	ds_read_b128 v[52:55], v56 offset:4608
	ds_read_b128 v[44:47], v56 offset:6912
	ds_read_b128 v[48:51], v56 offset:9216
	ds_read_b128 v[40:43], v56 offset:11520
	ds_read_b128 v[32:35], v56 offset:16128
	s_mov_b32 s14, s23
	s_add_i32 s23, s23, 1
	s_bitcmp1_b32 s23, 0
	s_cselect_b32 s15, 0x12000, 0
	v_add_u32_e32 v20, s15, v93
	v_add_u32_e32 v21, v20, v98
	ds_read_b128 v[172:175], v106 offset:46080
	ds_read_b128 v[88:91], v106 offset:48384
	ds_read_b128 v[84:87], v106 offset:50688
	ds_read_b128 v[80:83], v106 offset:52992
	s_waitcnt lgkmcnt(10)
	v_mfma_f32_16x16x32_f16 a[116:119], v[16:19], v[76:79], a[116:119]
	v_mfma_f32_16x16x32_f16 a[108:111], v[12:15], v[76:79], a[108:111]
	s_waitcnt vmcnt(15)
	ds_write_b128 v21, v[108:111]
	v_mfma_f32_16x16x32_f16 a[100:103], v[8:11], v[76:79], a[100:103]
	v_mfma_f32_16x16x32_f16 a[160:163], v[0:3], v[76:79], a[160:163]
	s_waitcnt vmcnt(13)
	ds_write_b128 v21, v[116:119] offset:4608
	s_waitcnt lgkmcnt(11)
	v_mfma_f32_16x16x32_f16 a[152:155], v[16:19], v[72:75], a[152:155]
	v_mfma_f32_16x16x32_f16 a[148:151], v[12:15], v[72:75], a[148:151]
	s_waitcnt vmcnt(11)
	ds_write_b128 v21, v[120:123] offset:9216
	v_mfma_f32_16x16x32_f16 a[144:147], v[8:11], v[72:75], a[144:147]
	v_mfma_f32_16x16x32_f16 a[136:139], v[0:3], v[72:75], a[136:139]
	s_waitcnt vmcnt(9)
	ds_write_b128 v21, v[132:135] offset:13824
	s_waitcnt lgkmcnt(12)
	v_mfma_f32_16x16x32_f16 a[120:123], v[16:19], v[52:55], a[120:123]
	v_mfma_f32_16x16x32_f16 a[112:115], v[12:15], v[52:55], a[112:115]
	s_waitcnt vmcnt(7)
	ds_write_b128 v21, v[136:139] offset:18432
	v_mfma_f32_16x16x32_f16 a[104:107], v[8:11], v[52:55], a[104:107]
	v_mfma_f32_16x16x32_f16 a[92:95], v[0:3], v[52:55], a[92:95]
	s_waitcnt vmcnt(5)
	ds_write_b128 v21, v[148:151] offset:23040
	s_waitcnt lgkmcnt(13)
	v_mfma_f32_16x16x32_f16 a[80:83], v[16:19], v[44:47], a[80:83]
	v_mfma_f32_16x16x32_f16 a[76:79], v[12:15], v[44:47], a[76:79]
	s_waitcnt vmcnt(3)
	ds_write_b128 v21, v[152:155] offset:27648
	v_mfma_f32_16x16x32_f16 a[72:75], v[8:11], v[44:47], a[72:75]
	v_mfma_f32_16x16x32_f16 a[68:71], v[0:3], v[44:47], a[68:71]
	s_waitcnt vmcnt(1)
	ds_write_b128 v21, v[160:163] offset:32256
	s_waitcnt lgkmcnt(14)
	v_mfma_f32_16x16x32_f16 a[64:67], v[16:19], v[48:51], a[64:67]
	v_mfma_f32_16x16x32_f16 a[60:63], v[12:15], v[48:51], a[60:63]
	s_waitcnt vmcnt(7)
	ds_write_b128 v21, v[112:115] offset:36864
	v_mfma_f32_16x16x32_f16 a[56:59], v[8:11], v[48:51], a[56:59]
	v_mfma_f32_16x16x32_f16 a[52:55], v[0:3], v[48:51], a[52:55]
	s_waitcnt vmcnt(6)
	ds_write_b128 v21, v[124:127] offset:41472
	s_waitcnt lgkmcnt(14)
	v_mfma_f32_16x16x32_f16 a[44:47], v[16:19], v[40:43], a[44:47]
	v_mfma_f32_16x16x32_f16 a[40:43], v[12:15], v[40:43], a[40:43]
	s_waitcnt vmcnt(5)
	ds_write_b128 v21, v[128:131] offset:46080
	v_mfma_f32_16x16x32_f16 a[36:39], v[8:11], v[40:43], a[36:39]
	v_mfma_f32_16x16x32_f16 a[32:35], v[0:3], v[40:43], a[32:35]
	s_waitcnt vmcnt(4)
	ds_write_b128 v21, v[140:143] offset:50688
	v_mfma_f32_16x16x32_f16 a[28:31], v[16:19], v[4:7], a[28:31]
	v_mfma_f32_16x16x32_f16 a[24:27], v[12:15], v[4:7], a[24:27]
	s_waitcnt vmcnt(3)
	ds_write_b128 v21, v[144:147] offset:55296
	v_mfma_f32_16x16x32_f16 a[20:23], v[8:11], v[4:7], a[20:23]
	v_mfma_f32_16x16x32_f16 a[16:19], v[0:3], v[4:7], a[16:19]
	s_waitcnt vmcnt(2)
	ds_write_b128 v21, v[156:159] offset:59904
	s_waitcnt lgkmcnt(14)
	v_mfma_f32_16x16x32_f16 a[12:15], v[16:19], v[32:35], a[12:15]
	v_mfma_f32_16x16x32_f16 a[8:11], v[12:15], v[32:35], a[8:11]
	s_waitcnt vmcnt(1)
	ds_write_b128 v21, v[164:167] offset:64512
	v_mfma_f32_16x16x32_f16 a[4:7], v[8:11], v[32:35], a[4:7]
	v_mfma_f32_16x16x32_f16 a[0:3], v[0:3], v[32:35], a[0:3]
	v_add_u32_e32 v0, v20, v99
	s_waitcnt vmcnt(0)
	ds_write_b128 v0, v[168:171]
	ds_read_b128 v[36:39], v56 offset:64
	ds_read_b128 v[28:31], v56 offset:2368
	ds_read_b128 v[24:27], v56 offset:4672
	ds_read_b128 v[20:23], v56 offset:6976
	ds_read_b128 v[16:19], v56 offset:9280
	ds_read_b128 v[12:15], v56 offset:11584
	ds_read_b128 v[8:11], v56 offset:13888
	ds_read_b128 v[0:3], v56 offset:16192
	ds_read_b128 v[56:59], v106 offset:36928
	ds_read_b128 v[60:63], v106 offset:39232
	ds_read_b128 v[64:67], v106 offset:41536
	ds_read_b128 v[68:71], v106 offset:43840
	s_cmp_gt_u32 s14, 29
	s_cbranch_scc1 .Lgw7_nl
; #define MMA_BLK(afx, bfx, nh_) _Pragma("unroll") for (int mi = 0; mi < 8; ++mi) _Pragma("unroll") for (int ni = 0; ni < 4; ++ni) mfma16_acc(acc[mi][(nh_) * 4 + ni], bfx[ni], afx[mi])
; template <class Epi>
; __device__ __forceinline__ void gemm_run(const GemmArgs g, Epi epi, char* smem) {
;     ...
;       MMA_BLK(afA, bfB, 1);
;       __builtin_amdgcn_sched_barrier(0);
;       if (kt + 2 < nk) {
;         const int ko = (kt + 2) * 64;
; #pragma unroll
;         for (int i = 0; i < 8; ++i) { ra[i] = __builtin_amdgcn_raw_buffer_load_b128(Ars, aoff, i * astep + ko * 2, 0); rb[i] = __builtin_amdgcn_raw_buffer_load_b128(Brs, boff, i * bstep + ko * 2, 0); }
;       }
	s_waitcnt lgkmcnt(14)
	v_mfma_f32_16x16x32_f16 a[252:255], v[172:175], v[76:79], a[252:255]
	s_waitcnt lgkmcnt(14)
	v_mfma_f32_16x16x32_f16 a[248:251], v[88:91], v[76:79], a[248:251]
	s_waitcnt lgkmcnt(14)
	v_mfma_f32_16x16x32_f16 a[244:247], v[84:87], v[76:79], a[244:247]
	s_add_i32 s87, s7, 0xfff20000
	s_waitcnt lgkmcnt(14)
	v_mfma_f32_16x16x32_f16 a[240:243], v[80:83], v[76:79], a[240:243]
	s_mov_b32 s14, s10
	v_mfma_f32_16x16x32_f16 a[236:239], v[172:175], v[72:75], a[236:239]
	s_mov_b32 s15, s11
	v_mfma_f32_16x16x32_f16 a[232:235], v[88:91], v[72:75], a[232:235]
	buffer_load_dwordx4 v[108:111], v92, s[8:11], s87 offen
	v_mfma_f32_16x16x32_f16 a[228:231], v[84:87], v[72:75], a[228:231]
	buffer_load_dwordx4 v[112:115], v92, s[12:15], s87 offen
	v_mfma_f32_16x16x32_f16 a[224:227], v[80:83], v[72:75], a[224:227]
	s_add_i32 s87, s7, 0xfff40000
	v_mfma_f32_16x16x32_f16 a[220:223], v[172:175], v[52:55], a[220:223]
	buffer_load_dwordx4 v[116:119], v92, s[8:11], s87 offen
	v_mfma_f32_16x16x32_f16 a[216:219], v[88:91], v[52:55], a[216:219]
	buffer_load_dwordx4 v[124:127], v92, s[12:15], s87 offen
	v_mfma_f32_16x16x32_f16 a[212:215], v[84:87], v[52:55], a[212:215]
	s_add_i32 s87, s7, 0xfff60000
	v_mfma_f32_16x16x32_f16 a[208:211], v[80:83], v[52:55], a[208:211]
	buffer_load_dwordx4 v[120:123], v92, s[8:11], s87 offen
	v_mfma_f32_16x16x32_f16 a[204:207], v[172:175], v[44:47], a[204:207]
	buffer_load_dwordx4 v[128:131], v92, s[12:15], s87 offen
	v_mfma_f32_16x16x32_f16 a[200:203], v[88:91], v[44:47], a[200:203]
	s_add_i32 s87, s7, 0xfff80000
	v_mfma_f32_16x16x32_f16 a[196:199], v[84:87], v[44:47], a[196:199]
	buffer_load_dwordx4 v[132:135], v92, s[8:11], s87 offen
	v_mfma_f32_16x16x32_f16 a[192:195], v[80:83], v[44:47], a[192:195]
	buffer_load_dwordx4 v[140:143], v92, s[12:15], s87 offen
	v_mfma_f32_16x16x32_f16 a[188:191], v[172:175], v[48:51], a[188:191]
	s_add_i32 s87, s7, 0xfffa0000
	v_mfma_f32_16x16x32_f16 a[184:187], v[88:91], v[48:51], a[184:187]
	buffer_load_dwordx4 v[136:139], v92, s[8:11], s87 offen
	v_mfma_f32_16x16x32_f16 a[180:183], v[84:87], v[48:51], a[180:183]
	buffer_load_dwordx4 v[144:147], v92, s[12:15], s87 offen
	v_mfma_f32_16x16x32_f16 a[176:179], v[80:83], v[48:51], a[176:179]
	s_add_i32 s87, s7, 0xfffc0000
	v_mfma_f32_16x16x32_f16 a[172:175], v[172:175], v[40:43], a[172:175]
	buffer_load_dwordx4 v[148:151], v92, s[8:11], s87 offen
	v_mfma_f32_16x16x32_f16 a[168:171], v[88:91], v[40:43], a[168:171]
	buffer_load_dwordx4 v[156:159], v92, s[12:15], s87 offen
	v_mfma_f32_16x16x32_f16 a[164:167], v[84:87], v[40:43], a[164:167]
	s_add_i32 s87, s7, 0xfffe0000
	v_mfma_f32_16x16x32_f16 a[156:159], v[80:83], v[40:43], a[156:159]
	buffer_load_dwordx4 v[152:155], v92, s[8:11], s87 offen
	v_mfma_f32_16x16x32_f16 a[140:143], v[172:175], v[4:7], a[140:143]
	buffer_load_dwordx4 v[164:167], v92, s[12:15], s87 offen
	v_mfma_f32_16x16x32_f16 a[132:135], v[88:91], v[4:7], a[132:135]
	buffer_load_dwordx4 v[160:163], v92, s[8:11], s7 offen
	v_mfma_f32_16x16x32_f16 a[128:131], v[84:87], v[4:7], a[128:131]
	buffer_load_dwordx4 v[168:171], v92, s[12:15], s7 offen
	v_mfma_f32_16x16x32_f16 a[124:127], v[80:83], v[4:7], a[124:127]
	v_mfma_f32_16x16x32_f16 a[96:99], v[172:175], v[32:35], a[96:99]
	v_mfma_f32_16x16x32_f16 a[88:91], v[88:91], v[32:35], a[88:91]
	v_mfma_f32_16x16x32_f16 a[84:87], v[84:87], v[32:35], a[84:87]
	v_mfma_f32_16x16x32_f16 a[48:51], v[80:83], v[32:35], a[48:51]
	s_branch .LBB0_1007
.Lgw7_nl:
	s_waitcnt lgkmcnt(14)
	v_mfma_f32_16x16x32_f16 a[252:255], v[172:175], v[76:79], a[252:255]
	s_waitcnt lgkmcnt(14)
	v_mfma_f32_16x16x32_f16 a[248:251], v[88:91], v[76:79], a[248:251]
	s_waitcnt lgkmcnt(14)
	v_mfma_f32_16x16x32_f16 a[244:247], v[84:87], v[76:79], a[244:247]
	s_waitcnt lgkmcnt(14)
	v_mfma_f32_16x16x32_f16 a[240:243], v[80:83], v[76:79], a[240:243]
	v_mfma_f32_16x16x32_f16 a[236:239], v[172:175], v[72:75], a[236:239]
	v_mfma_f32_16x16x32_f16 a[232:235], v[88:91], v[72:75], a[232:235]
	v_mfma_f32_16x16x32_f16 a[228:231], v[84:87], v[72:75], a[228:231]
	v_mfma_f32_16x16x32_f16 a[224:227], v[80:83], v[72:75], a[224:227]
	v_mfma_f32_16x16x32_f16 a[220:223], v[172:175], v[52:55], a[220:223]
	v_mfma_f32_16x16x32_f16 a[216:219], v[88:91], v[52:55], a[216:219]
	v_mfma_f32_16x16x32_f16 a[212:215], v[84:87], v[52:55], a[212:215]
	v_mfma_f32_16x16x32_f16 a[208:211], v[80:83], v[52:55], a[208:211]
	v_mfma_f32_16x16x32_f16 a[204:207], v[172:175], v[44:47], a[204:207]
	v_mfma_f32_16x16x32_f16 a[200:203], v[88:91], v[44:47], a[200:203]
	v_mfma_f32_16x16x32_f16 a[196:199], v[84:87], v[44:47], a[196:199]
	v_mfma_f32_16x16x32_f16 a[192:195], v[80:83], v[44:47], a[192:195]
	v_mfma_f32_16x16x32_f16 a[188:191], v[172:175], v[48:51], a[188:191]
	v_mfma_f32_16x16x32_f16 a[184:187], v[88:91], v[48:51], a[184:187]
	v_mfma_f32_16x16x32_f16 a[180:183], v[84:87], v[48:51], a[180:183]
	v_mfma_f32_16x16x32_f16 a[176:179], v[80:83], v[48:51], a[176:179]
	v_mfma_f32_16x16x32_f16 a[172:175], v[172:175], v[40:43], a[172:175]
	v_mfma_f32_16x16x32_f16 a[168:171], v[88:91], v[40:43], a[168:171]
	v_mfma_f32_16x16x32_f16 a[164:167], v[84:87], v[40:43], a[164:167]
	v_mfma_f32_16x16x32_f16 a[156:159], v[80:83], v[40:43], a[156:159]
	v_mfma_f32_16x16x32_f16 a[140:143], v[172:175], v[4:7], a[140:143]
	v_mfma_f32_16x16x32_f16 a[132:135], v[88:91], v[4:7], a[132:135]
	v_mfma_f32_16x16x32_f16 a[128:131], v[84:87], v[4:7], a[128:131]
	v_mfma_f32_16x16x32_f16 a[124:127], v[80:83], v[4:7], a[124:127]
	v_mfma_f32_16x16x32_f16 a[96:99], v[172:175], v[32:35], a[96:99]
	v_mfma_f32_16x16x32_f16 a[88:91], v[88:91], v[32:35], a[88:91]
	v_mfma_f32_16x16x32_f16 a[84:87], v[84:87], v[32:35], a[84:87]
	v_mfma_f32_16x16x32_f16 a[48:51], v[80:83], v[32:35], a[48:51]
	s_branch .LBB0_1007

; #define LD_AF(dst, ks_) _Pragma("unroll") for (int i = 0; i < 8; ++i) dst[i] = *(const h8*)(sA + i * 16 * G_LD + (ks_) * 32)
; #define LD_BF(dst, ks_, nh_) _Pragma("unroll") for (int i = 0; i < 4; ++i) dst[i] = *(const h8*)(sB + ((nh_) * 4 + i) * 16 * G_LD + (ks_) * 32)
; #define MMA_BLK(afx, bfx, nh_) _Pragma("unroll") for (int mi = 0; mi < 8; ++mi) _Pragma("unroll") for (int ni = 0; ni < 4; ++ni) mfma16_acc(acc[mi][(nh_) * 4 + ni], bfx[ni], afx[mi])
; template <class Epi>
; __device__ __forceinline__ void gemm_run(const GemmArgs g, Epi epi, char* smem) {
;     ...
;     for (int kt = 0; kt < nk; ++kt) {
;       const hf* sA = sbase + (kt & 1) * G_STAGE + (wm * 128 + fr) * G_LD + fqs;
;       const hf* sB = sbase + (kt & 1) * G_STAGE + (256 + wn * 128 + fr) * G_LD + fqs;
;       hf* st = sbase + ((kt + 1) & 1) * G_STAGE;
;       h8 afA[8], afB[8], bfA[4], bfB[4];
;     ...
;       LD_AF(afA, 0); LD_BF(bfA, 0, 0);
;       if (kt + 1 < nk) {
; #pragma unroll
;         for (int i = 0; i < 8; ++i) *(u4*)(st + (lr + 32 * i) * G_LD + lcw) = ra[i];
;       }
;       __builtin_amdgcn_sched_barrier(0);
;       LD_BF(bfB, 0, 1);
;       MMA_BLK(afA, bfA, 0);
;       __builtin_amdgcn_sched_barrier(0);
;       if (kt + 1 < nk) {
; #pragma unroll
;         for (int i = 0; i < 8; ++i) *(u4*)(st + (256 + lr + 32 * i) * G_LD + lcw) = rb[i];
;       }
;       LD_AF(afB, 1); LD_BF(bfA, 1, 0);
;       MMA_BLK(afA, bfB, 1);
.LBB0_1059:
	s_bitcmp1_b32 s87, 0
	s_cselect_b32 s15, 0x12000, 0
	s_add_i32 s15, s15, 16
	v_add3_u32 v56, s15, v133, v141
	v_add3_u32 v92, s15, v134, v141
	ds_read_b128 v[4:7], v56 offset:13824
	ds_read_b128 v[16:19], v92 offset:36864
	ds_read_b128 v[12:15], v92 offset:39168
	ds_read_b128 v[8:11], v92 offset:41472
	ds_read_b128 v[0:3], v92 offset:43776
	ds_read_b128 v[76:79], v56
	ds_read_b128 v[72:75], v56 offset:2304
	ds_read_b128 v[52:55], v56 offset:4608
	ds_read_b128 v[44:47], v56 offset:6912
	ds_read_b128 v[48:51], v56 offset:9216
	ds_read_b128 v[40:43], v56 offset:11520
	ds_read_b128 v[32:35], v56 offset:16128
	s_mov_b32 s14, s87
	s_add_i32 s87, s87, 1
	s_bitcmp1_b32 s87, 0
	s_cselect_b32 s15, 0x12000, 0
	v_add_u32_e32 v20, s15, v131
	v_add_u32_e32 v21, v20, v136
	ds_read_b128 v[170:173], v92 offset:46080
	ds_read_b128 v[88:91], v92 offset:48384
	ds_read_b128 v[84:87], v92 offset:50688
	ds_read_b128 v[80:83], v92 offset:52992
	s_waitcnt lgkmcnt(10)
	v_mfma_f32_16x16x32_f16 a[220:223], v[16:19], v[76:79], a[220:223]
	v_mfma_f32_16x16x32_f16 a[216:219], v[12:15], v[76:79], a[216:219]
	s_waitcnt vmcnt(15)
	ds_write_b128 v21, v[94:97]
	v_mfma_f32_16x16x32_f16 a[212:215], v[8:11], v[76:79], a[212:215]
	v_mfma_f32_16x16x32_f16 a[208:211], v[0:3], v[76:79], a[208:211]
	s_waitcnt vmcnt(13)
	ds_write_b128 v21, v[102:105] offset:4608
	s_waitcnt lgkmcnt(11)
	v_mfma_f32_16x16x32_f16 a[200:203], v[16:19], v[72:75], a[200:203]
	v_mfma_f32_16x16x32_f16 a[196:199], v[12:15], v[72:75], a[196:199]
	s_waitcnt vmcnt(11)
	ds_write_b128 v21, v[106:109] offset:9216
	v_mfma_f32_16x16x32_f16 a[188:191], v[8:11], v[72:75], a[188:191]
	v_mfma_f32_16x16x32_f16 a[180:183], v[0:3], v[72:75], a[180:183]
	s_waitcnt vmcnt(9)
	ds_write_b128 v21, v[118:121] offset:13824
	s_waitcnt lgkmcnt(12)
	v_mfma_f32_16x16x32_f16 a[172:175], v[16:19], v[52:55], a[172:175]
	v_mfma_f32_16x16x32_f16 a[164:167], v[12:15], v[52:55], a[164:167]
	s_waitcnt vmcnt(7)
	ds_write_b128 v21, v[122:125] offset:18432
	v_mfma_f32_16x16x32_f16 a[156:159], v[8:11], v[52:55], a[156:159]
	v_mfma_f32_16x16x32_f16 a[148:151], v[0:3], v[52:55], a[148:151]
	s_waitcnt vmcnt(5)
	ds_write_b128 v21, v[146:149] offset:23040
	s_waitcnt lgkmcnt(13)
	v_mfma_f32_16x16x32_f16 a[140:143], v[16:19], v[44:47], a[140:143]
	v_mfma_f32_16x16x32_f16 a[132:135], v[12:15], v[44:47], a[132:135]
	s_waitcnt vmcnt(3)
	ds_write_b128 v21, v[150:153] offset:27648
	v_mfma_f32_16x16x32_f16 a[124:127], v[8:11], v[44:47], a[124:127]
	v_mfma_f32_16x16x32_f16 a[116:119], v[0:3], v[44:47], a[116:119]
	s_waitcnt vmcnt(1)
	ds_write_b128 v21, v[158:161] offset:32256
	s_waitcnt lgkmcnt(14)
	v_mfma_f32_16x16x32_f16 a[108:111], v[16:19], v[48:51], a[108:111]
	v_mfma_f32_16x16x32_f16 a[100:103], v[12:15], v[48:51], a[100:103]
	s_waitcnt vmcnt(7)
	ds_write_b128 v21, v[98:101] offset:36864
	v_mfma_f32_16x16x32_f16 a[92:95], v[8:11], v[48:51], a[92:95]
	v_mfma_f32_16x16x32_f16 a[84:87], v[0:3], v[48:51], a[84:87]
	s_waitcnt vmcnt(6)
	ds_write_b128 v21, v[110:113] offset:41472
	s_waitcnt lgkmcnt(14)
	v_mfma_f32_16x16x32_f16 a[76:79], v[16:19], v[40:43], a[76:79]
	v_mfma_f32_16x16x32_f16 a[68:71], v[12:15], v[40:43], a[68:71]
	s_waitcnt vmcnt(5)
	ds_write_b128 v21, v[114:117] offset:46080
	v_mfma_f32_16x16x32_f16 a[60:63], v[8:11], v[40:43], a[60:63]
	v_mfma_f32_16x16x32_f16 a[52:55], v[0:3], v[40:43], a[52:55]
	s_waitcnt vmcnt(4)
	ds_write_b128 v21, v[126:129] offset:50688
	v_mfma_f32_16x16x32_f16 a[44:47], v[16:19], v[4:7], a[44:47]
	v_mfma_f32_16x16x32_f16 a[36:39], v[12:15], v[4:7], a[36:39]
	s_waitcnt vmcnt(3)
	ds_write_b128 v21, v[142:145] offset:55296
	v_mfma_f32_16x16x32_f16 a[28:31], v[8:11], v[4:7], a[28:31]
	v_mfma_f32_16x16x32_f16 a[20:23], v[0:3], v[4:7], a[20:23]
	s_waitcnt vmcnt(2)
	ds_write_b128 v21, v[154:157] offset:59904
	s_waitcnt lgkmcnt(14)
	v_mfma_f32_16x16x32_f16 a[12:15], v[16:19], v[32:35], a[12:15]
	v_mfma_f32_16x16x32_f16 a[8:11], v[12:15], v[32:35], a[8:11]
	s_waitcnt vmcnt(1)
	ds_write_b128 v21, v[162:165] offset:64512
	v_mfma_f32_16x16x32_f16 a[4:7], v[8:11], v[32:35], a[4:7]
	v_mfma_f32_16x16x32_f16 a[0:3], v[0:3], v[32:35], a[0:3]
	v_add_u32_e32 v0, v20, v137
	s_waitcnt vmcnt(0)
	ds_write_b128 v0, v[166:169]
	ds_read_b128 v[36:39], v56 offset:64
	ds_read_b128 v[28:31], v56 offset:2368
	ds_read_b128 v[24:27], v56 offset:4672
	ds_read_b128 v[20:23], v56 offset:6976
	ds_read_b128 v[16:19], v56 offset:9280
	ds_read_b128 v[12:15], v56 offset:11584
	ds_read_b128 v[8:11], v56 offset:13888
	ds_read_b128 v[0:3], v56 offset:16192
	ds_read_b128 v[56:59], v92 offset:36928
	ds_read_b128 v[60:63], v92 offset:39232
	ds_read_b128 v[64:67], v92 offset:41536
	ds_read_b128 v[68:71], v92 offset:43840
	s_cmpk_gt_u32 s14, 0x55
	s_cbranch_scc1 .Lgw8_nl
; #define MMA_BLK(afx, bfx, nh_) _Pragma("unroll") for (int mi = 0; mi < 8; ++mi) _Pragma("unroll") for (int ni = 0; ni < 4; ++ni) mfma16_acc(acc[mi][(nh_) * 4 + ni], bfx[ni], afx[mi])
; template <class Epi>
; __device__ __forceinline__ void gemm_run(const GemmArgs g, Epi epi, char* smem) {
;     ...
;       MMA_BLK(afA, bfB, 1);
;       __builtin_amdgcn_sched_barrier(0);
;       if (kt + 2 < nk) {
;         const int ko = (kt + 2) * 64;
; #pragma unroll
;         for (int i = 0; i < 8; ++i) { ra[i] = __builtin_amdgcn_raw_buffer_load_b128(Ars, aoff, i * astep + ko * 2, 0); rb[i] = __builtin_amdgcn_raw_buffer_load_b128(Brs, boff, i * bstep + ko * 2, 0); }
;       }
	s_waitcnt lgkmcnt(14)
	v_mfma_f32_16x16x32_f16 a[240:243], v[170:173], v[76:79], a[240:243]
	s_waitcnt lgkmcnt(14)
	v_mfma_f32_16x16x32_f16 a[252:255], v[88:91], v[76:79], a[252:255]
	s_waitcnt lgkmcnt(14)
	v_mfma_f32_16x16x32_f16 a[248:251], v[84:87], v[76:79], a[248:251]
	s_add_i32 s88, s86, 0xffd98000
	s_waitcnt lgkmcnt(14)
	v_mfma_f32_16x16x32_f16 a[244:247], v[80:83], v[76:79], a[244:247]
	s_mov_b32 s14, s10
	v_mfma_f32_16x16x32_f16 a[236:239], v[170:173], v[72:75], a[236:239]
	s_mov_b32 s15, s11
	v_mfma_f32_16x16x32_f16 a[232:235], v[88:91], v[72:75], a[232:235]
	buffer_load_dwordx4 v[94:97], v130, s[8:11], s88 offen
	v_mfma_f32_16x16x32_f16 a[228:231], v[84:87], v[72:75], a[228:231]
	buffer_load_dwordx4 v[98:101], v130, s[12:15], s88 offen
	v_mfma_f32_16x16x32_f16 a[224:227], v[80:83], v[72:75], a[224:227]
	s_add_i32 s88, s86, 0xffdf0000
	v_mfma_f32_16x16x32_f16 a[204:207], v[170:173], v[52:55], a[204:207]
	buffer_load_dwordx4 v[102:105], v130, s[8:11], s88 offen
	v_mfma_f32_16x16x32_f16 a[192:195], v[88:91], v[52:55], a[192:195]
	buffer_load_dwordx4 v[110:113], v130, s[12:15], s88 offen
	v_mfma_f32_16x16x32_f16 a[184:187], v[84:87], v[52:55], a[184:187]
	s_add_i32 s88, s86, 0xffe48000
	v_mfma_f32_16x16x32_f16 a[176:179], v[80:83], v[52:55], a[176:179]
	buffer_load_dwordx4 v[106:109], v130, s[8:11], s88 offen
	v_mfma_f32_16x16x32_f16 a[168:171], v[170:173], v[44:47], a[168:171]
	buffer_load_dwordx4 v[114:117], v130, s[12:15], s88 offen
	v_mfma_f32_16x16x32_f16 a[160:163], v[88:91], v[44:47], a[160:163]
	s_add_i32 s88, s86, 0xffea0000
	v_mfma_f32_16x16x32_f16 a[152:155], v[84:87], v[44:47], a[152:155]
	buffer_load_dwordx4 v[118:121], v130, s[8:11], s88 offen
	v_mfma_f32_16x16x32_f16 a[144:147], v[80:83], v[44:47], a[144:147]
	buffer_load_dwordx4 v[126:129], v130, s[12:15], s88 offen
	v_mfma_f32_16x16x32_f16 a[136:139], v[170:173], v[48:51], a[136:139]
	s_add_i32 s88, s86, 0xffef8000
	v_mfma_f32_16x16x32_f16 a[128:131], v[88:91], v[48:51], a[128:131]
	buffer_load_dwordx4 v[122:125], v130, s[8:11], s88 offen
	v_mfma_f32_16x16x32_f16 a[120:123], v[84:87], v[48:51], a[120:123]
	buffer_load_dwordx4 v[142:145], v130, s[12:15], s88 offen
	v_mfma_f32_16x16x32_f16 a[112:115], v[80:83], v[48:51], a[112:115]
	s_add_i32 s88, s86, 0xfff50000
	v_mfma_f32_16x16x32_f16 a[104:107], v[170:173], v[40:43], a[104:107]
	buffer_load_dwordx4 v[146:149], v130, s[8:11], s88 offen
	v_mfma_f32_16x16x32_f16 a[96:99], v[88:91], v[40:43], a[96:99]
	buffer_load_dwordx4 v[154:157], v130, s[12:15], s88 offen
	v_mfma_f32_16x16x32_f16 a[88:91], v[84:87], v[40:43], a[88:91]
	s_add_i32 s88, s86, 0xfffa8000
	v_mfma_f32_16x16x32_f16 a[80:83], v[80:83], v[40:43], a[80:83]
	buffer_load_dwordx4 v[150:153], v130, s[8:11], s88 offen
	v_mfma_f32_16x16x32_f16 a[72:75], v[170:173], v[4:7], a[72:75]
	buffer_load_dwordx4 v[162:165], v130, s[12:15], s88 offen
	v_mfma_f32_16x16x32_f16 a[64:67], v[88:91], v[4:7], a[64:67]
	buffer_load_dwordx4 v[158:161], v130, s[8:11], s86 offen
	v_mfma_f32_16x16x32_f16 a[56:59], v[84:87], v[4:7], a[56:59]
	buffer_load_dwordx4 v[166:169], v130, s[12:15], s86 offen
	v_mfma_f32_16x16x32_f16 a[48:51], v[80:83], v[4:7], a[48:51]
	v_mfma_f32_16x16x32_f16 a[40:43], v[170:173], v[32:35], a[40:43]
	v_mfma_f32_16x16x32_f16 a[32:35], v[88:91], v[32:35], a[32:35]
	v_mfma_f32_16x16x32_f16 a[24:27], v[84:87], v[32:35], a[24:27]
	v_mfma_f32_16x16x32_f16 a[16:19], v[80:83], v[32:35], a[16:19]
	s_branch .LBB0_1058
.Lgw8_nl:
	s_waitcnt lgkmcnt(14)
	v_mfma_f32_16x16x32_f16 a[240:243], v[170:173], v[76:79], a[240:243]
	s_waitcnt lgkmcnt(14)
	v_mfma_f32_16x16x32_f16 a[252:255], v[88:91], v[76:79], a[252:255]
	s_waitcnt lgkmcnt(14)
	v_mfma_f32_16x16x32_f16 a[248:251], v[84:87], v[76:79], a[248:251]
	s_waitcnt lgkmcnt(14)
	v_mfma_f32_16x16x32_f16 a[244:247], v[80:83], v[76:79], a[244:247]
	v_mfma_f32_16x16x32_f16 a[236:239], v[170:173], v[72:75], a[236:239]
	v_mfma_f32_16x16x32_f16 a[232:235], v[88:91], v[72:75], a[232:235]
	v_mfma_f32_16x16x32_f16 a[228:231], v[84:87], v[72:75], a[228:231]
	v_mfma_f32_16x16x32_f16 a[224:227], v[80:83], v[72:75], a[224:227]
	v_mfma_f32_16x16x32_f16 a[204:207], v[170:173], v[52:55], a[204:207]
	v_mfma_f32_16x16x32_f16 a[192:195], v[88:91], v[52:55], a[192:195]
	v_mfma_f32_16x16x32_f16 a[184:187], v[84:87], v[52:55], a[184:187]
	v_mfma_f32_16x16x32_f16 a[176:179], v[80:83], v[52:55], a[176:179]
	v_mfma_f32_16x16x32_f16 a[168:171], v[170:173], v[44:47], a[168:171]
	v_mfma_f32_16x16x32_f16 a[160:163], v[88:91], v[44:47], a[160:163]
	v_mfma_f32_16x16x32_f16 a[152:155], v[84:87], v[44:47], a[152:155]
	v_mfma_f32_16x16x32_f16 a[144:147], v[80:83], v[44:47], a[144:147]
	v_mfma_f32_16x16x32_f16 a[136:139], v[170:173], v[48:51], a[136:139]
	v_mfma_f32_16x16x32_f16 a[128:131], v[88:91], v[48:51], a[128:131]
	v_mfma_f32_16x16x32_f16 a[120:123], v[84:87], v[48:51], a[120:123]
	v_mfma_f32_16x16x32_f16 a[112:115], v[80:83], v[48:51], a[112:115]
	v_mfma_f32_16x16x32_f16 a[104:107], v[170:173], v[40:43], a[104:107]
	v_mfma_f32_16x16x32_f16 a[96:99], v[88:91], v[40:43], a[96:99]
	v_mfma_f32_16x16x32_f16 a[88:91], v[84:87], v[40:43], a[88:91]
	v_mfma_f32_16x16x32_f16 a[80:83], v[80:83], v[40:43], a[80:83]
	v_mfma_f32_16x16x32_f16 a[72:75], v[170:173], v[4:7], a[72:75]
	v_mfma_f32_16x16x32_f16 a[64:67], v[88:91], v[4:7], a[64:67]
	v_mfma_f32_16x16x32_f16 a[56:59], v[84:87], v[4:7], a[56:59]
	v_mfma_f32_16x16x32_f16 a[48:51], v[80:83], v[4:7], a[48:51]
	v_mfma_f32_16x16x32_f16 a[40:43], v[170:173], v[32:35], a[40:43]
	v_mfma_f32_16x16x32_f16 a[32:35], v[88:91], v[32:35], a[32:35]
	v_mfma_f32_16x16x32_f16 a[24:27], v[84:87], v[32:35], a[24:27]
	v_mfma_f32_16x16x32_f16 a[16:19], v[80:83], v[32:35], a[16:19]
	s_branch .LBB0_1058

; #define LD_AF(dst, ks_) _Pragma("unroll") for (int i = 0; i < 8; ++i) dst[i] = *(const h8*)(sA + i * 16 * G_LD + (ks_) * 32)
; #define LD_BF(dst, ks_, nh_) _Pragma("unroll") for (int i = 0; i < 4; ++i) dst[i] = *(const h8*)(sB + ((nh_) * 4 + i) * 16 * G_LD + (ks_) * 32)
; #define MMA_BLK(afx, bfx, nh_) _Pragma("unroll") for (int mi = 0; mi < 8; ++mi) _Pragma("unroll") for (int ni = 0; ni < 4; ++ni) mfma16_acc(acc[mi][(nh_) * 4 + ni], bfx[ni], afx[mi])
; template <class Epi>
; __device__ __forceinline__ void gemm_run(const GemmArgs g, Epi epi, char* smem) {
;     ...
;     for (int kt = 0; kt < nk; ++kt) {
;       const hf* sA = sbase + (kt & 1) * G_STAGE + (wm * 128 + fr) * G_LD + fqs;
;       const hf* sB = sbase + (kt & 1) * G_STAGE + (256 + wn * 128 + fr) * G_LD + fqs;
;       hf* st = sbase + ((kt + 1) & 1) * G_STAGE;
;       h8 afA[8], afB[8], bfA[4], bfB[4];
;     ...
;       LD_AF(afA, 0); LD_BF(bfA, 0, 0);
;       if (kt + 1 < nk) {
; #pragma unroll
;         for (int i = 0; i < 8; ++i) *(u4*)(st + (lr + 32 * i) * G_LD + lcw) = ra[i];
;       }
;       __builtin_amdgcn_sched_barrier(0);
;       LD_BF(bfB, 0, 1);
;       MMA_BLK(afA, bfA, 0);
;       __builtin_amdgcn_sched_barrier(0);
;       if (kt + 1 < nk) {
; #pragma unroll
;         for (int i = 0; i < 8; ++i) *(u4*)(st + (256 + lr + 32 * i) * G_LD + lcw) = rb[i];
;       }
;       LD_AF(afB, 1); LD_BF(bfA, 1, 0);
;       MMA_BLK(afA, bfB, 1);
.LBB0_1066:
	s_bitcmp1_b32 s23, 0
	s_cselect_b32 s15, 0x12000, 0
	s_add_i32 s15, s15, 16
	v_add3_u32 v56, s15, v94, v105
	v_add3_u32 v106, s15, v96, v105
	ds_read_b128 v[4:7], v56 offset:13824
	ds_read_b128 v[16:19], v106 offset:36864
	ds_read_b128 v[12:15], v106 offset:39168
	ds_read_b128 v[8:11], v106 offset:41472
	ds_read_b128 v[0:3], v106 offset:43776
	ds_read_b128 v[76:79], v56
	ds_read_b128 v[72:75], v56 offset:2304
	ds_read_b128 v[52:55], v56 offset:4608
	ds_read_b128 v[44:47], v56 offset:6912
	ds_read_b128 v[48:51], v56 offset:9216
	ds_read_b128 v[40:43], v56 offset:11520
	ds_read_b128 v[32:35], v56 offset:16128
	s_mov_b32 s14, s23
	s_add_i32 s23, s23, 1
	s_bitcmp1_b32 s23, 0
	s_cselect_b32 s15, 0x12000, 0
	v_add_u32_e32 v20, s15, v93
	v_add_u32_e32 v21, v20, v98
	ds_read_b128 v[172:175], v106 offset:46080
	ds_read_b128 v[88:91], v106 offset:48384
	ds_read_b128 v[84:87], v106 offset:50688
	ds_read_b128 v[80:83], v106 offset:52992
	s_waitcnt lgkmcnt(10)
	v_mfma_f32_16x16x32_f16 a[116:119], v[16:19], v[76:79], a[116:119]
	v_mfma_f32_16x16x32_f16 a[108:111], v[12:15], v[76:79], a[108:111]
	s_waitcnt vmcnt(15)
	ds_write_b128 v21, v[108:111]
	v_mfma_f32_16x16x32_f16 a[100:103], v[8:11], v[76:79], a[100:103]
	v_mfma_f32_16x16x32_f16 a[160:163], v[0:3], v[76:79], a[160:163]
	s_waitcnt vmcnt(13)
	ds_write_b128 v21, v[116:119] offset:4608
	s_waitcnt lgkmcnt(11)
	v_mfma_f32_16x16x32_f16 a[152:155], v[16:19], v[72:75], a[152:155]
	v_mfma_f32_16x16x32_f16 a[148:151], v[12:15], v[72:75], a[148:151]
	s_waitcnt vmcnt(11)
	ds_write_b128 v21, v[120:123] offset:9216
	v_mfma_f32_16x16x32_f16 a[144:147], v[8:11], v[72:75], a[144:147]
	v_mfma_f32_16x16x32_f16 a[136:139], v[0:3], v[72:75], a[136:139]
	s_waitcnt vmcnt(9)
	ds_write_b128 v21, v[132:135] offset:13824
	s_waitcnt lgkmcnt(12)
	v_mfma_f32_16x16x32_f16 a[120:123], v[16:19], v[52:55], a[120:123]
	v_mfma_f32_16x16x32_f16 a[112:115], v[12:15], v[52:55], a[112:115]
	s_waitcnt vmcnt(7)
	ds_write_b128 v21, v[136:139] offset:18432
	v_mfma_f32_16x16x32_f16 a[104:107], v[8:11], v[52:55], a[104:107]
	v_mfma_f32_16x16x32_f16 a[92:95], v[0:3], v[52:55], a[92:95]
	s_waitcnt vmcnt(5)
	ds_write_b128 v21, v[148:151] offset:23040
	s_waitcnt lgkmcnt(13)
	v_mfma_f32_16x16x32_f16 a[80:83], v[16:19], v[44:47], a[80:83]
	v_mfma_f32_16x16x32_f16 a[76:79], v[12:15], v[44:47], a[76:79]
	s_waitcnt vmcnt(3)
	ds_write_b128 v21, v[152:155] offset:27648
	v_mfma_f32_16x16x32_f16 a[72:75], v[8:11], v[44:47], a[72:75]
	v_mfma_f32_16x16x32_f16 a[68:71], v[0:3], v[44:47], a[68:71]
	s_waitcnt vmcnt(1)
	ds_write_b128 v21, v[160:163] offset:32256
	s_waitcnt lgkmcnt(14)
	v_mfma_f32_16x16x32_f16 a[64:67], v[16:19], v[48:51], a[64:67]
	v_mfma_f32_16x16x32_f16 a[60:63], v[12:15], v[48:51], a[60:63]
	s_waitcnt vmcnt(7)
	ds_write_b128 v21, v[112:115] offset:36864
	v_mfma_f32_16x16x32_f16 a[56:59], v[8:11], v[48:51], a[56:59]
	v_mfma_f32_16x16x32_f16 a[52:55], v[0:3], v[48:51], a[52:55]
	s_waitcnt vmcnt(6)
	ds_write_b128 v21, v[124:127] offset:41472
	s_waitcnt lgkmcnt(14)
	v_mfma_f32_16x16x32_f16 a[44:47], v[16:19], v[40:43], a[44:47]
	v_mfma_f32_16x16x32_f16 a[40:43], v[12:15], v[40:43], a[40:43]
	s_waitcnt vmcnt(5)
	ds_write_b128 v21, v[128:131] offset:46080
	v_mfma_f32_16x16x32_f16 a[36:39], v[8:11], v[40:43], a[36:39]
	v_mfma_f32_16x16x32_f16 a[32:35], v[0:3], v[40:43], a[32:35]
	s_waitcnt vmcnt(4)
	ds_write_b128 v21, v[140:143] offset:50688
	v_mfma_f32_16x16x32_f16 a[28:31], v[16:19], v[4:7], a[28:31]
	v_mfma_f32_16x16x32_f16 a[24:27], v[12:15], v[4:7], a[24:27]
	s_waitcnt vmcnt(3)
	ds_write_b128 v21, v[144:147] offset:55296
	v_mfma_f32_16x16x32_f16 a[20:23], v[8:11], v[4:7], a[20:23]
	v_mfma_f32_16x16x32_f16 a[16:19], v[0:3], v[4:7], a[16:19]
	s_waitcnt vmcnt(2)
	ds_write_b128 v21, v[156:159] offset:59904
	s_waitcnt lgkmcnt(14)
	v_mfma_f32_16x16x32_f16 a[12:15], v[16:19], v[32:35], a[12:15]
	v_mfma_f32_16x16x32_f16 a[8:11], v[12:15], v[32:35], a[8:11]
	s_waitcnt vmcnt(1)
	ds_write_b128 v21, v[164:167] offset:64512
	v_mfma_f32_16x16x32_f16 a[4:7], v[8:11], v[32:35], a[4:7]
	v_mfma_f32_16x16x32_f16 a[0:3], v[0:3], v[32:35], a[0:3]
	v_add_u32_e32 v0, v20, v99
	s_waitcnt vmcnt(0)
	ds_write_b128 v0, v[168:171]
	ds_read_b128 v[36:39], v56 offset:64
	ds_read_b128 v[28:31], v56 offset:2368
	ds_read_b128 v[24:27], v56 offset:4672
	ds_read_b128 v[20:23], v56 offset:6976
	ds_read_b128 v[16:19], v56 offset:9280
	ds_read_b128 v[12:15], v56 offset:11584
	ds_read_b128 v[8:11], v56 offset:13888
	ds_read_b128 v[0:3], v56 offset:16192
	ds_read_b128 v[56:59], v106 offset:36928
	ds_read_b128 v[60:63], v106 offset:39232
	ds_read_b128 v[64:67], v106 offset:41536
	ds_read_b128 v[68:71], v106 offset:43840
	s_cmp_gt_u32 s14, 29
	s_cbranch_scc1 .Lgw9_nl
; #define MMA_BLK(afx, bfx, nh_) _Pragma("unroll") for (int mi = 0; mi < 8; ++mi) _Pragma("unroll") for (int ni = 0; ni < 4; ++ni) mfma16_acc(acc[mi][(nh_) * 4 + ni], bfx[ni], afx[mi])
; template <class Epi>
; __device__ __forceinline__ void gemm_run(const GemmArgs g, Epi epi, char* smem) {
;     ...
;       MMA_BLK(afA, bfB, 1);
;       __builtin_amdgcn_sched_barrier(0);
;       if (kt + 2 < nk) {
;         const int ko = (kt + 2) * 64;
; #pragma unroll
;         for (int i = 0; i < 8; ++i) { ra[i] = __builtin_amdgcn_raw_buffer_load_b128(Ars, aoff, i * astep + ko * 2, 0); rb[i] = __builtin_amdgcn_raw_buffer_load_b128(Brs, boff, i * bstep + ko * 2, 0); }
;       }
	s_waitcnt lgkmcnt(14)
	v_mfma_f32_16x16x32_f16 a[252:255], v[172:175], v[76:79], a[252:255]
	s_waitcnt lgkmcnt(14)
	v_mfma_f32_16x16x32_f16 a[248:251], v[88:91], v[76:79], a[248:251]
	s_waitcnt lgkmcnt(14)
	v_mfma_f32_16x16x32_f16 a[244:247], v[84:87], v[76:79], a[244:247]
	s_add_i32 s89, s21, 0xfff20000
	s_waitcnt lgkmcnt(14)
	v_mfma_f32_16x16x32_f16 a[240:243], v[80:83], v[76:79], a[240:243]
	s_mov_b32 s14, s10
	v_mfma_f32_16x16x32_f16 a[236:239], v[172:175], v[72:75], a[236:239]
	s_mov_b32 s15, s11
	v_mfma_f32_16x16x32_f16 a[232:235], v[88:91], v[72:75], a[232:235]
	buffer_load_dwordx4 v[108:111], v92, s[8:11], s89 offen
	v_mfma_f32_16x16x32_f16 a[228:231], v[84:87], v[72:75], a[228:231]
	buffer_load_dwordx4 v[112:115], v92, s[12:15], s89 offen
	v_mfma_f32_16x16x32_f16 a[224:227], v[80:83], v[72:75], a[224:227]
	s_add_i32 s89, s21, 0xfff40000
	v_mfma_f32_16x16x32_f16 a[220:223], v[172:175], v[52:55], a[220:223]
	buffer_load_dwordx4 v[116:119], v92, s[8:11], s89 offen
	v_mfma_f32_16x16x32_f16 a[216:219], v[88:91], v[52:55], a[216:219]
	buffer_load_dwordx4 v[124:127], v92, s[12:15], s89 offen
	v_mfma_f32_16x16x32_f16 a[212:215], v[84:87], v[52:55], a[212:215]
	s_add_i32 s89, s21, 0xfff60000
	v_mfma_f32_16x16x32_f16 a[208:211], v[80:83], v[52:55], a[208:211]
	buffer_load_dwordx4 v[120:123], v92, s[8:11], s89 offen
	v_mfma_f32_16x16x32_f16 a[204:207], v[172:175], v[44:47], a[204:207]
	buffer_load_dwordx4 v[128:131], v92, s[12:15], s89 offen
	v_mfma_f32_16x16x32_f16 a[200:203], v[88:91], v[44:47], a[200:203]
	s_add_i32 s89, s21, 0xfff80000
	v_mfma_f32_16x16x32_f16 a[196:199], v[84:87], v[44:47], a[196:199]
	buffer_load_dwordx4 v[132:135], v92, s[8:11], s89 offen
	v_mfma_f32_16x16x32_f16 a[192:195], v[80:83], v[44:47], a[192:195]
	buffer_load_dwordx4 v[140:143], v92, s[12:15], s89 offen
	v_mfma_f32_16x16x32_f16 a[188:191], v[172:175], v[48:51], a[188:191]
	s_add_i32 s89, s21, 0xfffa0000
	v_mfma_f32_16x16x32_f16 a[184:187], v[88:91], v[48:51], a[184:187]
	buffer_load_dwordx4 v[136:139], v92, s[8:11], s89 offen
	v_mfma_f32_16x16x32_f16 a[180:183], v[84:87], v[48:51], a[180:183]
	buffer_load_dwordx4 v[144:147], v92, s[12:15], s89 offen
	v_mfma_f32_16x16x32_f16 a[176:179], v[80:83], v[48:51], a[176:179]
	s_add_i32 s89, s21, 0xfffc0000
	v_mfma_f32_16x16x32_f16 a[172:175], v[172:175], v[40:43], a[172:175]
	buffer_load_dwordx4 v[148:151], v92, s[8:11], s89 offen
	v_mfma_f32_16x16x32_f16 a[168:171], v[88:91], v[40:43], a[168:171]
	buffer_load_dwordx4 v[156:159], v92, s[12:15], s89 offen
	v_mfma_f32_16x16x32_f16 a[164:167], v[84:87], v[40:43], a[164:167]
	s_add_i32 s89, s21, 0xfffe0000
	v_mfma_f32_16x16x32_f16 a[156:159], v[80:83], v[40:43], a[156:159]
	buffer_load_dwordx4 v[152:155], v92, s[8:11], s89 offen
	v_mfma_f32_16x16x32_f16 a[140:143], v[172:175], v[4:7], a[140:143]
	buffer_load_dwordx4 v[164:167], v92, s[12:15], s89 offen
	v_mfma_f32_16x16x32_f16 a[132:135], v[88:91], v[4:7], a[132:135]
	buffer_load_dwordx4 v[160:163], v92, s[8:11], s21 offen
	v_mfma_f32_16x16x32_f16 a[128:131], v[84:87], v[4:7], a[128:131]
	buffer_load_dwordx4 v[168:171], v92, s[12:15], s21 offen
	v_mfma_f32_16x16x32_f16 a[124:127], v[80:83], v[4:7], a[124:127]
	v_mfma_f32_16x16x32_f16 a[96:99], v[172:175], v[32:35], a[96:99]
	v_mfma_f32_16x16x32_f16 a[88:91], v[88:91], v[32:35], a[88:91]
	v_mfma_f32_16x16x32_f16 a[84:87], v[84:87], v[32:35], a[84:87]
	v_mfma_f32_16x16x32_f16 a[48:51], v[80:83], v[32:35], a[48:51]
	s_branch .LBB0_1065

; #define LD_AF(dst, ks_) _Pragma("unroll") for (int i = 0; i < 8; ++i) dst[i] = *(const h8*)(sA + i * 16 * G_LD + (ks_) * 32)
; #define LD_BF(dst, ks_, nh_) _Pragma("unroll") for (int i = 0; i < 4; ++i) dst[i] = *(const h8*)(sB + ((nh_) * 4 + i) * 16 * G_LD + (ks_) * 32)
; #define MMA_BLK(afx, bfx, nh_) _Pragma("unroll") for (int mi = 0; mi < 8; ++mi) _Pragma("unroll") for (int ni = 0; ni < 4; ++ni) mfma16_acc(acc[mi][(nh_) * 4 + ni], bfx[ni], afx[mi])
; template <class Epi>
; __device__ __forceinline__ void gemm_run(const GemmArgs g, Epi epi, char* smem) {
;     ...
;     for (int kt = 0; kt < nk; ++kt) {
;       const hf* sA = sbase + (kt & 1) * G_STAGE + (wm * 128 + fr) * G_LD + fqs;
;       const hf* sB = sbase + (kt & 1) * G_STAGE + (256 + wn * 128 + fr) * G_LD + fqs;
;       hf* st = sbase + ((kt + 1) & 1) * G_STAGE;
;       h8 afA[8], afB[8], bfA[4], bfB[4];
;     ...
;       LD_AF(afA, 0); LD_BF(bfA, 0, 0);
;       if (kt + 1 < nk) {
; #pragma unroll
;         for (int i = 0; i < 8; ++i) *(u4*)(st + (lr + 32 * i) * G_LD + lcw) = ra[i];
;       }
;       __builtin_amdgcn_sched_barrier(0);
;       LD_BF(bfB, 0, 1);
;       MMA_BLK(afA, bfA, 0);
;       __builtin_amdgcn_sched_barrier(0);
;       if (kt + 1 < nk) {
; #pragma unroll
;         for (int i = 0; i < 8; ++i) *(u4*)(st + (256 + lr + 32 * i) * G_LD + lcw) = rb[i];
;       }
;       LD_AF(afB, 1); LD_BF(bfA, 1, 0);
;       MMA_BLK(afA, bfB, 1);
.LBB0_1117:
	s_bitcmp1_b32 s85, 0
	s_cselect_b32 s15, 0x12000, 0
	s_add_i32 s15, s15, 16
	v_add3_u32 v56, s15, v131, v139
	v_add3_u32 v92, s15, v132, v139
	ds_read_b128 v[4:7], v56 offset:13824
	ds_read_b128 v[16:19], v92 offset:36864
	ds_read_b128 v[12:15], v92 offset:39168
	ds_read_b128 v[8:11], v92 offset:41472
	ds_read_b128 v[0:3], v92 offset:43776
	ds_read_b128 v[76:79], v56
	ds_read_b128 v[72:75], v56 offset:2304
	ds_read_b128 v[52:55], v56 offset:4608
	ds_read_b128 v[44:47], v56 offset:6912
	ds_read_b128 v[48:51], v56 offset:9216
	ds_read_b128 v[40:43], v56 offset:11520
	ds_read_b128 v[32:35], v56 offset:16128
	s_mov_b32 s14, s85
	s_add_i32 s85, s85, 1
	s_bitcmp1_b32 s85, 0
	s_cselect_b32 s15, 0x12000, 0
	v_add_u32_e32 v20, s15, v129
	v_add_u32_e32 v21, v20, v134
	ds_read_b128 v[172:175], v92 offset:46080
	ds_read_b128 v[88:91], v92 offset:48384
	ds_read_b128 v[84:87], v92 offset:50688
	ds_read_b128 v[80:83], v92 offset:52992
	s_waitcnt lgkmcnt(10)
	v_mfma_f32_16x16x32_f16 a[204:207], v[16:19], v[76:79], a[204:207]
	v_mfma_f32_16x16x32_f16 a[200:203], v[12:15], v[76:79], a[200:203]
	s_waitcnt vmcnt(15)
	ds_write_b128 v21, v[94:97]
	v_mfma_f32_16x16x32_f16 a[196:199], v[8:11], v[76:79], a[196:199]
	v_mfma_f32_16x16x32_f16 a[188:191], v[0:3], v[76:79], a[188:191]
	s_waitcnt vmcnt(13)
	ds_write_b128 v21, v[102:105] offset:4608
	s_waitcnt lgkmcnt(11)
	v_mfma_f32_16x16x32_f16 a[192:195], v[16:19], v[72:75], a[192:195]
	v_mfma_f32_16x16x32_f16 a[184:187], v[12:15], v[72:75], a[184:187]
	s_waitcnt vmcnt(11)
	ds_write_b128 v21, v[106:109] offset:9216
	v_mfma_f32_16x16x32_f16 a[180:183], v[8:11], v[72:75], a[180:183]
	v_mfma_f32_16x16x32_f16 a[176:179], v[0:3], v[72:75], a[176:179]
	s_waitcnt vmcnt(9)
	ds_write_b128 v21, v[118:121] offset:13824
	s_waitcnt lgkmcnt(12)
	v_mfma_f32_16x16x32_f16 a[156:159], v[16:19], v[52:55], a[156:159]
	v_mfma_f32_16x16x32_f16 a[152:155], v[12:15], v[52:55], a[152:155]
	s_waitcnt vmcnt(7)
	ds_write_b128 v21, v[122:125] offset:18432
	v_mfma_f32_16x16x32_f16 a[148:151], v[8:11], v[52:55], a[148:151]
	v_mfma_f32_16x16x32_f16 a[144:147], v[0:3], v[52:55], a[144:147]
	s_waitcnt vmcnt(5)
	ds_write_b128 v21, v[148:151] offset:23040
	s_waitcnt lgkmcnt(13)
	v_mfma_f32_16x16x32_f16 a[124:127], v[16:19], v[44:47], a[124:127]
	v_mfma_f32_16x16x32_f16 a[120:123], v[12:15], v[44:47], a[120:123]
	s_waitcnt vmcnt(3)
	ds_write_b128 v21, v[152:155] offset:27648
	v_mfma_f32_16x16x32_f16 a[116:119], v[8:11], v[44:47], a[116:119]
	v_mfma_f32_16x16x32_f16 a[112:115], v[0:3], v[44:47], a[112:115]
	s_waitcnt vmcnt(1)
	ds_write_b128 v21, v[160:163] offset:32256
	s_waitcnt lgkmcnt(14)
	v_mfma_f32_16x16x32_f16 a[92:95], v[16:19], v[48:51], a[92:95]
	v_mfma_f32_16x16x32_f16 a[88:91], v[12:15], v[48:51], a[88:91]
	s_waitcnt vmcnt(7)
	ds_write_b128 v21, v[98:101] offset:36864
	v_mfma_f32_16x16x32_f16 a[84:87], v[8:11], v[48:51], a[84:87]
	v_mfma_f32_16x16x32_f16 a[80:83], v[0:3], v[48:51], a[80:83]
	s_waitcnt vmcnt(6)
	ds_write_b128 v21, v[110:113] offset:41472
	s_waitcnt lgkmcnt(14)
	v_mfma_f32_16x16x32_f16 a[60:63], v[16:19], v[40:43], a[60:63]
	v_mfma_f32_16x16x32_f16 a[56:59], v[12:15], v[40:43], a[56:59]
	s_waitcnt vmcnt(5)
	ds_write_b128 v21, v[114:117] offset:46080
	v_mfma_f32_16x16x32_f16 a[52:55], v[8:11], v[40:43], a[52:55]
	v_mfma_f32_16x16x32_f16 a[48:51], v[0:3], v[40:43], a[48:51]
	s_waitcnt vmcnt(4)
	ds_write_b128 v21, v[140:143] offset:50688
	v_mfma_f32_16x16x32_f16 a[32:35], v[16:19], v[4:7], a[32:35]
	v_mfma_f32_16x16x32_f16 a[28:31], v[12:15], v[4:7], a[28:31]
	s_waitcnt vmcnt(3)
	ds_write_b128 v21, v[144:147] offset:55296
	v_mfma_f32_16x16x32_f16 a[24:27], v[8:11], v[4:7], a[24:27]
	v_mfma_f32_16x16x32_f16 a[20:23], v[0:3], v[4:7], a[20:23]
	s_waitcnt vmcnt(2)
	ds_write_b128 v21, v[156:159] offset:59904
	s_waitcnt lgkmcnt(14)
	v_mfma_f32_16x16x32_f16 a[12:15], v[16:19], v[32:35], a[12:15]
	v_mfma_f32_16x16x32_f16 a[8:11], v[12:15], v[32:35], a[8:11]
	s_waitcnt vmcnt(1)
	ds_write_b128 v21, v[164:167] offset:64512
	v_mfma_f32_16x16x32_f16 a[4:7], v[8:11], v[32:35], a[4:7]
	v_mfma_f32_16x16x32_f16 a[0:3], v[0:3], v[32:35], a[0:3]
	v_add_u32_e32 v0, v20, v135
	s_waitcnt vmcnt(0)
	ds_write_b128 v0, v[168:171]
	ds_read_b128 v[36:39], v56 offset:64
	ds_read_b128 v[28:31], v56 offset:2368
	ds_read_b128 v[24:27], v56 offset:4672
	ds_read_b128 v[20:23], v56 offset:6976
	ds_read_b128 v[16:19], v56 offset:9280
	ds_read_b128 v[12:15], v56 offset:11584
	ds_read_b128 v[8:11], v56 offset:13888
	ds_read_b128 v[0:3], v56 offset:16192
	ds_read_b128 v[56:59], v92 offset:36928
	ds_read_b128 v[60:63], v92 offset:39232
	ds_read_b128 v[64:67], v92 offset:41536
	ds_read_b128 v[68:71], v92 offset:43840
	s_cmpk_gt_u32 s14, 0x55
	s_cbranch_scc1 .Lgw10_nl
; #define MMA_BLK(afx, bfx, nh_) _Pragma("unroll") for (int mi = 0; mi < 8; ++mi) _Pragma("unroll") for (int ni = 0; ni < 4; ++ni) mfma16_acc(acc[mi][(nh_) * 4 + ni], bfx[ni], afx[mi])
; template <class Epi>
; __device__ __forceinline__ void gemm_run(const GemmArgs g, Epi epi, char* smem) {
;     ...
;       MMA_BLK(afA, bfB, 1);
;       __builtin_amdgcn_sched_barrier(0);
;       if (kt + 2 < nk) {
;         const int ko = (kt + 2) * 64;
; #pragma unroll
;         for (int i = 0; i < 8; ++i) { ra[i] = __builtin_amdgcn_raw_buffer_load_b128(Ars, aoff, i * astep + ko * 2, 0); rb[i] = __builtin_amdgcn_raw_buffer_load_b128(Brs, boff, i * bstep + ko * 2, 0); }
;       }
	s_waitcnt lgkmcnt(14)
	v_mfma_f32_16x16x32_f16 a[240:243], v[172:175], v[76:79], a[240:243]
	s_waitcnt lgkmcnt(14)
	v_mfma_f32_16x16x32_f16 a[252:255], v[88:91], v[76:79], a[252:255]
	s_waitcnt lgkmcnt(14)
	v_mfma_f32_16x16x32_f16 a[248:251], v[84:87], v[76:79], a[248:251]
	s_add_i32 s86, s84, 0xffd98000
	s_waitcnt lgkmcnt(14)
	v_mfma_f32_16x16x32_f16 a[244:247], v[80:83], v[76:79], a[244:247]
	s_mov_b32 s14, s10
	v_mfma_f32_16x16x32_f16 a[236:239], v[172:175], v[72:75], a[236:239]
	s_mov_b32 s15, s11
	v_mfma_f32_16x16x32_f16 a[232:235], v[88:91], v[72:75], a[232:235]
	buffer_load_dwordx4 v[94:97], v128, s[8:11], s86 offen
	v_mfma_f32_16x16x32_f16 a[228:231], v[84:87], v[72:75], a[228:231]
	buffer_load_dwordx4 v[98:101], v128, s[12:15], s86 offen
	v_mfma_f32_16x16x32_f16 a[224:227], v[80:83], v[72:75], a[224:227]
	s_add_i32 s86, s84, 0xffdf0000
	v_mfma_f32_16x16x32_f16 a[220:223], v[172:175], v[52:55], a[220:223]
	buffer_load_dwordx4 v[102:105], v128, s[8:11], s86 offen
	v_mfma_f32_16x16x32_f16 a[216:219], v[88:91], v[52:55], a[216:219]
	buffer_load_dwordx4 v[110:113], v128, s[12:15], s86 offen
	v_mfma_f32_16x16x32_f16 a[212:215], v[84:87], v[52:55], a[212:215]
	s_add_i32 s86, s84, 0xffe48000
	v_mfma_f32_16x16x32_f16 a[208:211], v[80:83], v[52:55], a[208:211]
	buffer_load_dwordx4 v[106:109], v128, s[8:11], s86 offen
	v_mfma_f32_16x16x32_f16 a[172:175], v[172:175], v[44:47], a[172:175]
	buffer_load_dwordx4 v[114:117], v128, s[12:15], s86 offen
	v_mfma_f32_16x16x32_f16 a[168:171], v[88:91], v[44:47], a[168:171]
	s_add_i32 s86, s84, 0xffea0000
	v_mfma_f32_16x16x32_f16 a[164:167], v[84:87], v[44:47], a[164:167]
	buffer_load_dwordx4 v[118:121], v128, s[8:11], s86 offen
	v_mfma_f32_16x16x32_f16 a[160:163], v[80:83], v[44:47], a[160:163]
	buffer_load_dwordx4 v[140:143], v128, s[12:15], s86 offen
	v_mfma_f32_16x16x32_f16 a[140:143], v[172:175], v[48:51], a[140:143]
	s_add_i32 s86, s84, 0xffef8000
	v_mfma_f32_16x16x32_f16 a[136:139], v[88:91], v[48:51], a[136:139]
	buffer_load_dwordx4 v[122:125], v128, s[8:11], s86 offen
	v_mfma_f32_16x16x32_f16 a[132:135], v[84:87], v[48:51], a[132:135]
	buffer_load_dwordx4 v[144:147], v128, s[12:15], s86 offen
	v_mfma_f32_16x16x32_f16 a[128:131], v[80:83], v[48:51], a[128:131]
	s_add_i32 s86, s84, 0xfff50000
	v_mfma_f32_16x16x32_f16 a[108:111], v[172:175], v[40:43], a[108:111]
	buffer_load_dwordx4 v[148:151], v128, s[8:11], s86 offen
	v_mfma_f32_16x16x32_f16 a[104:107], v[88:91], v[40:43], a[104:107]
	buffer_load_dwordx4 v[156:159], v128, s[12:15], s86 offen
	v_mfma_f32_16x16x32_f16 a[100:103], v[84:87], v[40:43], a[100:103]
	s_add_i32 s86, s84, 0xfffa8000
	v_mfma_f32_16x16x32_f16 a[96:99], v[80:83], v[40:43], a[96:99]
	buffer_load_dwordx4 v[152:155], v128, s[8:11], s86 offen
	v_mfma_f32_16x16x32_f16 a[76:79], v[172:175], v[4:7], a[76:79]
	buffer_load_dwordx4 v[164:167], v128, s[12:15], s86 offen
	v_mfma_f32_16x16x32_f16 a[72:75], v[88:91], v[4:7], a[72:75]
	buffer_load_dwordx4 v[160:163], v128, s[8:11], s84 offen
	v_mfma_f32_16x16x32_f16 a[68:71], v[84:87], v[4:7], a[68:71]
	buffer_load_dwordx4 v[168:171], v128, s[12:15], s84 offen
	v_mfma_f32_16x16x32_f16 a[64:67], v[80:83], v[4:7], a[64:67]
	v_mfma_f32_16x16x32_f16 a[44:47], v[172:175], v[32:35], a[44:47]
	v_mfma_f32_16x16x32_f16 a[40:43], v[88:91], v[32:35], a[40:43]
	v_mfma_f32_16x16x32_f16 a[36:39], v[84:87], v[32:35], a[36:39]
	v_mfma_f32_16x16x32_f16 a[16:19], v[80:83], v[32:35], a[16:19]
	s_branch .LBB0_1116
.Lgw10_nl:
	s_waitcnt lgkmcnt(14)
	v_mfma_f32_16x16x32_f16 a[240:243], v[172:175], v[76:79], a[240:243]
	s_waitcnt lgkmcnt(14)
	v_mfma_f32_16x16x32_f16 a[252:255], v[88:91], v[76:79], a[252:255]
	s_waitcnt lgkmcnt(14)
	v_mfma_f32_16x16x32_f16 a[248:251], v[84:87], v[76:79], a[248:251]
	s_waitcnt lgkmcnt(14)
	v_mfma_f32_16x16x32_f16 a[244:247], v[80:83], v[76:79], a[244:247]
	v_mfma_f32_16x16x32_f16 a[236:239], v[172:175], v[72:75], a[236:239]
	v_mfma_f32_16x16x32_f16 a[232:235], v[88:91], v[72:75], a[232:235]
	v_mfma_f32_16x16x32_f16 a[228:231], v[84:87], v[72:75], a[228:231]
	v_mfma_f32_16x16x32_f16 a[224:227], v[80:83], v[72:75], a[224:227]
	v_mfma_f32_16x16x32_f16 a[220:223], v[172:175], v[52:55], a[220:223]
	v_mfma_f32_16x16x32_f16 a[216:219], v[88:91], v[52:55], a[216:219]
	v_mfma_f32_16x16x32_f16 a[212:215], v[84:87], v[52:55], a[212:215]
	v_mfma_f32_16x16x32_f16 a[208:211], v[80:83], v[52:55], a[208:211]
	v_mfma_f32_16x16x32_f16 a[172:175], v[172:175], v[44:47], a[172:175]
	v_mfma_f32_16x16x32_f16 a[168:171], v[88:91], v[44:47], a[168:171]
	v_mfma_f32_16x16x32_f16 a[164:167], v[84:87], v[44:47], a[164:167]
	v_mfma_f32_16x16x32_f16 a[160:163], v[80:83], v[44:47], a[160:163]
	v_mfma_f32_16x16x32_f16 a[140:143], v[172:175], v[48:51], a[140:143]
	v_mfma_f32_16x16x32_f16 a[136:139], v[88:91], v[48:51], a[136:139]
	v_mfma_f32_16x16x32_f16 a[132:135], v[84:87], v[48:51], a[132:135]
	v_mfma_f32_16x16x32_f16 a[128:131], v[80:83], v[48:51], a[128:131]
	v_mfma_f32_16x16x32_f16 a[108:111], v[172:175], v[40:43], a[108:111]
	v_mfma_f32_16x16x32_f16 a[104:107], v[88:91], v[40:43], a[104:107]
	v_mfma_f32_16x16x32_f16 a[100:103], v[84:87], v[40:43], a[100:103]
	v_mfma_f32_16x16x32_f16 a[96:99], v[80:83], v[40:43], a[96:99]
	v_mfma_f32_16x16x32_f16 a[76:79], v[172:175], v[4:7], a[76:79]
	v_mfma_f32_16x16x32_f16 a[72:75], v[88:91], v[4:7], a[72:75]
	v_mfma_f32_16x16x32_f16 a[68:71], v[84:87], v[4:7], a[68:71]
	v_mfma_f32_16x16x32_f16 a[64:67], v[80:83], v[4:7], a[64:67]
	v_mfma_f32_16x16x32_f16 a[44:47], v[172:175], v[32:35], a[44:47]
	v_mfma_f32_16x16x32_f16 a[40:43], v[88:91], v[32:35], a[40:43]
	v_mfma_f32_16x16x32_f16 a[36:39], v[84:87], v[32:35], a[36:39]
	v_mfma_f32_16x16x32_f16 a[16:19], v[80:83], v[32:35], a[16:19]
	s_branch .LBB0_1116

; #define LD_AF(dst, ks_) _Pragma("unroll") for (int i = 0; i < 8; ++i) dst[i] = *(const h8*)(sA + i * 16 * G_LD + (ks_) * 32)
; #define LD_BF(dst, ks_, nh_) _Pragma("unroll") for (int i = 0; i < 4; ++i) dst[i] = *(const h8*)(sB + ((nh_) * 4 + i) * 16 * G_LD + (ks_) * 32)
; #define MMA_BLK(afx, bfx, nh_) _Pragma("unroll") for (int mi = 0; mi < 8; ++mi) _Pragma("unroll") for (int ni = 0; ni < 4; ++ni) mfma16_acc(acc[mi][(nh_) * 4 + ni], bfx[ni], afx[mi])
; template <class Epi>
; __device__ __forceinline__ void gemm_run(const GemmArgs g, Epi epi, char* smem) {
;     ...
;     for (int kt = 0; kt < nk; ++kt) {
;       const hf* sA = sbase + (kt & 1) * G_STAGE + (wm * 128 + fr) * G_LD + fqs;
;       const hf* sB = sbase + (kt & 1) * G_STAGE + (256 + wn * 128 + fr) * G_LD + fqs;
;       hf* st = sbase + ((kt + 1) & 1) * G_STAGE;
;       h8 afA[8], afB[8], bfA[4], bfB[4];
;     ...
;       LD_AF(afA, 0); LD_BF(bfA, 0, 0);
;       if (kt + 1 < nk) {
; #pragma unroll
;         for (int i = 0; i < 8; ++i) *(u4*)(st + (lr + 32 * i) * G_LD + lcw) = ra[i];
;       }
;       __builtin_amdgcn_sched_barrier(0);
;       LD_BF(bfB, 0, 1);
;       MMA_BLK(afA, bfA, 0);
;       __builtin_amdgcn_sched_barrier(0);
;       if (kt + 1 < nk) {
; #pragma unroll
;         for (int i = 0; i < 8; ++i) *(u4*)(st + (256 + lr + 32 * i) * G_LD + lcw) = rb[i];
;       }
;       LD_AF(afB, 1); LD_BF(bfA, 1, 0);
;       MMA_BLK(afA, bfB, 1);
.LBB0_1201:
	s_bitcmp1_b32 s13, 0
	s_cselect_b32 s11, 0x12000, 0
	s_add_i32 s11, s11, 16
	v_add3_u32 v56, s11, v97, v105
	v_add3_u32 v92, s11, v98, v105
	ds_read_b128 v[4:7], v56 offset:13824
	ds_read_b128 v[16:19], v92 offset:36864
	ds_read_b128 v[12:15], v92 offset:39168
	ds_read_b128 v[8:11], v92 offset:41472
	ds_read_b128 v[0:3], v92 offset:43776
	ds_read_b128 v[76:79], v56
	ds_read_b128 v[72:75], v56 offset:2304
	ds_read_b128 v[52:55], v56 offset:4608
	ds_read_b128 v[44:47], v56 offset:6912
	ds_read_b128 v[48:51], v56 offset:9216
	ds_read_b128 v[40:43], v56 offset:11520
	ds_read_b128 v[32:35], v56 offset:16128
	s_mov_b32 s10, s13
	s_add_i32 s13, s13, 1
	s_bitcmp1_b32 s13, 0
	s_cselect_b32 s11, 0x12000, 0
	v_add_u32_e32 v20, s11, v95
	v_add_u32_e32 v21, v20, v100
	ds_read_b128 v[170:173], v92 offset:46080
	ds_read_b128 v[88:91], v92 offset:48384
	ds_read_b128 v[84:87], v92 offset:50688
	ds_read_b128 v[80:83], v92 offset:52992
	s_waitcnt lgkmcnt(10)
	v_mfma_f32_16x16x32_f16 a[252:255], v[16:19], v[76:79], a[252:255]
	v_mfma_f32_16x16x32_f16 a[244:247], v[12:15], v[76:79], a[244:247]
	s_waitcnt vmcnt(15)
	ds_write_b128 v21, v[106:109]
	v_mfma_f32_16x16x32_f16 a[236:239], v[8:11], v[76:79], a[236:239]
	v_mfma_f32_16x16x32_f16 a[228:231], v[0:3], v[76:79], a[228:231]
	s_waitcnt vmcnt(13)
	ds_write_b128 v21, v[114:117] offset:4608
	s_waitcnt lgkmcnt(11)
	v_mfma_f32_16x16x32_f16 a[220:223], v[16:19], v[72:75], a[220:223]
	v_mfma_f32_16x16x32_f16 a[212:215], v[12:15], v[72:75], a[212:215]
	s_waitcnt vmcnt(11)
	ds_write_b128 v21, v[122:125] offset:9216
	v_mfma_f32_16x16x32_f16 a[204:207], v[8:11], v[72:75], a[204:207]
	v_mfma_f32_16x16x32_f16 a[196:199], v[0:3], v[72:75], a[196:199]
	s_waitcnt vmcnt(9)
	ds_write_b128 v21, v[130:133] offset:13824
	s_waitcnt lgkmcnt(12)
	v_mfma_f32_16x16x32_f16 a[188:191], v[16:19], v[52:55], a[188:191]
	v_mfma_f32_16x16x32_f16 a[180:183], v[12:15], v[52:55], a[180:183]
	s_waitcnt vmcnt(7)
	ds_write_b128 v21, v[138:141] offset:18432
	v_mfma_f32_16x16x32_f16 a[172:175], v[8:11], v[52:55], a[172:175]
	v_mfma_f32_16x16x32_f16 a[164:167], v[0:3], v[52:55], a[164:167]
	s_waitcnt vmcnt(5)
	ds_write_b128 v21, v[146:149] offset:23040
	s_waitcnt lgkmcnt(13)
	v_mfma_f32_16x16x32_f16 a[156:159], v[16:19], v[44:47], a[156:159]
	v_mfma_f32_16x16x32_f16 a[148:151], v[12:15], v[44:47], a[148:151]
	s_waitcnt vmcnt(3)
	ds_write_b128 v21, v[154:157] offset:27648
	v_mfma_f32_16x16x32_f16 a[140:143], v[8:11], v[44:47], a[140:143]
	v_mfma_f32_16x16x32_f16 a[132:135], v[0:3], v[44:47], a[132:135]
	s_waitcnt vmcnt(1)
	ds_write_b128 v21, v[162:165] offset:32256
	s_waitcnt lgkmcnt(14)
	v_mfma_f32_16x16x32_f16 a[124:127], v[16:19], v[48:51], a[124:127]
	v_mfma_f32_16x16x32_f16 a[116:119], v[12:15], v[48:51], a[116:119]
	ds_write_b128 v21, v[110:113] offset:36864
	v_mfma_f32_16x16x32_f16 a[108:111], v[8:11], v[48:51], a[108:111]
	v_mfma_f32_16x16x32_f16 a[100:103], v[0:3], v[48:51], a[100:103]
	ds_write_b128 v21, v[118:121] offset:41472
	s_waitcnt lgkmcnt(14)
	v_mfma_f32_16x16x32_f16 a[92:95], v[16:19], v[40:43], a[92:95]
	v_mfma_f32_16x16x32_f16 a[84:87], v[12:15], v[40:43], a[84:87]
	ds_write_b128 v21, v[126:129] offset:46080
	v_mfma_f32_16x16x32_f16 a[76:79], v[8:11], v[40:43], a[76:79]
	v_mfma_f32_16x16x32_f16 a[68:71], v[0:3], v[40:43], a[68:71]
	ds_write_b128 v21, v[134:137] offset:50688
	v_mfma_f32_16x16x32_f16 a[60:63], v[16:19], v[4:7], a[60:63]
	v_mfma_f32_16x16x32_f16 a[52:55], v[12:15], v[4:7], a[52:55]
	ds_write_b128 v21, v[142:145] offset:55296
	v_mfma_f32_16x16x32_f16 a[44:47], v[8:11], v[4:7], a[44:47]
	v_mfma_f32_16x16x32_f16 a[36:39], v[0:3], v[4:7], a[36:39]
	ds_write_b128 v21, v[150:153] offset:59904
	s_waitcnt lgkmcnt(14)
	v_mfma_f32_16x16x32_f16 a[28:31], v[16:19], v[32:35], a[28:31]
	v_mfma_f32_16x16x32_f16 a[24:27], v[12:15], v[32:35], a[24:27]
	ds_write_b128 v21, v[158:161] offset:64512
	v_mfma_f32_16x16x32_f16 a[20:23], v[8:11], v[32:35], a[20:23]
	v_mfma_f32_16x16x32_f16 a[12:15], v[0:3], v[32:35], a[12:15]
	v_add_u32_e32 v0, v20, v101
	s_waitcnt vmcnt(0)
	ds_write_b128 v0, v[166:169]
	ds_read_b128 v[36:39], v56 offset:64
	ds_read_b128 v[28:31], v56 offset:2368
	ds_read_b128 v[24:27], v56 offset:4672
	ds_read_b128 v[20:23], v56 offset:6976
	ds_read_b128 v[16:19], v56 offset:9280
	ds_read_b128 v[12:15], v56 offset:11584
	ds_read_b128 v[8:11], v56 offset:13888
	ds_read_b128 v[0:3], v56 offset:16192
	ds_read_b128 v[56:59], v92 offset:36928
	ds_read_b128 v[60:63], v92 offset:39232
	ds_read_b128 v[64:67], v92 offset:41536
	ds_read_b128 v[68:71], v92 offset:43840
	s_cmp_gt_u32 s10, 29
	s_cbranch_scc1 .Lgw11_nl
; #define MMA_BLK(afx, bfx, nh_) _Pragma("unroll") for (int mi = 0; mi < 8; ++mi) _Pragma("unroll") for (int ni = 0; ni < 4; ++ni) mfma16_acc(acc[mi][(nh_) * 4 + ni], bfx[ni], afx[mi])
; template <class Epi>
; __device__ __forceinline__ void gemm_run(const GemmArgs g, Epi epi, char* smem) {
;     ...
;       MMA_BLK(afA, bfB, 1);
;       __builtin_amdgcn_sched_barrier(0);
;       if (kt + 2 < nk) {
;         const int ko = (kt + 2) * 64;
; #pragma unroll
;         for (int i = 0; i < 8; ++i) { ra[i] = __builtin_amdgcn_raw_buffer_load_b128(Ars, aoff, i * astep + ko * 2, 0); rb[i] = __builtin_amdgcn_raw_buffer_load_b128(Brs, boff, i * bstep + ko * 2, 0); }
;       }
	s_waitcnt lgkmcnt(14)
	v_mfma_f32_16x16x32_f16 a[248:251], v[170:173], v[76:79], a[248:251]
	s_waitcnt lgkmcnt(14)
	v_mfma_f32_16x16x32_f16 a[240:243], v[88:91], v[76:79], a[240:243]
	s_waitcnt lgkmcnt(14)
	v_mfma_f32_16x16x32_f16 a[232:235], v[84:87], v[76:79], a[232:235]
	s_add_i32 s15, s3, 0xfff20000
	s_waitcnt lgkmcnt(14)
	v_mfma_f32_16x16x32_f16 a[224:227], v[80:83], v[76:79], a[224:227]
	s_mov_b32 s10, s54
	v_mfma_f32_16x16x32_f16 a[216:219], v[170:173], v[72:75], a[216:219]
	s_mov_b32 s11, s55
	v_mfma_f32_16x16x32_f16 a[208:211], v[88:91], v[72:75], a[208:211]
	buffer_load_dwordx4 v[106:109], v94, s[52:55], s15 offen
	v_mfma_f32_16x16x32_f16 a[200:203], v[84:87], v[72:75], a[200:203]
	buffer_load_dwordx4 v[110:113], v94, s[8:11], s15 offen
	v_mfma_f32_16x16x32_f16 a[192:195], v[80:83], v[72:75], a[192:195]
	s_add_i32 s15, s3, 0xfff40000
	v_mfma_f32_16x16x32_f16 a[184:187], v[170:173], v[52:55], a[184:187]
	buffer_load_dwordx4 v[114:117], v94, s[52:55], s15 offen
	v_mfma_f32_16x16x32_f16 a[176:179], v[88:91], v[52:55], a[176:179]
	buffer_load_dwordx4 v[118:121], v94, s[8:11], s15 offen
	v_mfma_f32_16x16x32_f16 a[168:171], v[84:87], v[52:55], a[168:171]
	s_add_i32 s15, s3, 0xfff60000
	v_mfma_f32_16x16x32_f16 a[160:163], v[80:83], v[52:55], a[160:163]
	buffer_load_dwordx4 v[122:125], v94, s[52:55], s15 offen
	v_mfma_f32_16x16x32_f16 a[152:155], v[170:173], v[44:47], a[152:155]
	buffer_load_dwordx4 v[126:129], v94, s[8:11], s15 offen
	v_mfma_f32_16x16x32_f16 a[144:147], v[88:91], v[44:47], a[144:147]
	s_add_i32 s15, s3, 0xfff80000
	v_mfma_f32_16x16x32_f16 a[136:139], v[84:87], v[44:47], a[136:139]
	buffer_load_dwordx4 v[130:133], v94, s[52:55], s15 offen
	v_mfma_f32_16x16x32_f16 a[128:131], v[80:83], v[44:47], a[128:131]
	buffer_load_dwordx4 v[134:137], v94, s[8:11], s15 offen
	v_mfma_f32_16x16x32_f16 a[120:123], v[170:173], v[48:51], a[120:123]
	s_add_i32 s15, s3, 0xfffa0000
	v_mfma_f32_16x16x32_f16 a[112:115], v[88:91], v[48:51], a[112:115]
	buffer_load_dwordx4 v[138:141], v94, s[52:55], s15 offen
	v_mfma_f32_16x16x32_f16 a[104:107], v[84:87], v[48:51], a[104:107]
	buffer_load_dwordx4 v[142:145], v94, s[8:11], s15 offen
	v_mfma_f32_16x16x32_f16 a[96:99], v[80:83], v[48:51], a[96:99]
	s_add_i32 s15, s3, 0xfffc0000
	v_mfma_f32_16x16x32_f16 a[88:91], v[170:173], v[40:43], a[88:91]
	buffer_load_dwordx4 v[146:149], v94, s[52:55], s15 offen
	v_mfma_f32_16x16x32_f16 a[80:83], v[88:91], v[40:43], a[80:83]
	buffer_load_dwordx4 v[150:153], v94, s[8:11], s15 offen
	v_mfma_f32_16x16x32_f16 a[72:75], v[84:87], v[40:43], a[72:75]
	s_add_i32 s15, s3, 0xfffe0000
	v_mfma_f32_16x16x32_f16 a[64:67], v[80:83], v[40:43], a[64:67]
	buffer_load_dwordx4 v[154:157], v94, s[52:55], s15 offen
	v_mfma_f32_16x16x32_f16 a[56:59], v[170:173], v[4:7], a[56:59]
	buffer_load_dwordx4 v[158:161], v94, s[8:11], s15 offen
	v_mfma_f32_16x16x32_f16 a[48:51], v[88:91], v[4:7], a[48:51]
	buffer_load_dwordx4 v[162:165], v94, s[52:55], s3 offen
	v_mfma_f32_16x16x32_f16 a[40:43], v[84:87], v[4:7], a[40:43]
	buffer_load_dwordx4 v[166:169], v94, s[8:11], s3 offen
	v_mfma_f32_16x16x32_f16 a[32:35], v[80:83], v[4:7], a[32:35]
	v_mfma_f32_16x16x32_f16 a[16:19], v[170:173], v[32:35], a[16:19]
	v_mfma_f32_16x16x32_f16 a[8:11], v[88:91], v[32:35], a[8:11]
	v_mfma_f32_16x16x32_f16 a[4:7], v[84:87], v[32:35], a[4:7]
	v_mfma_f32_16x16x32_f16 a[0:3], v[80:83], v[32:35], a[0:3]
	s_branch .LBB0_1200
.Lgw11_nl:
	s_waitcnt lgkmcnt(14)
	v_mfma_f32_16x16x32_f16 a[248:251], v[170:173], v[76:79], a[248:251]
	s_waitcnt lgkmcnt(14)
	v_mfma_f32_16x16x32_f16 a[240:243], v[88:91], v[76:79], a[240:243]
	s_waitcnt lgkmcnt(14)
	v_mfma_f32_16x16x32_f16 a[232:235], v[84:87], v[76:79], a[232:235]
	s_waitcnt lgkmcnt(14)
	v_mfma_f32_16x16x32_f16 a[224:227], v[80:83], v[76:79], a[224:227]
	v_mfma_f32_16x16x32_f16 a[216:219], v[170:173], v[72:75], a[216:219]
	v_mfma_f32_16x16x32_f16 a[208:211], v[88:91], v[72:75], a[208:211]
	v_mfma_f32_16x16x32_f16 a[200:203], v[84:87], v[72:75], a[200:203]
	v_mfma_f32_16x16x32_f16 a[192:195], v[80:83], v[72:75], a[192:195]
	v_mfma_f32_16x16x32_f16 a[184:187], v[170:173], v[52:55], a[184:187]
	v_mfma_f32_16x16x32_f16 a[176:179], v[88:91], v[52:55], a[176:179]
	v_mfma_f32_16x16x32_f16 a[168:171], v[84:87], v[52:55], a[168:171]
	v_mfma_f32_16x16x32_f16 a[160:163], v[80:83], v[52:55], a[160:163]
	v_mfma_f32_16x16x32_f16 a[152:155], v[170:173], v[44:47], a[152:155]
	v_mfma_f32_16x16x32_f16 a[144:147], v[88:91], v[44:47], a[144:147]
	v_mfma_f32_16x16x32_f16 a[136:139], v[84:87], v[44:47], a[136:139]
	v_mfma_f32_16x16x32_f16 a[128:131], v[80:83], v[44:47], a[128:131]
	v_mfma_f32_16x16x32_f16 a[120:123], v[170:173], v[48:51], a[120:123]
	v_mfma_f32_16x16x32_f16 a[112:115], v[88:91], v[48:51], a[112:115]
	v_mfma_f32_16x16x32_f16 a[104:107], v[84:87], v[48:51], a[104:107]
	v_mfma_f32_16x16x32_f16 a[96:99], v[80:83], v[48:51], a[96:99]
	v_mfma_f32_16x16x32_f16 a[88:91], v[170:173], v[40:43], a[88:91]
	v_mfma_f32_16x16x32_f16 a[80:83], v[88:91], v[40:43], a[80:83]
	v_mfma_f32_16x16x32_f16 a[72:75], v[84:87], v[40:43], a[72:75]
	v_mfma_f32_16x16x32_f16 a[64:67], v[80:83], v[40:43], a[64:67]
	v_mfma_f32_16x16x32_f16 a[56:59], v[170:173], v[4:7], a[56:59]
	v_mfma_f32_16x16x32_f16 a[48:51], v[88:91], v[4:7], a[48:51]
	v_mfma_f32_16x16x32_f16 a[40:43], v[84:87], v[4:7], a[40:43]
	v_mfma_f32_16x16x32_f16 a[32:35], v[80:83], v[4:7], a[32:35]
	v_mfma_f32_16x16x32_f16 a[16:19], v[170:173], v[32:35], a[16:19]
	v_mfma_f32_16x16x32_f16 a[8:11], v[88:91], v[32:35], a[8:11]
	v_mfma_f32_16x16x32_f16 a[4:7], v[84:87], v[32:35], a[4:7]
	v_mfma_f32_16x16x32_f16 a[0:3], v[80:83], v[32:35], a[0:3]
	s_branch .LBB0_1200

; #define LD_AF(dst, ks_) _Pragma("unroll") for (int i = 0; i < 8; ++i) dst[i] = *(const h8*)(sA + i * 16 * G_LD + (ks_) * 32)
; #define LD_BF(dst, ks_, nh_) _Pragma("unroll") for (int i = 0; i < 4; ++i) dst[i] = *(const h8*)(sB + ((nh_) * 4 + i) * 16 * G_LD + (ks_) * 32)
; #define MMA_BLK(afx, bfx, nh_) _Pragma("unroll") for (int mi = 0; mi < 8; ++mi) _Pragma("unroll") for (int ni = 0; ni < 4; ++ni) mfma16_acc(acc[mi][(nh_) * 4 + ni], bfx[ni], afx[mi])
; template <class Epi>
; __device__ __forceinline__ void gemm_run(const GemmArgs g, Epi epi, char* smem) {
;     ...
;     for (int kt = 0; kt < nk; ++kt) {
;       const hf* sA = sbase + (kt & 1) * G_STAGE + (wm * 128 + fr) * G_LD + fqs;
;       const hf* sB = sbase + (kt & 1) * G_STAGE + (256 + wn * 128 + fr) * G_LD + fqs;
;       hf* st = sbase + ((kt + 1) & 1) * G_STAGE;
;       h8 afA[8], afB[8], bfA[4], bfB[4];
;     ...
;       LD_AF(afA, 0); LD_BF(bfA, 0, 0);
;       if (kt + 1 < nk) {
; #pragma unroll
;         for (int i = 0; i < 8; ++i) *(u4*)(st + (lr + 32 * i) * G_LD + lcw) = ra[i];
;       }
;       __builtin_amdgcn_sched_barrier(0);
;       LD_BF(bfB, 0, 1);
;       MMA_BLK(afA, bfA, 0);
;       __builtin_amdgcn_sched_barrier(0);
;       if (kt + 1 < nk) {
; #pragma unroll
;         for (int i = 0; i < 8; ++i) *(u4*)(st + (256 + lr + 32 * i) * G_LD + lcw) = rb[i];
;       }
;       LD_AF(afB, 1); LD_BF(bfA, 1, 0);
;       MMA_BLK(afA, bfB, 1);
.LBB0_1623:
	s_bitcmp1_b32 s21, 0
	s_cselect_b32 s15, 0x12000, 0
	s_add_i32 s15, s15, 16
	v_add3_u32 v104, s15, v96, v103
	v_add3_u32 v64, s15, v95, v103
	ds_read_b128 v[36:39], v104 offset:36864
	ds_read_b128 v[56:59], v64
	ds_read_b128 v[32:35], v104 offset:39168
	ds_read_b128 v[24:27], v104 offset:41472
	ds_read_b128 v[16:19], v104 offset:43776
	ds_read_b128 v[44:47], v64 offset:2304
	ds_read_b128 v[28:31], v64 offset:4608
	ds_read_b128 v[12:15], v64 offset:6912
	ds_read_b128 v[4:7], v64 offset:9216
	ds_read_b128 v[0:3], v64 offset:11520
	ds_read_b128 v[8:11], v64 offset:13824
	ds_read_b128 v[20:23], v64 offset:16128
	s_mov_b32 s14, s21
	s_add_i32 s21, s21, 1
	s_bitcmp1_b32 s21, 0
	s_cselect_b32 s77, 0x12000, 0
	v_add_u32_e32 v40, s77, v93
	v_add_u32_e32 v41, v40, v98
	ds_read_b128 v[170:173], v104 offset:46080
	ds_read_b128 v[88:91], v104 offset:48384
	ds_read_b128 v[84:87], v104 offset:50688
	ds_read_b128 v[80:83], v104 offset:52992
	s_waitcnt lgkmcnt(14)
	v_mfma_f32_16x16x32_f16 a[140:143], v[36:39], v[56:59], a[140:143]
	s_waitcnt lgkmcnt(13)
	v_mfma_f32_16x16x32_f16 a[136:139], v[32:35], v[56:59], a[136:139]
	s_waitcnt vmcnt(15)
	ds_write_b128 v41, v[106:109]
	s_waitcnt lgkmcnt(13)
	v_mfma_f32_16x16x32_f16 a[128:131], v[24:27], v[56:59], a[128:131]
	s_waitcnt lgkmcnt(12)
	v_mfma_f32_16x16x32_f16 a[120:123], v[16:19], v[56:59], a[120:123]
	s_waitcnt vmcnt(14)
	ds_write_b128 v41, v[110:113] offset:4608
	s_waitcnt lgkmcnt(12)
	v_mfma_f32_16x16x32_f16 a[156:159], v[36:39], v[44:47], a[156:159]
	v_mfma_f32_16x16x32_f16 a[152:155], v[32:35], v[44:47], a[152:155]
	s_waitcnt vmcnt(11)
	ds_write_b128 v41, v[118:121] offset:9216
	v_mfma_f32_16x16x32_f16 a[148:151], v[24:27], v[44:47], a[148:151]
	v_mfma_f32_16x16x32_f16 a[144:147], v[16:19], v[44:47], a[144:147]
	s_waitcnt vmcnt(10)
	ds_write_b128 v41, v[126:129] offset:13824
	s_waitcnt lgkmcnt(13)
	v_mfma_f32_16x16x32_f16 a[108:111], v[36:39], v[28:31], a[108:111]
	v_mfma_f32_16x16x32_f16 a[104:107], v[32:35], v[28:31], a[104:107]
	s_waitcnt vmcnt(7)
	ds_write_b128 v41, v[134:137] offset:18432
	v_mfma_f32_16x16x32_f16 a[100:103], v[24:27], v[28:31], a[100:103]
	v_mfma_f32_16x16x32_f16 a[96:99], v[16:19], v[28:31], a[96:99]
	s_waitcnt vmcnt(6)
	ds_write_b128 v41, v[142:145] offset:23040
	s_waitcnt lgkmcnt(14)
	v_mfma_f32_16x16x32_f16 a[76:79], v[36:39], v[12:15], a[76:79]
	v_mfma_f32_16x16x32_f16 a[72:75], v[32:35], v[12:15], a[72:75]
	s_waitcnt vmcnt(3)
	ds_write_b128 v41, v[146:149] offset:27648
	v_mfma_f32_16x16x32_f16 a[68:71], v[24:27], v[12:15], a[68:71]
	v_mfma_f32_16x16x32_f16 a[64:67], v[16:19], v[12:15], a[64:67]
	s_waitcnt vmcnt(2)
	ds_write_b128 v41, v[154:157] offset:32256
	s_waitcnt lgkmcnt(14)
	v_mfma_f32_16x16x32_f16 a[60:63], v[36:39], v[4:7], a[60:63]
	v_mfma_f32_16x16x32_f16 a[56:59], v[32:35], v[4:7], a[56:59]
	s_waitcnt vmcnt(7)
	ds_write_b128 v41, v[114:117] offset:36864
	v_mfma_f32_16x16x32_f16 a[52:55], v[24:27], v[4:7], a[52:55]
	v_mfma_f32_16x16x32_f16 a[48:51], v[16:19], v[4:7], a[48:51]
	s_waitcnt vmcnt(6)
	ds_write_b128 v41, v[122:125] offset:41472
	s_waitcnt lgkmcnt(14)
	v_mfma_f32_16x16x32_f16 a[44:47], v[36:39], v[0:3], a[44:47]
	v_mfma_f32_16x16x32_f16 a[40:43], v[32:35], v[0:3], a[40:43]
	s_waitcnt vmcnt(5)
	ds_write_b128 v41, v[130:133] offset:46080
	v_mfma_f32_16x16x32_f16 a[36:39], v[24:27], v[0:3], a[36:39]
	v_mfma_f32_16x16x32_f16 a[32:35], v[16:19], v[0:3], a[32:35]
	s_waitcnt vmcnt(4)
	ds_write_b128 v41, v[138:141] offset:50688
	s_waitcnt lgkmcnt(14)
	v_mfma_f32_16x16x32_f16 a[28:31], v[36:39], v[8:11], a[28:31]
	v_mfma_f32_16x16x32_f16 a[24:27], v[32:35], v[8:11], a[24:27]
	s_waitcnt vmcnt(3)
	ds_write_b128 v41, v[150:153] offset:55296
	v_mfma_f32_16x16x32_f16 a[20:23], v[24:27], v[8:11], a[20:23]
	v_mfma_f32_16x16x32_f16 a[16:19], v[16:19], v[8:11], a[16:19]
	s_waitcnt vmcnt(2)
	ds_write_b128 v41, v[158:161] offset:59904
	s_waitcnt lgkmcnt(14)
	v_mfma_f32_16x16x32_f16 a[12:15], v[36:39], v[20:23], a[12:15]
	v_mfma_f32_16x16x32_f16 a[8:11], v[32:35], v[20:23], a[8:11]
	s_waitcnt vmcnt(1)
	ds_write_b128 v41, v[162:165] offset:64512
	v_mfma_f32_16x16x32_f16 a[4:7], v[24:27], v[20:23], a[4:7]
	v_mfma_f32_16x16x32_f16 a[0:3], v[16:19], v[20:23], a[0:3]
	v_add_u32_e32 v16, v40, v99
	s_waitcnt vmcnt(0)
	ds_write_b128 v16, v[166:169]
	ds_read_b128 v[60:63], v64 offset:64
	ds_read_b128 v[52:55], v64 offset:2368
	ds_read_b128 v[48:51], v64 offset:4672
	ds_read_b128 v[40:43], v64 offset:6976
	ds_read_b128 v[36:39], v64 offset:9280
	ds_read_b128 v[32:35], v64 offset:11584
	ds_read_b128 v[24:27], v64 offset:13888
	ds_read_b128 v[16:19], v64 offset:16192
	ds_read_b128 v[64:67], v104 offset:36928
	ds_read_b128 v[68:71], v104 offset:39232
	ds_read_b128 v[72:75], v104 offset:41536
	ds_read_b128 v[76:79], v104 offset:43840
	s_cmp_gt_u32 s14, 5
	s_cbranch_scc1 .Lgw12_nl
; #define MMA_BLK(afx, bfx, nh_) _Pragma("unroll") for (int mi = 0; mi < 8; ++mi) _Pragma("unroll") for (int ni = 0; ni < 4; ++ni) mfma16_acc(acc[mi][(nh_) * 4 + ni], bfx[ni], afx[mi])
; template <class Epi>
; __device__ __forceinline__ void gemm_run(const GemmArgs g, Epi epi, char* smem) {
;     ...
;       MMA_BLK(afA, bfB, 1);
;       __builtin_amdgcn_sched_barrier(0);
;       if (kt + 2 < nk) {
;         const int ko = (kt + 2) * 64;
; #pragma unroll
;         for (int i = 0; i < 8; ++i) { ra[i] = __builtin_amdgcn_raw_buffer_load_b128(Ars, aoff, i * astep + ko * 2, 0); rb[i] = __builtin_amdgcn_raw_buffer_load_b128(Brs, boff, i * bstep + ko * 2, 0); }
;       }
	s_waitcnt lgkmcnt(14)
	v_mfma_f32_16x16x32_f16 a[252:255], v[170:173], v[56:59], a[252:255]
	s_waitcnt lgkmcnt(14)
	v_mfma_f32_16x16x32_f16 a[248:251], v[88:91], v[56:59], a[248:251]
	s_waitcnt lgkmcnt(14)
	v_mfma_f32_16x16x32_f16 a[244:247], v[84:87], v[56:59], a[244:247]
	s_add_i32 s77, s19, 0xfffc8000
	s_waitcnt lgkmcnt(14)
	v_mfma_f32_16x16x32_f16 a[240:243], v[80:83], v[56:59], a[240:243]
	s_mov_b32 s14, s10
	v_mfma_f32_16x16x32_f16 a[236:239], v[170:173], v[44:47], a[236:239]
	s_mov_b32 s15, s11
	v_mfma_f32_16x16x32_f16 a[232:235], v[88:91], v[44:47], a[232:235]
	s_add_i32 s82, s19, 0xfffd0000
	v_mfma_f32_16x16x32_f16 a[228:231], v[84:87], v[44:47], a[228:231]
	buffer_load_dwordx4 v[106:109], v92, s[8:11], s77 offen
	v_mfma_f32_16x16x32_f16 a[224:227], v[80:83], v[44:47], a[224:227]
	buffer_load_dwordx4 v[110:113], v92, s[8:11], s82 offen
	v_mfma_f32_16x16x32_f16 a[220:223], v[170:173], v[28:31], a[220:223]
	buffer_load_dwordx4 v[114:117], v92, s[12:15], s77 offen
	v_mfma_f32_16x16x32_f16 a[216:219], v[88:91], v[28:31], a[216:219]
	buffer_load_dwordx4 v[122:125], v92, s[12:15], s82 offen
	v_mfma_f32_16x16x32_f16 a[212:215], v[84:87], v[28:31], a[212:215]
	s_add_i32 s77, s19, 0xfffd8000
	v_mfma_f32_16x16x32_f16 a[208:211], v[80:83], v[28:31], a[208:211]
	s_add_i32 s82, s19, 0xfffe0000
	v_mfma_f32_16x16x32_f16 a[204:207], v[170:173], v[12:15], a[204:207]
	buffer_load_dwordx4 v[118:121], v92, s[8:11], s77 offen
	v_mfma_f32_16x16x32_f16 a[200:203], v[88:91], v[12:15], a[200:203]
	buffer_load_dwordx4 v[126:129], v92, s[8:11], s82 offen
	v_mfma_f32_16x16x32_f16 a[196:199], v[84:87], v[12:15], a[196:199]
	buffer_load_dwordx4 v[130:133], v92, s[12:15], s77 offen
	v_mfma_f32_16x16x32_f16 a[192:195], v[80:83], v[12:15], a[192:195]
	buffer_load_dwordx4 v[138:141], v92, s[12:15], s82 offen
	v_mfma_f32_16x16x32_f16 a[188:191], v[170:173], v[4:7], a[188:191]
	s_add_i32 s77, s19, 0xfffe8000
	v_mfma_f32_16x16x32_f16 a[184:187], v[88:91], v[4:7], a[184:187]
	s_add_i32 s82, s19, 0xffff0000
	v_mfma_f32_16x16x32_f16 a[180:183], v[84:87], v[4:7], a[180:183]
	buffer_load_dwordx4 v[134:137], v92, s[8:11], s77 offen
	v_mfma_f32_16x16x32_f16 a[176:179], v[80:83], v[4:7], a[176:179]
	buffer_load_dwordx4 v[142:145], v92, s[8:11], s82 offen
	v_mfma_f32_16x16x32_f16 a[172:175], v[170:173], v[0:3], a[172:175]
	buffer_load_dwordx4 v[150:153], v92, s[12:15], s77 offen
	v_mfma_f32_16x16x32_f16 a[168:171], v[88:91], v[0:3], a[168:171]
	buffer_load_dwordx4 v[158:161], v92, s[12:15], s82 offen
	v_mfma_f32_16x16x32_f16 a[164:167], v[84:87], v[0:3], a[164:167]
	s_add_i32 s77, s19, 0xffff8000
	v_mfma_f32_16x16x32_f16 a[160:163], v[80:83], v[0:3], a[160:163]
	buffer_load_dwordx4 v[146:149], v92, s[8:11], s77 offen
	v_mfma_f32_16x16x32_f16 a[132:135], v[170:173], v[8:11], a[132:135]
	buffer_load_dwordx4 v[154:157], v92, s[8:11], s19 offen
	v_mfma_f32_16x16x32_f16 a[124:127], v[88:91], v[8:11], a[124:127]
	buffer_load_dwordx4 v[162:165], v92, s[12:15], s77 offen
	v_mfma_f32_16x16x32_f16 a[116:119], v[84:87], v[8:11], a[116:119]
	buffer_load_dwordx4 v[166:169], v92, s[12:15], s19 offen
	v_mfma_f32_16x16x32_f16 a[112:115], v[80:83], v[8:11], a[112:115]
	v_mfma_f32_16x16x32_f16 a[92:95], v[170:173], v[20:23], a[92:95]
	v_mfma_f32_16x16x32_f16 a[88:91], v[88:91], v[20:23], a[88:91]
	v_mfma_f32_16x16x32_f16 a[84:87], v[84:87], v[20:23], a[84:87]
	v_mfma_f32_16x16x32_f16 a[80:83], v[80:83], v[20:23], a[80:83]
	s_branch .LBB0_1622
.Lgw12_nl:
	s_waitcnt lgkmcnt(14)
	v_mfma_f32_16x16x32_f16 a[252:255], v[170:173], v[56:59], a[252:255]
	s_waitcnt lgkmcnt(14)
	v_mfma_f32_16x16x32_f16 a[248:251], v[88:91], v[56:59], a[248:251]
	s_waitcnt lgkmcnt(14)
	v_mfma_f32_16x16x32_f16 a[244:247], v[84:87], v[56:59], a[244:247]
	s_waitcnt lgkmcnt(14)
	v_mfma_f32_16x16x32_f16 a[240:243], v[80:83], v[56:59], a[240:243]
	v_mfma_f32_16x16x32_f16 a[236:239], v[170:173], v[44:47], a[236:239]
	v_mfma_f32_16x16x32_f16 a[232:235], v[88:91], v[44:47], a[232:235]
	v_mfma_f32_16x16x32_f16 a[228:231], v[84:87], v[44:47], a[228:231]
	v_mfma_f32_16x16x32_f16 a[224:227], v[80:83], v[44:47], a[224:227]
	v_mfma_f32_16x16x32_f16 a[220:223], v[170:173], v[28:31], a[220:223]
	v_mfma_f32_16x16x32_f16 a[216:219], v[88:91], v[28:31], a[216:219]
	v_mfma_f32_16x16x32_f16 a[212:215], v[84:87], v[28:31], a[212:215]
	v_mfma_f32_16x16x32_f16 a[208:211], v[80:83], v[28:31], a[208:211]
	v_mfma_f32_16x16x32_f16 a[204:207], v[170:173], v[12:15], a[204:207]
	v_mfma_f32_16x16x32_f16 a[200:203], v[88:91], v[12:15], a[200:203]
	v_mfma_f32_16x16x32_f16 a[196:199], v[84:87], v[12:15], a[196:199]
	v_mfma_f32_16x16x32_f16 a[192:195], v[80:83], v[12:15], a[192:195]
	v_mfma_f32_16x16x32_f16 a[188:191], v[170:173], v[4:7], a[188:191]
	v_mfma_f32_16x16x32_f16 a[184:187], v[88:91], v[4:7], a[184:187]
	v_mfma_f32_16x16x32_f16 a[180:183], v[84:87], v[4:7], a[180:183]
	v_mfma_f32_16x16x32_f16 a[176:179], v[80:83], v[4:7], a[176:179]
	v_mfma_f32_16x16x32_f16 a[172:175], v[170:173], v[0:3], a[172:175]
	v_mfma_f32_16x16x32_f16 a[168:171], v[88:91], v[0:3], a[168:171]
	v_mfma_f32_16x16x32_f16 a[164:167], v[84:87], v[0:3], a[164:167]
	v_mfma_f32_16x16x32_f16 a[160:163], v[80:83], v[0:3], a[160:163]
	v_mfma_f32_16x16x32_f16 a[132:135], v[170:173], v[8:11], a[132:135]
	v_mfma_f32_16x16x32_f16 a[124:127], v[88:91], v[8:11], a[124:127]
	v_mfma_f32_16x16x32_f16 a[116:119], v[84:87], v[8:11], a[116:119]
	v_mfma_f32_16x16x32_f16 a[112:115], v[80:83], v[8:11], a[112:115]
	v_mfma_f32_16x16x32_f16 a[92:95], v[170:173], v[20:23], a[92:95]
	v_mfma_f32_16x16x32_f16 a[88:91], v[88:91], v[20:23], a[88:91]
	v_mfma_f32_16x16x32_f16 a[84:87], v[84:87], v[20:23], a[84:87]
	v_mfma_f32_16x16x32_f16 a[80:83], v[80:83], v[20:23], a[80:83]
	s_branch .LBB0_1622

; #define LD_AF(dst, ks_) _Pragma("unroll") for (int i = 0; i < 8; ++i) dst[i] = *(const h8*)(sA + i * 16 * G_LD + (ks_) * 32)
; #define LD_BF(dst, ks_, nh_) _Pragma("unroll") for (int i = 0; i < 4; ++i) dst[i] = *(const h8*)(sB + ((nh_) * 4 + i) * 16 * G_LD + (ks_) * 32)
; #define MMA_BLK(afx, bfx, nh_) _Pragma("unroll") for (int mi = 0; mi < 8; ++mi) _Pragma("unroll") for (int ni = 0; ni < 4; ++ni) mfma16_acc(acc[mi][(nh_) * 4 + ni], bfx[ni], afx[mi])
; template <class Epi>
; __device__ __forceinline__ void gemm_run(const GemmArgs g, Epi epi, char* smem) {
;     ...
;     for (int kt = 0; kt < nk; ++kt) {
;       const hf* sA = sbase + (kt & 1) * G_STAGE + (wm * 128 + fr) * G_LD + fqs;
;       const hf* sB = sbase + (kt & 1) * G_STAGE + (256 + wn * 128 + fr) * G_LD + fqs;
;       hf* st = sbase + ((kt + 1) & 1) * G_STAGE;
;       h8 afA[8], afB[8], bfA[4], bfB[4];
;     ...
;       LD_AF(afA, 0); LD_BF(bfA, 0, 0);
;       if (kt + 1 < nk) {
; #pragma unroll
;         for (int i = 0; i < 8; ++i) *(u4*)(st + (lr + 32 * i) * G_LD + lcw) = ra[i];
;       }
;       __builtin_amdgcn_sched_barrier(0);
;       LD_BF(bfB, 0, 1);
;       MMA_BLK(afA, bfA, 0);
;       __builtin_amdgcn_sched_barrier(0);
;       if (kt + 1 < nk) {
; #pragma unroll
;         for (int i = 0; i < 8; ++i) *(u4*)(st + (256 + lr + 32 * i) * G_LD + lcw) = rb[i];
;       }
;       LD_AF(afB, 1); LD_BF(bfA, 1, 0);
;       MMA_BLK(afA, bfB, 1);
.LBB0_1631:
	s_bitcmp1_b32 s15, 0
	s_cselect_b32 s11, 0x12000, 0
	s_add_i32 s11, s11, 16
	v_add3_u32 v104, s11, v96, v103
	v_add3_u32 v64, s11, v95, v103
	ds_read_b128 v[36:39], v104 offset:36864
	ds_read_b128 v[56:59], v64
	ds_read_b128 v[32:35], v104 offset:39168
	ds_read_b128 v[24:27], v104 offset:41472
	ds_read_b128 v[16:19], v104 offset:43776
	ds_read_b128 v[44:47], v64 offset:2304
	ds_read_b128 v[28:31], v64 offset:4608
	ds_read_b128 v[12:15], v64 offset:6912
	ds_read_b128 v[4:7], v64 offset:9216
	ds_read_b128 v[0:3], v64 offset:11520
	ds_read_b128 v[8:11], v64 offset:13824
	ds_read_b128 v[20:23], v64 offset:16128
	s_mov_b32 s10, s15
	s_add_i32 s15, s15, 1
	s_bitcmp1_b32 s15, 0
	s_cselect_b32 s16, 0x12000, 0
	v_add_u32_e32 v40, s16, v93
	v_add_u32_e32 v41, v40, v98
	ds_read_b128 v[170:173], v104 offset:46080
	ds_read_b128 v[88:91], v104 offset:48384
	ds_read_b128 v[84:87], v104 offset:50688
	ds_read_b128 v[80:83], v104 offset:52992
	s_waitcnt lgkmcnt(14)
	v_mfma_f32_16x16x32_f16 a[252:255], v[36:39], v[56:59], a[252:255]
	s_waitcnt lgkmcnt(13)
	v_mfma_f32_16x16x32_f16 a[236:239], v[32:35], v[56:59], a[236:239]
	s_waitcnt vmcnt(15)
	ds_write_b128 v41, v[106:109]
	s_waitcnt lgkmcnt(13)
	v_mfma_f32_16x16x32_f16 a[228:231], v[24:27], v[56:59], a[228:231]
	s_waitcnt lgkmcnt(12)
	v_mfma_f32_16x16x32_f16 a[224:227], v[16:19], v[56:59], a[224:227]
	s_waitcnt vmcnt(14)
	ds_write_b128 v41, v[110:113] offset:4608
	s_waitcnt lgkmcnt(12)
	v_mfma_f32_16x16x32_f16 a[212:215], v[36:39], v[44:47], a[212:215]
	v_mfma_f32_16x16x32_f16 a[204:207], v[32:35], v[44:47], a[204:207]
	s_waitcnt vmcnt(11)
	ds_write_b128 v41, v[118:121] offset:9216
	v_mfma_f32_16x16x32_f16 a[196:199], v[24:27], v[44:47], a[196:199]
	v_mfma_f32_16x16x32_f16 a[192:195], v[16:19], v[44:47], a[192:195]
	s_waitcnt vmcnt(10)
	ds_write_b128 v41, v[126:129] offset:13824
	s_waitcnt lgkmcnt(13)
	v_mfma_f32_16x16x32_f16 a[180:183], v[36:39], v[28:31], a[180:183]
	v_mfma_f32_16x16x32_f16 a[172:175], v[32:35], v[28:31], a[172:175]
	s_waitcnt vmcnt(7)
	ds_write_b128 v41, v[134:137] offset:18432
	v_mfma_f32_16x16x32_f16 a[164:167], v[24:27], v[28:31], a[164:167]
	v_mfma_f32_16x16x32_f16 a[160:163], v[16:19], v[28:31], a[160:163]
	s_waitcnt vmcnt(6)
	ds_write_b128 v41, v[142:145] offset:23040
	s_waitcnt lgkmcnt(14)
	v_mfma_f32_16x16x32_f16 a[148:151], v[36:39], v[12:15], a[148:151]
	v_mfma_f32_16x16x32_f16 a[140:143], v[32:35], v[12:15], a[140:143]
	s_waitcnt vmcnt(3)
	ds_write_b128 v41, v[146:149] offset:27648
	v_mfma_f32_16x16x32_f16 a[132:135], v[24:27], v[12:15], a[132:135]
	v_mfma_f32_16x16x32_f16 a[128:131], v[16:19], v[12:15], a[128:131]
	s_waitcnt vmcnt(2)
	ds_write_b128 v41, v[154:157] offset:32256
	s_waitcnt lgkmcnt(14)
	v_mfma_f32_16x16x32_f16 a[116:119], v[36:39], v[4:7], a[116:119]
	v_mfma_f32_16x16x32_f16 a[108:111], v[32:35], v[4:7], a[108:111]
	s_waitcnt vmcnt(7)
	ds_write_b128 v41, v[114:117] offset:36864
	v_mfma_f32_16x16x32_f16 a[100:103], v[24:27], v[4:7], a[100:103]
	v_mfma_f32_16x16x32_f16 a[96:99], v[16:19], v[4:7], a[96:99]
	s_waitcnt vmcnt(6)
	ds_write_b128 v41, v[122:125] offset:41472
	s_waitcnt lgkmcnt(14)
	v_mfma_f32_16x16x32_f16 a[84:87], v[36:39], v[0:3], a[84:87]
	v_mfma_f32_16x16x32_f16 a[76:79], v[32:35], v[0:3], a[76:79]
	s_waitcnt vmcnt(5)
	ds_write_b128 v41, v[130:133] offset:46080
	v_mfma_f32_16x16x32_f16 a[68:71], v[24:27], v[0:3], a[68:71]
	v_mfma_f32_16x16x32_f16 a[64:67], v[16:19], v[0:3], a[64:67]
	s_waitcnt vmcnt(4)
	ds_write_b128 v41, v[138:141] offset:50688
	s_waitcnt lgkmcnt(14)
	v_mfma_f32_16x16x32_f16 a[52:55], v[36:39], v[8:11], a[52:55]
	v_mfma_f32_16x16x32_f16 a[44:47], v[32:35], v[8:11], a[44:47]
	s_waitcnt vmcnt(3)
	ds_write_b128 v41, v[150:153] offset:55296
	v_mfma_f32_16x16x32_f16 a[36:39], v[24:27], v[8:11], a[36:39]
	v_mfma_f32_16x16x32_f16 a[32:35], v[16:19], v[8:11], a[32:35]
	s_waitcnt vmcnt(2)
	ds_write_b128 v41, v[158:161] offset:59904
	s_waitcnt lgkmcnt(14)
	v_mfma_f32_16x16x32_f16 a[24:27], v[36:39], v[20:23], a[24:27]
	v_mfma_f32_16x16x32_f16 a[16:19], v[32:35], v[20:23], a[16:19]
	s_waitcnt vmcnt(1)
	ds_write_b128 v41, v[162:165] offset:64512
	v_mfma_f32_16x16x32_f16 a[8:11], v[24:27], v[20:23], a[8:11]
	v_mfma_f32_16x16x32_f16 a[0:3], v[16:19], v[20:23], a[0:3]
	v_add_u32_e32 v16, v40, v99
	s_waitcnt vmcnt(0)
	ds_write_b128 v16, v[166:169]
	ds_read_b128 v[60:63], v64 offset:64
	ds_read_b128 v[52:55], v64 offset:2368
	ds_read_b128 v[48:51], v64 offset:4672
	ds_read_b128 v[40:43], v64 offset:6976
	ds_read_b128 v[36:39], v64 offset:9280
	ds_read_b128 v[32:35], v64 offset:11584
	ds_read_b128 v[24:27], v64 offset:13888
	ds_read_b128 v[16:19], v64 offset:16192
	ds_read_b128 v[64:67], v104 offset:36928
	ds_read_b128 v[68:71], v104 offset:39232
	ds_read_b128 v[72:75], v104 offset:41536
	ds_read_b128 v[76:79], v104 offset:43840
	s_cmp_gt_u32 s10, 1
	s_cbranch_scc1 .Lgw13_nl
; #define MMA_BLK(afx, bfx, nh_) _Pragma("unroll") for (int mi = 0; mi < 8; ++mi) _Pragma("unroll") for (int ni = 0; ni < 4; ++ni) mfma16_acc(acc[mi][(nh_) * 4 + ni], bfx[ni], afx[mi])
; template <class Epi>
; __device__ __forceinline__ void gemm_run(const GemmArgs g, Epi epi, char* smem) {
;     ...
;       MMA_BLK(afA, bfB, 1);
;       __builtin_amdgcn_sched_barrier(0);
;       if (kt + 2 < nk) {
;         const int ko = (kt + 2) * 64;
; #pragma unroll
;         for (int i = 0; i < 8; ++i) { ra[i] = __builtin_amdgcn_raw_buffer_load_b128(Ars, aoff, i * astep + ko * 2, 0); rb[i] = __builtin_amdgcn_raw_buffer_load_b128(Brs, boff, i * bstep + ko * 2, 0); }
;       }
	s_waitcnt lgkmcnt(14)
	v_mfma_f32_16x16x32_f16 a[248:251], v[170:173], v[56:59], a[248:251]
	s_waitcnt lgkmcnt(14)
	v_mfma_f32_16x16x32_f16 a[244:247], v[88:91], v[56:59], a[244:247]
	s_waitcnt lgkmcnt(14)
	v_mfma_f32_16x16x32_f16 a[240:243], v[84:87], v[56:59], a[240:243]
	s_add_i32 s16, s13, 0xfffe4000
	s_waitcnt lgkmcnt(14)
	v_mfma_f32_16x16x32_f16 a[232:235], v[80:83], v[56:59], a[232:235]
	s_mov_b32 s10, s22
	v_mfma_f32_16x16x32_f16 a[220:223], v[170:173], v[44:47], a[220:223]
	s_mov_b32 s11, s23
	v_mfma_f32_16x16x32_f16 a[216:219], v[88:91], v[44:47], a[216:219]
	s_add_i32 s17, s13, 0xfffe8000
	v_mfma_f32_16x16x32_f16 a[208:211], v[84:87], v[44:47], a[208:211]
	buffer_load_dwordx4 v[106:109], v92, s[20:23], s16 offen
	v_mfma_f32_16x16x32_f16 a[200:203], v[80:83], v[44:47], a[200:203]
	buffer_load_dwordx4 v[110:113], v92, s[20:23], s17 offen
	v_mfma_f32_16x16x32_f16 a[188:191], v[170:173], v[28:31], a[188:191]
	buffer_load_dwordx4 v[114:117], v92, s[8:11], s16 offen
	v_mfma_f32_16x16x32_f16 a[184:187], v[88:91], v[28:31], a[184:187]
	buffer_load_dwordx4 v[122:125], v92, s[8:11], s17 offen
	v_mfma_f32_16x16x32_f16 a[176:179], v[84:87], v[28:31], a[176:179]
	s_add_i32 s16, s13, 0xfffec000
	v_mfma_f32_16x16x32_f16 a[168:171], v[80:83], v[28:31], a[168:171]
	s_add_i32 s17, s13, 0xffff0000
	v_mfma_f32_16x16x32_f16 a[156:159], v[170:173], v[12:15], a[156:159]
	buffer_load_dwordx4 v[118:121], v92, s[20:23], s16 offen
	v_mfma_f32_16x16x32_f16 a[152:155], v[88:91], v[12:15], a[152:155]
	buffer_load_dwordx4 v[126:129], v92, s[20:23], s17 offen
	v_mfma_f32_16x16x32_f16 a[144:147], v[84:87], v[12:15], a[144:147]
	buffer_load_dwordx4 v[130:133], v92, s[8:11], s16 offen
	v_mfma_f32_16x16x32_f16 a[136:139], v[80:83], v[12:15], a[136:139]
	buffer_load_dwordx4 v[138:141], v92, s[8:11], s17 offen
	v_mfma_f32_16x16x32_f16 a[124:127], v[170:173], v[4:7], a[124:127]
	s_add_i32 s16, s13, 0xffff4000
	v_mfma_f32_16x16x32_f16 a[120:123], v[88:91], v[4:7], a[120:123]
	s_add_i32 s17, s13, 0xffff8000
	v_mfma_f32_16x16x32_f16 a[112:115], v[84:87], v[4:7], a[112:115]
	buffer_load_dwordx4 v[134:137], v92, s[20:23], s16 offen
	v_mfma_f32_16x16x32_f16 a[104:107], v[80:83], v[4:7], a[104:107]
	buffer_load_dwordx4 v[142:145], v92, s[20:23], s17 offen
	v_mfma_f32_16x16x32_f16 a[92:95], v[170:173], v[0:3], a[92:95]
	buffer_load_dwordx4 v[150:153], v92, s[8:11], s16 offen
	v_mfma_f32_16x16x32_f16 a[88:91], v[88:91], v[0:3], a[88:91]
	buffer_load_dwordx4 v[158:161], v92, s[8:11], s17 offen
	v_mfma_f32_16x16x32_f16 a[80:83], v[84:87], v[0:3], a[80:83]
	s_add_i32 s16, s13, 0xffffc000
	v_mfma_f32_16x16x32_f16 a[72:75], v[80:83], v[0:3], a[72:75]
	buffer_load_dwordx4 v[146:149], v92, s[20:23], s16 offen
	v_mfma_f32_16x16x32_f16 a[60:63], v[170:173], v[8:11], a[60:63]
	buffer_load_dwordx4 v[154:157], v92, s[20:23], s13 offen
	v_mfma_f32_16x16x32_f16 a[56:59], v[88:91], v[8:11], a[56:59]
	buffer_load_dwordx4 v[162:165], v92, s[8:11], s16 offen
	v_mfma_f32_16x16x32_f16 a[48:51], v[84:87], v[8:11], a[48:51]
	buffer_load_dwordx4 v[166:169], v92, s[8:11], s13 offen
	v_mfma_f32_16x16x32_f16 a[40:43], v[80:83], v[8:11], a[40:43]
	v_mfma_f32_16x16x32_f16 a[28:31], v[170:173], v[20:23], a[28:31]
	v_mfma_f32_16x16x32_f16 a[20:23], v[88:91], v[20:23], a[20:23]
	v_mfma_f32_16x16x32_f16 a[12:15], v[84:87], v[20:23], a[12:15]
	v_mfma_f32_16x16x32_f16 a[4:7], v[80:83], v[20:23], a[4:7]
	s_branch .LBB0_1630
.Lgw13_nl:
	s_waitcnt lgkmcnt(14)
	v_mfma_f32_16x16x32_f16 a[248:251], v[170:173], v[56:59], a[248:251]
	s_waitcnt lgkmcnt(14)
	v_mfma_f32_16x16x32_f16 a[244:247], v[88:91], v[56:59], a[244:247]
	s_waitcnt lgkmcnt(14)
	v_mfma_f32_16x16x32_f16 a[240:243], v[84:87], v[56:59], a[240:243]
	s_waitcnt lgkmcnt(14)
	v_mfma_f32_16x16x32_f16 a[232:235], v[80:83], v[56:59], a[232:235]
	v_mfma_f32_16x16x32_f16 a[220:223], v[170:173], v[44:47], a[220:223]
	v_mfma_f32_16x16x32_f16 a[216:219], v[88:91], v[44:47], a[216:219]
	v_mfma_f32_16x16x32_f16 a[208:211], v[84:87], v[44:47], a[208:211]
	v_mfma_f32_16x16x32_f16 a[200:203], v[80:83], v[44:47], a[200:203]
	v_mfma_f32_16x16x32_f16 a[188:191], v[170:173], v[28:31], a[188:191]
	v_mfma_f32_16x16x32_f16 a[184:187], v[88:91], v[28:31], a[184:187]
	v_mfma_f32_16x16x32_f16 a[176:179], v[84:87], v[28:31], a[176:179]
	v_mfma_f32_16x16x32_f16 a[168:171], v[80:83], v[28:31], a[168:171]
	v_mfma_f32_16x16x32_f16 a[156:159], v[170:173], v[12:15], a[156:159]
	v_mfma_f32_16x16x32_f16 a[152:155], v[88:91], v[12:15], a[152:155]
	v_mfma_f32_16x16x32_f16 a[144:147], v[84:87], v[12:15], a[144:147]
	v_mfma_f32_16x16x32_f16 a[136:139], v[80:83], v[12:15], a[136:139]
	v_mfma_f32_16x16x32_f16 a[124:127], v[170:173], v[4:7], a[124:127]
	v_mfma_f32_16x16x32_f16 a[120:123], v[88:91], v[4:7], a[120:123]
	v_mfma_f32_16x16x32_f16 a[112:115], v[84:87], v[4:7], a[112:115]
	v_mfma_f32_16x16x32_f16 a[104:107], v[80:83], v[4:7], a[104:107]
	v_mfma_f32_16x16x32_f16 a[92:95], v[170:173], v[0:3], a[92:95]
	v_mfma_f32_16x16x32_f16 a[88:91], v[88:91], v[0:3], a[88:91]
	v_mfma_f32_16x16x32_f16 a[80:83], v[84:87], v[0:3], a[80:83]
	v_mfma_f32_16x16x32_f16 a[72:75], v[80:83], v[0:3], a[72:75]
	v_mfma_f32_16x16x32_f16 a[60:63], v[170:173], v[8:11], a[60:63]
	v_mfma_f32_16x16x32_f16 a[56:59], v[88:91], v[8:11], a[56:59]
	v_mfma_f32_16x16x32_f16 a[48:51], v[84:87], v[8:11], a[48:51]
	v_mfma_f32_16x16x32_f16 a[40:43], v[80:83], v[8:11], a[40:43]
	v_mfma_f32_16x16x32_f16 a[28:31], v[170:173], v[20:23], a[28:31]
	v_mfma_f32_16x16x32_f16 a[20:23], v[88:91], v[20:23], a[20:23]
	v_mfma_f32_16x16x32_f16 a[12:15], v[84:87], v[20:23], a[12:15]
	v_mfma_f32_16x16x32_f16 a[4:7], v[80:83], v[20:23], a[4:7]
	s_branch .LBB0_1630

; #define LD_AF(dst, ks_) _Pragma("unroll") for (int i = 0; i < 8; ++i) dst[i] = *(const h8*)(sA + i * 16 * G_LD + (ks_) * 32)
; #define LD_BF(dst, ks_, nh_) _Pragma("unroll") for (int i = 0; i < 4; ++i) dst[i] = *(const h8*)(sB + ((nh_) * 4 + i) * 16 * G_LD + (ks_) * 32)
; #define MMA_BLK(afx, bfx, nh_) _Pragma("unroll") for (int mi = 0; mi < 8; ++mi) _Pragma("unroll") for (int ni = 0; ni < 4; ++ni) mfma16_acc(acc[mi][(nh_) * 4 + ni], bfx[ni], afx[mi])
; template <class Epi>
; __device__ __forceinline__ void gemm_run(const GemmArgs g, Epi epi, char* smem) {
;     ...
;     for (int kt = 0; kt < nk; ++kt) {
;       const hf* sA = sbase + (kt & 1) * G_STAGE + (wm * 128 + fr) * G_LD + fqs;
;       const hf* sB = sbase + (kt & 1) * G_STAGE + (256 + wn * 128 + fr) * G_LD + fqs;
;       hf* st = sbase + ((kt + 1) & 1) * G_STAGE;
;       h8 afA[8], afB[8], bfA[4], bfB[4];
;     ...
;       LD_AF(afA, 0); LD_BF(bfA, 0, 0);
;       if (kt + 1 < nk) {
; #pragma unroll
;         for (int i = 0; i < 8; ++i) *(u4*)(st + (lr + 32 * i) * G_LD + lcw) = ra[i];
;       }
;       __builtin_amdgcn_sched_barrier(0);
;       LD_BF(bfB, 0, 1);
;       MMA_BLK(afA, bfA, 0);
;       __builtin_amdgcn_sched_barrier(0);
;       if (kt + 1 < nk) {
; #pragma unroll
;         for (int i = 0; i < 8; ++i) *(u4*)(st + (256 + lr + 32 * i) * G_LD + lcw) = rb[i];
;       }
;       LD_AF(afB, 1); LD_BF(bfA, 1, 0);
;       MMA_BLK(afA, bfB, 1);
.LBB0_2023:
	s_bitcmp1_b32 s23, 0
	s_cselect_b32 s15, 0x12000, 0
	s_add_i32 s15, s15, 16
	v_add3_u32 v92, s15, v132, v139
	v_add3_u32 v64, s15, v131, v139
	ds_read_b128 v[36:39], v92 offset:36864
	ds_read_b128 v[56:59], v64
	ds_read_b128 v[32:35], v92 offset:39168
	ds_read_b128 v[24:27], v92 offset:41472
	ds_read_b128 v[16:19], v92 offset:43776
	ds_read_b128 v[44:47], v64 offset:2304
	ds_read_b128 v[28:31], v64 offset:4608
	ds_read_b128 v[12:15], v64 offset:6912
	ds_read_b128 v[4:7], v64 offset:9216
	ds_read_b128 v[0:3], v64 offset:11520
	ds_read_b128 v[8:11], v64 offset:13824
	ds_read_b128 v[20:23], v64 offset:16128
	s_mov_b32 s14, s23
	s_add_i32 s23, s23, 1
	s_bitcmp1_b32 s23, 0
	s_cselect_b32 s62, 0x12000, 0
	v_add_u32_e32 v40, s62, v129
	v_add_u32_e32 v41, v40, v134
	ds_read_b128 v[172:175], v92 offset:46080
	ds_read_b128 v[88:91], v92 offset:48384
	ds_read_b128 v[84:87], v92 offset:50688
	ds_read_b128 v[80:83], v92 offset:52992
	s_waitcnt lgkmcnt(14)
	v_mfma_f32_16x16x32_f16 a[208:211], v[36:39], v[56:59], a[208:211]
	s_waitcnt lgkmcnt(13)
	v_mfma_f32_16x16x32_f16 a[200:203], v[32:35], v[56:59], a[200:203]
	s_waitcnt vmcnt(15)
	ds_write_b128 v41, v[94:97]
	s_waitcnt lgkmcnt(13)
	v_mfma_f32_16x16x32_f16 a[196:199], v[24:27], v[56:59], a[196:199]
	s_waitcnt lgkmcnt(12)
	v_mfma_f32_16x16x32_f16 a[192:195], v[16:19], v[56:59], a[192:195]
	s_waitcnt vmcnt(14)
	ds_write_b128 v41, v[98:101] offset:4608
	s_waitcnt lgkmcnt(12)
	v_mfma_f32_16x16x32_f16 a[188:191], v[36:39], v[44:47], a[188:191]
	v_mfma_f32_16x16x32_f16 a[184:187], v[32:35], v[44:47], a[184:187]
	s_waitcnt vmcnt(11)
	ds_write_b128 v41, v[106:109] offset:9216
	v_mfma_f32_16x16x32_f16 a[180:183], v[24:27], v[44:47], a[180:183]
	v_mfma_f32_16x16x32_f16 a[176:179], v[16:19], v[44:47], a[176:179]
	s_waitcnt vmcnt(10)
	ds_write_b128 v41, v[114:117] offset:13824
	s_waitcnt lgkmcnt(13)
	v_mfma_f32_16x16x32_f16 a[156:159], v[36:39], v[28:31], a[156:159]
	v_mfma_f32_16x16x32_f16 a[152:155], v[32:35], v[28:31], a[152:155]
	s_waitcnt vmcnt(7)
	ds_write_b128 v41, v[122:125] offset:18432
	v_mfma_f32_16x16x32_f16 a[148:151], v[24:27], v[28:31], a[148:151]
	v_mfma_f32_16x16x32_f16 a[144:147], v[16:19], v[28:31], a[144:147]
	s_waitcnt vmcnt(6)
	ds_write_b128 v41, v[144:147] offset:23040
	s_waitcnt lgkmcnt(14)
	v_mfma_f32_16x16x32_f16 a[124:127], v[36:39], v[12:15], a[124:127]
	v_mfma_f32_16x16x32_f16 a[120:123], v[32:35], v[12:15], a[120:123]
	s_waitcnt vmcnt(3)
	ds_write_b128 v41, v[148:151] offset:27648
	v_mfma_f32_16x16x32_f16 a[116:119], v[24:27], v[12:15], a[116:119]
	v_mfma_f32_16x16x32_f16 a[112:115], v[16:19], v[12:15], a[112:115]
	s_waitcnt vmcnt(2)
	ds_write_b128 v41, v[156:159] offset:32256
	s_waitcnt lgkmcnt(14)
	v_mfma_f32_16x16x32_f16 a[92:95], v[36:39], v[4:7], a[92:95]
	v_mfma_f32_16x16x32_f16 a[88:91], v[32:35], v[4:7], a[88:91]
	s_waitcnt vmcnt(7)
	ds_write_b128 v41, v[102:105] offset:36864
	v_mfma_f32_16x16x32_f16 a[84:87], v[24:27], v[4:7], a[84:87]
	v_mfma_f32_16x16x32_f16 a[80:83], v[16:19], v[4:7], a[80:83]
	s_waitcnt vmcnt(6)
	ds_write_b128 v41, v[110:113] offset:41472
	s_waitcnt lgkmcnt(14)
	v_mfma_f32_16x16x32_f16 a[60:63], v[36:39], v[0:3], a[60:63]
	v_mfma_f32_16x16x32_f16 a[56:59], v[32:35], v[0:3], a[56:59]
	s_waitcnt vmcnt(5)
	ds_write_b128 v41, v[118:121] offset:46080
	v_mfma_f32_16x16x32_f16 a[52:55], v[24:27], v[0:3], a[52:55]
	v_mfma_f32_16x16x32_f16 a[48:51], v[16:19], v[0:3], a[48:51]
	s_waitcnt vmcnt(4)
	ds_write_b128 v41, v[140:143] offset:50688
	s_waitcnt lgkmcnt(14)
	v_mfma_f32_16x16x32_f16 a[28:31], v[36:39], v[8:11], a[28:31]
	v_mfma_f32_16x16x32_f16 a[24:27], v[32:35], v[8:11], a[24:27]
	s_waitcnt vmcnt(3)
	ds_write_b128 v41, v[152:155] offset:55296
	v_mfma_f32_16x16x32_f16 a[20:23], v[24:27], v[8:11], a[20:23]
	v_mfma_f32_16x16x32_f16 a[16:19], v[16:19], v[8:11], a[16:19]
	s_waitcnt vmcnt(2)
	ds_write_b128 v41, v[160:163] offset:59904
	s_waitcnt lgkmcnt(14)
	v_mfma_f32_16x16x32_f16 a[12:15], v[36:39], v[20:23], a[12:15]
	v_mfma_f32_16x16x32_f16 a[8:11], v[32:35], v[20:23], a[8:11]
	s_waitcnt vmcnt(1)
	ds_write_b128 v41, v[164:167] offset:64512
	v_mfma_f32_16x16x32_f16 a[4:7], v[24:27], v[20:23], a[4:7]
	v_mfma_f32_16x16x32_f16 a[0:3], v[16:19], v[20:23], a[0:3]
	v_add_u32_e32 v16, v40, v135
	s_waitcnt vmcnt(0)
	ds_write_b128 v16, v[168:171]
	ds_read_b128 v[60:63], v64 offset:64
	ds_read_b128 v[52:55], v64 offset:2368
	ds_read_b128 v[48:51], v64 offset:4672
	ds_read_b128 v[40:43], v64 offset:6976
	ds_read_b128 v[36:39], v64 offset:9280
	ds_read_b128 v[32:35], v64 offset:11584
	ds_read_b128 v[24:27], v64 offset:13888
	ds_read_b128 v[16:19], v64 offset:16192
	ds_read_b128 v[64:67], v92 offset:36928
	ds_read_b128 v[68:71], v92 offset:39232
	ds_read_b128 v[72:75], v92 offset:41536
	ds_read_b128 v[76:79], v92 offset:43840
	s_cmp_gt_u32 s14, 29
	s_cbranch_scc1 .Lgw14_nl
; #define MMA_BLK(afx, bfx, nh_) _Pragma("unroll") for (int mi = 0; mi < 8; ++mi) _Pragma("unroll") for (int ni = 0; ni < 4; ++ni) mfma16_acc(acc[mi][(nh_) * 4 + ni], bfx[ni], afx[mi])
; template <class Epi>
; __device__ __forceinline__ void gemm_run(const GemmArgs g, Epi epi, char* smem) {
;     ...
;       MMA_BLK(afA, bfB, 1);
;       __builtin_amdgcn_sched_barrier(0);
;       if (kt + 2 < nk) {
;         const int ko = (kt + 2) * 64;
; #pragma unroll
;         for (int i = 0; i < 8; ++i) { ra[i] = __builtin_amdgcn_raw_buffer_load_b128(Ars, aoff, i * astep + ko * 2, 0); rb[i] = __builtin_amdgcn_raw_buffer_load_b128(Brs, boff, i * bstep + ko * 2, 0); }
;       }
	s_waitcnt lgkmcnt(14)
	v_mfma_f32_16x16x32_f16 a[240:243], v[172:175], v[56:59], a[240:243]
	s_waitcnt lgkmcnt(14)
	v_mfma_f32_16x16x32_f16 a[252:255], v[88:91], v[56:59], a[252:255]
	s_waitcnt lgkmcnt(14)
	v_mfma_f32_16x16x32_f16 a[248:251], v[84:87], v[56:59], a[248:251]
	s_add_i32 s62, s21, 0xfff20000
	s_waitcnt lgkmcnt(14)
	v_mfma_f32_16x16x32_f16 a[244:247], v[80:83], v[56:59], a[244:247]
	s_mov_b32 s14, s10
	v_mfma_f32_16x16x32_f16 a[236:239], v[172:175], v[44:47], a[236:239]
	s_mov_b32 s15, s11
	v_mfma_f32_16x16x32_f16 a[232:235], v[88:91], v[44:47], a[232:235]
	s_add_i32 s63, s21, 0xfff40000
	v_mfma_f32_16x16x32_f16 a[228:231], v[84:87], v[44:47], a[228:231]
	buffer_load_dwordx4 v[94:97], v128, s[8:11], s62 offen
	v_mfma_f32_16x16x32_f16 a[224:227], v[80:83], v[44:47], a[224:227]
	buffer_load_dwordx4 v[98:101], v128, s[8:11], s63 offen
	v_mfma_f32_16x16x32_f16 a[220:223], v[172:175], v[28:31], a[220:223]
	buffer_load_dwordx4 v[102:105], v128, s[12:15], s62 offen
	v_mfma_f32_16x16x32_f16 a[216:219], v[88:91], v[28:31], a[216:219]
	buffer_load_dwordx4 v[110:113], v128, s[12:15], s63 offen
	v_mfma_f32_16x16x32_f16 a[212:215], v[84:87], v[28:31], a[212:215]
	s_add_i32 s62, s21, 0xfff60000
	v_mfma_f32_16x16x32_f16 a[204:207], v[80:83], v[28:31], a[204:207]
	s_add_i32 s63, s21, 0xfff80000
	v_mfma_f32_16x16x32_f16 a[172:175], v[172:175], v[12:15], a[172:175]
	buffer_load_dwordx4 v[106:109], v128, s[8:11], s62 offen
	v_mfma_f32_16x16x32_f16 a[168:171], v[88:91], v[12:15], a[168:171]
	buffer_load_dwordx4 v[114:117], v128, s[8:11], s63 offen
	v_mfma_f32_16x16x32_f16 a[164:167], v[84:87], v[12:15], a[164:167]
	buffer_load_dwordx4 v[118:121], v128, s[12:15], s62 offen
	v_mfma_f32_16x16x32_f16 a[160:163], v[80:83], v[12:15], a[160:163]
	buffer_load_dwordx4 v[140:143], v128, s[12:15], s63 offen
	v_mfma_f32_16x16x32_f16 a[140:143], v[172:175], v[4:7], a[140:143]
	s_add_i32 s62, s21, 0xfffa0000
	v_mfma_f32_16x16x32_f16 a[136:139], v[88:91], v[4:7], a[136:139]
	s_add_i32 s63, s21, 0xfffc0000
	v_mfma_f32_16x16x32_f16 a[132:135], v[84:87], v[4:7], a[132:135]
	buffer_load_dwordx4 v[122:125], v128, s[8:11], s62 offen
	v_mfma_f32_16x16x32_f16 a[128:131], v[80:83], v[4:7], a[128:131]
	buffer_load_dwordx4 v[144:147], v128, s[8:11], s63 offen
	v_mfma_f32_16x16x32_f16 a[108:111], v[172:175], v[0:3], a[108:111]
	buffer_load_dwordx4 v[152:155], v128, s[12:15], s62 offen
	v_mfma_f32_16x16x32_f16 a[104:107], v[88:91], v[0:3], a[104:107]
	buffer_load_dwordx4 v[160:163], v128, s[12:15], s63 offen
	v_mfma_f32_16x16x32_f16 a[100:103], v[84:87], v[0:3], a[100:103]
	s_add_i32 s62, s21, 0xfffe0000
	v_mfma_f32_16x16x32_f16 a[96:99], v[80:83], v[0:3], a[96:99]
	buffer_load_dwordx4 v[148:151], v128, s[8:11], s62 offen
	v_mfma_f32_16x16x32_f16 a[76:79], v[172:175], v[8:11], a[76:79]
	buffer_load_dwordx4 v[156:159], v128, s[8:11], s21 offen
	v_mfma_f32_16x16x32_f16 a[72:75], v[88:91], v[8:11], a[72:75]
	buffer_load_dwordx4 v[164:167], v128, s[12:15], s62 offen
	v_mfma_f32_16x16x32_f16 a[68:71], v[84:87], v[8:11], a[68:71]
	buffer_load_dwordx4 v[168:171], v128, s[12:15], s21 offen
	v_mfma_f32_16x16x32_f16 a[64:67], v[80:83], v[8:11], a[64:67]
	v_mfma_f32_16x16x32_f16 a[44:47], v[172:175], v[20:23], a[44:47]
	v_mfma_f32_16x16x32_f16 a[40:43], v[88:91], v[20:23], a[40:43]
	v_mfma_f32_16x16x32_f16 a[36:39], v[84:87], v[20:23], a[36:39]
	v_mfma_f32_16x16x32_f16 a[32:35], v[80:83], v[20:23], a[32:35]
	s_branch .LBB0_2022
.Lgw14_nl:
	s_waitcnt lgkmcnt(14)
	v_mfma_f32_16x16x32_f16 a[240:243], v[172:175], v[56:59], a[240:243]
	s_waitcnt lgkmcnt(14)
	v_mfma_f32_16x16x32_f16 a[252:255], v[88:91], v[56:59], a[252:255]
	s_waitcnt lgkmcnt(14)
	v_mfma_f32_16x16x32_f16 a[248:251], v[84:87], v[56:59], a[248:251]
	s_waitcnt lgkmcnt(14)
	v_mfma_f32_16x16x32_f16 a[244:247], v[80:83], v[56:59], a[244:247]
	v_mfma_f32_16x16x32_f16 a[236:239], v[172:175], v[44:47], a[236:239]
	v_mfma_f32_16x16x32_f16 a[232:235], v[88:91], v[44:47], a[232:235]
	v_mfma_f32_16x16x32_f16 a[228:231], v[84:87], v[44:47], a[228:231]
	v_mfma_f32_16x16x32_f16 a[224:227], v[80:83], v[44:47], a[224:227]
	v_mfma_f32_16x16x32_f16 a[220:223], v[172:175], v[28:31], a[220:223]
	v_mfma_f32_16x16x32_f16 a[216:219], v[88:91], v[28:31], a[216:219]
	v_mfma_f32_16x16x32_f16 a[212:215], v[84:87], v[28:31], a[212:215]
	v_mfma_f32_16x16x32_f16 a[204:207], v[80:83], v[28:31], a[204:207]
	v_mfma_f32_16x16x32_f16 a[172:175], v[172:175], v[12:15], a[172:175]
	v_mfma_f32_16x16x32_f16 a[168:171], v[88:91], v[12:15], a[168:171]
	v_mfma_f32_16x16x32_f16 a[164:167], v[84:87], v[12:15], a[164:167]
	v_mfma_f32_16x16x32_f16 a[160:163], v[80:83], v[12:15], a[160:163]
	v_mfma_f32_16x16x32_f16 a[140:143], v[172:175], v[4:7], a[140:143]
	v_mfma_f32_16x16x32_f16 a[136:139], v[88:91], v[4:7], a[136:139]
	v_mfma_f32_16x16x32_f16 a[132:135], v[84:87], v[4:7], a[132:135]
	v_mfma_f32_16x16x32_f16 a[128:131], v[80:83], v[4:7], a[128:131]
	v_mfma_f32_16x16x32_f16 a[108:111], v[172:175], v[0:3], a[108:111]
	v_mfma_f32_16x16x32_f16 a[104:107], v[88:91], v[0:3], a[104:107]
	v_mfma_f32_16x16x32_f16 a[100:103], v[84:87], v[0:3], a[100:103]
	v_mfma_f32_16x16x32_f16 a[96:99], v[80:83], v[0:3], a[96:99]
	v_mfma_f32_16x16x32_f16 a[76:79], v[172:175], v[8:11], a[76:79]
	v_mfma_f32_16x16x32_f16 a[72:75], v[88:91], v[8:11], a[72:75]
	v_mfma_f32_16x16x32_f16 a[68:71], v[84:87], v[8:11], a[68:71]
	v_mfma_f32_16x16x32_f16 a[64:67], v[80:83], v[8:11], a[64:67]
	v_mfma_f32_16x16x32_f16 a[44:47], v[172:175], v[20:23], a[44:47]
	v_mfma_f32_16x16x32_f16 a[40:43], v[88:91], v[20:23], a[40:43]
	v_mfma_f32_16x16x32_f16 a[36:39], v[84:87], v[20:23], a[36:39]
	v_mfma_f32_16x16x32_f16 a[32:35], v[80:83], v[20:23], a[32:35]
	s_branch .LBB0_2022

; #define LD_AF(dst, ks_) _Pragma("unroll") for (int i = 0; i < 8; ++i) dst[i] = *(const h8*)(sA + i * 16 * G_LD + (ks_) * 32)
; #define LD_BF(dst, ks_, nh_) _Pragma("unroll") for (int i = 0; i < 4; ++i) dst[i] = *(const h8*)(sB + ((nh_) * 4 + i) * 16 * G_LD + (ks_) * 32)
; #define MMA_BLK(afx, bfx, nh_) _Pragma("unroll") for (int mi = 0; mi < 8; ++mi) _Pragma("unroll") for (int ni = 0; ni < 4; ++ni) mfma16_acc(acc[mi][(nh_) * 4 + ni], bfx[ni], afx[mi])
; template <class Epi>
; __device__ __forceinline__ void gemm_run(const GemmArgs g, Epi epi, char* smem) {
;     ...
;     for (int kt = 0; kt < nk; ++kt) {
;       const hf* sA = sbase + (kt & 1) * G_STAGE + (wm * 128 + fr) * G_LD + fqs;
;       const hf* sB = sbase + (kt & 1) * G_STAGE + (256 + wn * 128 + fr) * G_LD + fqs;
;       hf* st = sbase + ((kt + 1) & 1) * G_STAGE;
;       h8 afA[8], afB[8], bfA[4], bfB[4];
;     ...
;       LD_AF(afA, 0); LD_BF(bfA, 0, 0);
;       if (kt + 1 < nk) {
; #pragma unroll
;         for (int i = 0; i < 8; ++i) *(u4*)(st + (lr + 32 * i) * G_LD + lcw) = ra[i];
;       }
;       __builtin_amdgcn_sched_barrier(0);
;       LD_BF(bfB, 0, 1);
;       MMA_BLK(afA, bfA, 0);
;       __builtin_amdgcn_sched_barrier(0);
;       if (kt + 1 < nk) {
; #pragma unroll
;         for (int i = 0; i < 8; ++i) *(u4*)(st + (256 + lr + 32 * i) * G_LD + lcw) = rb[i];
;       }
;       LD_AF(afB, 1); LD_BF(bfA, 1, 0);
;       MMA_BLK(afA, bfB, 1);
.LBB0_2052:
	s_bitcmp1_b32 s19, 0
	s_cselect_b32 s15, 0x12000, 0
	s_add_i32 s15, s15, 16
	v_add3_u32 v106, s15, v96, v105
	v_add3_u32 v64, s15, v94, v105
	ds_read_b128 v[36:39], v106 offset:36864
	ds_read_b128 v[56:59], v64
	ds_read_b128 v[32:35], v106 offset:39168
	ds_read_b128 v[24:27], v106 offset:41472
	ds_read_b128 v[16:19], v106 offset:43776
	ds_read_b128 v[44:47], v64 offset:2304
	ds_read_b128 v[28:31], v64 offset:4608
	ds_read_b128 v[12:15], v64 offset:6912
	ds_read_b128 v[4:7], v64 offset:9216
	ds_read_b128 v[0:3], v64 offset:11520
	ds_read_b128 v[8:11], v64 offset:13824
	ds_read_b128 v[20:23], v64 offset:16128
	s_mov_b32 s14, s19
	s_add_i32 s19, s19, 1
	s_bitcmp1_b32 s19, 0
	s_cselect_b32 s52, 0x12000, 0
	v_add_u32_e32 v40, s52, v93
	v_add_u32_e32 v41, v40, v98
	ds_read_b128 v[172:175], v106 offset:46080
	ds_read_b128 v[88:91], v106 offset:48384
	ds_read_b128 v[84:87], v106 offset:50688
	ds_read_b128 v[80:83], v106 offset:52992
	s_waitcnt lgkmcnt(14)
	v_mfma_f32_16x16x32_f16 a[120:123], v[36:39], v[56:59], a[120:123]
	s_waitcnt lgkmcnt(13)
	v_mfma_f32_16x16x32_f16 a[116:119], v[32:35], v[56:59], a[116:119]
	s_waitcnt vmcnt(15)
	ds_write_b128 v41, v[108:111]
	s_waitcnt lgkmcnt(13)
	v_mfma_f32_16x16x32_f16 a[112:115], v[24:27], v[56:59], a[112:115]
	s_waitcnt lgkmcnt(12)
	v_mfma_f32_16x16x32_f16 a[160:163], v[16:19], v[56:59], a[160:163]
	s_waitcnt vmcnt(14)
	ds_write_b128 v41, v[112:115] offset:4608
	s_waitcnt lgkmcnt(12)
	v_mfma_f32_16x16x32_f16 a[152:155], v[36:39], v[44:47], a[152:155]
	v_mfma_f32_16x16x32_f16 a[148:151], v[32:35], v[44:47], a[148:151]
	s_waitcnt vmcnt(11)
	ds_write_b128 v41, v[120:123] offset:9216
	v_mfma_f32_16x16x32_f16 a[144:147], v[24:27], v[44:47], a[144:147]
	v_mfma_f32_16x16x32_f16 a[136:139], v[16:19], v[44:47], a[136:139]
	s_waitcnt vmcnt(10)
	ds_write_b128 v41, v[128:131] offset:13824
	s_waitcnt lgkmcnt(13)
	v_mfma_f32_16x16x32_f16 a[108:111], v[36:39], v[28:31], a[108:111]
	v_mfma_f32_16x16x32_f16 a[104:107], v[32:35], v[28:31], a[104:107]
	s_waitcnt vmcnt(7)
	ds_write_b128 v41, v[136:139] offset:18432
	v_mfma_f32_16x16x32_f16 a[100:103], v[24:27], v[28:31], a[100:103]
	v_mfma_f32_16x16x32_f16 a[92:95], v[16:19], v[28:31], a[92:95]
	s_waitcnt vmcnt(6)
	ds_write_b128 v41, v[144:147] offset:23040
	s_waitcnt lgkmcnt(14)
	v_mfma_f32_16x16x32_f16 a[76:79], v[36:39], v[12:15], a[76:79]
	v_mfma_f32_16x16x32_f16 a[72:75], v[32:35], v[12:15], a[72:75]
	s_waitcnt vmcnt(3)
	ds_write_b128 v41, v[148:151] offset:27648
	v_mfma_f32_16x16x32_f16 a[68:71], v[24:27], v[12:15], a[68:71]
	v_mfma_f32_16x16x32_f16 a[64:67], v[16:19], v[12:15], a[64:67]
	s_waitcnt vmcnt(2)
	ds_write_b128 v41, v[156:159] offset:32256
	s_waitcnt lgkmcnt(14)
	v_mfma_f32_16x16x32_f16 a[60:63], v[36:39], v[4:7], a[60:63]
	v_mfma_f32_16x16x32_f16 a[56:59], v[32:35], v[4:7], a[56:59]
	s_waitcnt vmcnt(7)
	ds_write_b128 v41, v[116:119] offset:36864
	v_mfma_f32_16x16x32_f16 a[52:55], v[24:27], v[4:7], a[52:55]
	v_mfma_f32_16x16x32_f16 a[48:51], v[16:19], v[4:7], a[48:51]
	s_waitcnt vmcnt(6)
	ds_write_b128 v41, v[124:127] offset:41472
	s_waitcnt lgkmcnt(14)
	v_mfma_f32_16x16x32_f16 a[44:47], v[36:39], v[0:3], a[44:47]
	v_mfma_f32_16x16x32_f16 a[40:43], v[32:35], v[0:3], a[40:43]
	s_waitcnt vmcnt(5)
	ds_write_b128 v41, v[132:135] offset:46080
	v_mfma_f32_16x16x32_f16 a[36:39], v[24:27], v[0:3], a[36:39]
	v_mfma_f32_16x16x32_f16 a[32:35], v[16:19], v[0:3], a[32:35]
	s_waitcnt vmcnt(4)
	ds_write_b128 v41, v[140:143] offset:50688
	s_waitcnt lgkmcnt(14)
	v_mfma_f32_16x16x32_f16 a[28:31], v[36:39], v[8:11], a[28:31]
	v_mfma_f32_16x16x32_f16 a[24:27], v[32:35], v[8:11], a[24:27]
	s_waitcnt vmcnt(3)
	ds_write_b128 v41, v[152:155] offset:55296
	v_mfma_f32_16x16x32_f16 a[20:23], v[24:27], v[8:11], a[20:23]
	v_mfma_f32_16x16x32_f16 a[16:19], v[16:19], v[8:11], a[16:19]
	s_waitcnt vmcnt(2)
	ds_write_b128 v41, v[160:163] offset:59904
	s_waitcnt lgkmcnt(14)
	v_mfma_f32_16x16x32_f16 a[12:15], v[36:39], v[20:23], a[12:15]
	v_mfma_f32_16x16x32_f16 a[8:11], v[32:35], v[20:23], a[8:11]
	s_waitcnt vmcnt(1)
	ds_write_b128 v41, v[164:167] offset:64512
	v_mfma_f32_16x16x32_f16 a[4:7], v[24:27], v[20:23], a[4:7]
	v_mfma_f32_16x16x32_f16 a[0:3], v[16:19], v[20:23], a[0:3]
	v_add_u32_e32 v16, v40, v99
	s_waitcnt vmcnt(0)
	ds_write_b128 v16, v[168:171]
	ds_read_b128 v[60:63], v64 offset:64
	ds_read_b128 v[52:55], v64 offset:2368
	ds_read_b128 v[48:51], v64 offset:4672
	ds_read_b128 v[40:43], v64 offset:6976
	ds_read_b128 v[36:39], v64 offset:9280
	ds_read_b128 v[32:35], v64 offset:11584
	ds_read_b128 v[24:27], v64 offset:13888
	ds_read_b128 v[16:19], v64 offset:16192
	ds_read_b128 v[64:67], v106 offset:36928
	ds_read_b128 v[68:71], v106 offset:39232
	ds_read_b128 v[72:75], v106 offset:41536
	ds_read_b128 v[76:79], v106 offset:43840
	s_cmp_gt_u32 s14, 29
	s_cbranch_scc1 .Lgw15_nl
; #define MMA_BLK(afx, bfx, nh_) _Pragma("unroll") for (int mi = 0; mi < 8; ++mi) _Pragma("unroll") for (int ni = 0; ni < 4; ++ni) mfma16_acc(acc[mi][(nh_) * 4 + ni], bfx[ni], afx[mi])
; template <class Epi>
; __device__ __forceinline__ void gemm_run(const GemmArgs g, Epi epi, char* smem) {
;     ...
;       MMA_BLK(afA, bfB, 1);
;       __builtin_amdgcn_sched_barrier(0);
;       if (kt + 2 < nk) {
;         const int ko = (kt + 2) * 64;
; #pragma unroll
;         for (int i = 0; i < 8; ++i) { ra[i] = __builtin_amdgcn_raw_buffer_load_b128(Ars, aoff, i * astep + ko * 2, 0); rb[i] = __builtin_amdgcn_raw_buffer_load_b128(Brs, boff, i * bstep + ko * 2, 0); }
;       }
	s_waitcnt lgkmcnt(14)
	v_mfma_f32_16x16x32_f16 a[252:255], v[172:175], v[56:59], a[252:255]
	s_waitcnt lgkmcnt(14)
	v_mfma_f32_16x16x32_f16 a[248:251], v[88:91], v[56:59], a[248:251]
	s_waitcnt lgkmcnt(14)
	v_mfma_f32_16x16x32_f16 a[244:247], v[84:87], v[56:59], a[244:247]
	s_add_i32 s52, s17, 0xfff20000
	s_waitcnt lgkmcnt(14)
	v_mfma_f32_16x16x32_f16 a[240:243], v[80:83], v[56:59], a[240:243]
	s_mov_b32 s14, s10
	v_mfma_f32_16x16x32_f16 a[236:239], v[172:175], v[44:47], a[236:239]
	s_mov_b32 s15, s11
	v_mfma_f32_16x16x32_f16 a[232:235], v[88:91], v[44:47], a[232:235]
	s_add_i32 s53, s17, 0xfff40000
	v_mfma_f32_16x16x32_f16 a[228:231], v[84:87], v[44:47], a[228:231]
	buffer_load_dwordx4 v[108:111], v92, s[8:11], s52 offen
	v_mfma_f32_16x16x32_f16 a[224:227], v[80:83], v[44:47], a[224:227]
	buffer_load_dwordx4 v[112:115], v92, s[8:11], s53 offen
	v_mfma_f32_16x16x32_f16 a[220:223], v[172:175], v[28:31], a[220:223]
	buffer_load_dwordx4 v[116:119], v92, s[12:15], s52 offen
	v_mfma_f32_16x16x32_f16 a[216:219], v[88:91], v[28:31], a[216:219]
	buffer_load_dwordx4 v[124:127], v92, s[12:15], s53 offen
	v_mfma_f32_16x16x32_f16 a[212:215], v[84:87], v[28:31], a[212:215]
	s_add_i32 s52, s17, 0xfff60000
	v_mfma_f32_16x16x32_f16 a[208:211], v[80:83], v[28:31], a[208:211]
	s_add_i32 s53, s17, 0xfff80000
	v_mfma_f32_16x16x32_f16 a[204:207], v[172:175], v[12:15], a[204:207]
	buffer_load_dwordx4 v[120:123], v92, s[8:11], s52 offen
	v_mfma_f32_16x16x32_f16 a[200:203], v[88:91], v[12:15], a[200:203]
	buffer_load_dwordx4 v[128:131], v92, s[8:11], s53 offen
	v_mfma_f32_16x16x32_f16 a[196:199], v[84:87], v[12:15], a[196:199]
	buffer_load_dwordx4 v[132:135], v92, s[12:15], s52 offen
	v_mfma_f32_16x16x32_f16 a[192:195], v[80:83], v[12:15], a[192:195]
	buffer_load_dwordx4 v[140:143], v92, s[12:15], s53 offen
	v_mfma_f32_16x16x32_f16 a[188:191], v[172:175], v[4:7], a[188:191]
	s_add_i32 s52, s17, 0xfffa0000
	v_mfma_f32_16x16x32_f16 a[184:187], v[88:91], v[4:7], a[184:187]
	s_add_i32 s53, s17, 0xfffc0000
	v_mfma_f32_16x16x32_f16 a[180:183], v[84:87], v[4:7], a[180:183]
	buffer_load_dwordx4 v[136:139], v92, s[8:11], s52 offen
	v_mfma_f32_16x16x32_f16 a[176:179], v[80:83], v[4:7], a[176:179]
	buffer_load_dwordx4 v[144:147], v92, s[8:11], s53 offen
	v_mfma_f32_16x16x32_f16 a[172:175], v[172:175], v[0:3], a[172:175]
	buffer_load_dwordx4 v[152:155], v92, s[12:15], s52 offen
	v_mfma_f32_16x16x32_f16 a[168:171], v[88:91], v[0:3], a[168:171]
	buffer_load_dwordx4 v[160:163], v92, s[12:15], s53 offen
	v_mfma_f32_16x16x32_f16 a[164:167], v[84:87], v[0:3], a[164:167]
	s_add_i32 s52, s17, 0xfffe0000
	v_mfma_f32_16x16x32_f16 a[156:159], v[80:83], v[0:3], a[156:159]
	buffer_load_dwordx4 v[148:151], v92, s[8:11], s52 offen
	v_mfma_f32_16x16x32_f16 a[140:143], v[172:175], v[8:11], a[140:143]
	buffer_load_dwordx4 v[156:159], v92, s[8:11], s17 offen
	v_mfma_f32_16x16x32_f16 a[132:135], v[88:91], v[8:11], a[132:135]
	buffer_load_dwordx4 v[164:167], v92, s[12:15], s52 offen
	v_mfma_f32_16x16x32_f16 a[128:131], v[84:87], v[8:11], a[128:131]
	buffer_load_dwordx4 v[168:171], v92, s[12:15], s17 offen
	v_mfma_f32_16x16x32_f16 a[124:127], v[80:83], v[8:11], a[124:127]
	v_mfma_f32_16x16x32_f16 a[96:99], v[172:175], v[20:23], a[96:99]
	v_mfma_f32_16x16x32_f16 a[88:91], v[88:91], v[20:23], a[88:91]
	v_mfma_f32_16x16x32_f16 a[84:87], v[84:87], v[20:23], a[84:87]
	v_mfma_f32_16x16x32_f16 a[80:83], v[80:83], v[20:23], a[80:83]
	s_branch .LBB0_2051
.Lgw15_nl:
	s_waitcnt lgkmcnt(14)
	v_mfma_f32_16x16x32_f16 a[252:255], v[172:175], v[56:59], a[252:255]
	s_waitcnt lgkmcnt(14)
	v_mfma_f32_16x16x32_f16 a[248:251], v[88:91], v[56:59], a[248:251]
	s_waitcnt lgkmcnt(14)
	v_mfma_f32_16x16x32_f16 a[244:247], v[84:87], v[56:59], a[244:247]
	s_waitcnt lgkmcnt(14)
	v_mfma_f32_16x16x32_f16 a[240:243], v[80:83], v[56:59], a[240:243]
	v_mfma_f32_16x16x32_f16 a[236:239], v[172:175], v[44:47], a[236:239]
	v_mfma_f32_16x16x32_f16 a[232:235], v[88:91], v[44:47], a[232:235]
	v_mfma_f32_16x16x32_f16 a[228:231], v[84:87], v[44:47], a[228:231]
	v_mfma_f32_16x16x32_f16 a[224:227], v[80:83], v[44:47], a[224:227]
	v_mfma_f32_16x16x32_f16 a[220:223], v[172:175], v[28:31], a[220:223]
	v_mfma_f32_16x16x32_f16 a[216:219], v[88:91], v[28:31], a[216:219]
	v_mfma_f32_16x16x32_f16 a[212:215], v[84:87], v[28:31], a[212:215]
	v_mfma_f32_16x16x32_f16 a[208:211], v[80:83], v[28:31], a[208:211]
	v_mfma_f32_16x16x32_f16 a[204:207], v[172:175], v[12:15], a[204:207]
	v_mfma_f32_16x16x32_f16 a[200:203], v[88:91], v[12:15], a[200:203]
	v_mfma_f32_16x16x32_f16 a[196:199], v[84:87], v[12:15], a[196:199]
	v_mfma_f32_16x16x32_f16 a[192:195], v[80:83], v[12:15], a[192:195]
	v_mfma_f32_16x16x32_f16 a[188:191], v[172:175], v[4:7], a[188:191]
	v_mfma_f32_16x16x32_f16 a[184:187], v[88:91], v[4:7], a[184:187]
	v_mfma_f32_16x16x32_f16 a[180:183], v[84:87], v[4:7], a[180:183]
	v_mfma_f32_16x16x32_f16 a[176:179], v[80:83], v[4:7], a[176:179]
	v_mfma_f32_16x16x32_f16 a[172:175], v[172:175], v[0:3], a[172:175]
	v_mfma_f32_16x16x32_f16 a[168:171], v[88:91], v[0:3], a[168:171]
	v_mfma_f32_16x16x32_f16 a[164:167], v[84:87], v[0:3], a[164:167]
	v_mfma_f32_16x16x32_f16 a[156:159], v[80:83], v[0:3], a[156:159]
	v_mfma_f32_16x16x32_f16 a[140:143], v[172:175], v[8:11], a[140:143]
	v_mfma_f32_16x16x32_f16 a[132:135], v[88:91], v[8:11], a[132:135]
	v_mfma_f32_16x16x32_f16 a[128:131], v[84:87], v[8:11], a[128:131]
	v_mfma_f32_16x16x32_f16 a[124:127], v[80:83], v[8:11], a[124:127]
	v_mfma_f32_16x16x32_f16 a[96:99], v[172:175], v[20:23], a[96:99]
	v_mfma_f32_16x16x32_f16 a[88:91], v[88:91], v[20:23], a[88:91]
	v_mfma_f32_16x16x32_f16 a[84:87], v[84:87], v[20:23], a[84:87]
	v_mfma_f32_16x16x32_f16 a[80:83], v[80:83], v[20:23], a[80:83]
	s_branch .LBB0_2051

; #define LD_AF(dst, ks_) _Pragma("unroll") for (int i = 0; i < 8; ++i) dst[i] = *(const h8*)(sA + i * 16 * G_LD + (ks_) * 32)
; #define LD_BF(dst, ks_, nh_) _Pragma("unroll") for (int i = 0; i < 4; ++i) dst[i] = *(const h8*)(sB + ((nh_) * 4 + i) * 16 * G_LD + (ks_) * 32)
; #define MMA_BLK(afx, bfx, nh_) _Pragma("unroll") for (int mi = 0; mi < 8; ++mi) _Pragma("unroll") for (int ni = 0; ni < 4; ++ni) mfma16_acc(acc[mi][(nh_) * 4 + ni], bfx[ni], afx[mi])
; template <class Epi>
; __device__ __forceinline__ void gemm_run(const GemmArgs g, Epi epi, char* smem) {
;     ...
;     for (int kt = 0; kt < nk; ++kt) {
;       const hf* sA = sbase + (kt & 1) * G_STAGE + (wm * 128 + fr) * G_LD + fqs;
;       const hf* sB = sbase + (kt & 1) * G_STAGE + (256 + wn * 128 + fr) * G_LD + fqs;
;       hf* st = sbase + ((kt + 1) & 1) * G_STAGE;
;       h8 afA[8], afB[8], bfA[4], bfB[4];
;     ...
;       LD_AF(afA, 0); LD_BF(bfA, 0, 0);
;       if (kt + 1 < nk) {
; #pragma unroll
;         for (int i = 0; i < 8; ++i) *(u4*)(st + (lr + 32 * i) * G_LD + lcw) = ra[i];
;       }
;       __builtin_amdgcn_sched_barrier(0);
;       LD_BF(bfB, 0, 1);
;       MMA_BLK(afA, bfA, 0);
;       __builtin_amdgcn_sched_barrier(0);
;       if (kt + 1 < nk) {
; #pragma unroll
;         for (int i = 0; i < 8; ++i) *(u4*)(st + (256 + lr + 32 * i) * G_LD + lcw) = rb[i];
;       }
;       LD_AF(afB, 1); LD_BF(bfA, 1, 0);
;       MMA_BLK(afA, bfB, 1);
.LBB0_2103:
	s_bitcmp1_b32 s55, 0
	s_cselect_b32 s15, 0x12000, 0
	s_add_i32 s15, s15, 16
	v_add3_u32 v92, s15, v132, v139
	v_add3_u32 v64, s15, v131, v139
	ds_read_b128 v[36:39], v92 offset:36864
	ds_read_b128 v[56:59], v64
	ds_read_b128 v[32:35], v92 offset:39168
	ds_read_b128 v[24:27], v92 offset:41472
	ds_read_b128 v[16:19], v92 offset:43776
	ds_read_b128 v[44:47], v64 offset:2304
	ds_read_b128 v[28:31], v64 offset:4608
	ds_read_b128 v[12:15], v64 offset:6912
	ds_read_b128 v[4:7], v64 offset:9216
	ds_read_b128 v[0:3], v64 offset:11520
	ds_read_b128 v[8:11], v64 offset:13824
	ds_read_b128 v[20:23], v64 offset:16128
	s_mov_b32 s14, s55
	s_add_i32 s55, s55, 1
	s_bitcmp1_b32 s55, 0
	s_cselect_b32 s58, 0x12000, 0
	v_add_u32_e32 v40, s58, v129
	v_add_u32_e32 v41, v40, v134
	ds_read_b128 v[172:175], v92 offset:46080
	ds_read_b128 v[88:91], v92 offset:48384
	ds_read_b128 v[84:87], v92 offset:50688
	ds_read_b128 v[80:83], v92 offset:52992
	s_waitcnt lgkmcnt(14)
	v_mfma_f32_16x16x32_f16 a[208:211], v[36:39], v[56:59], a[208:211]
	s_waitcnt lgkmcnt(13)
	v_mfma_f32_16x16x32_f16 a[200:203], v[32:35], v[56:59], a[200:203]
	s_waitcnt vmcnt(15)
	ds_write_b128 v41, v[94:97]
	s_waitcnt lgkmcnt(13)
	v_mfma_f32_16x16x32_f16 a[196:199], v[24:27], v[56:59], a[196:199]
	s_waitcnt lgkmcnt(12)
	v_mfma_f32_16x16x32_f16 a[192:195], v[16:19], v[56:59], a[192:195]
	s_waitcnt vmcnt(14)
	ds_write_b128 v41, v[98:101] offset:4608
	s_waitcnt lgkmcnt(12)
	v_mfma_f32_16x16x32_f16 a[188:191], v[36:39], v[44:47], a[188:191]
	v_mfma_f32_16x16x32_f16 a[184:187], v[32:35], v[44:47], a[184:187]
	s_waitcnt vmcnt(11)
	ds_write_b128 v41, v[106:109] offset:9216
	v_mfma_f32_16x16x32_f16 a[180:183], v[24:27], v[44:47], a[180:183]
	v_mfma_f32_16x16x32_f16 a[176:179], v[16:19], v[44:47], a[176:179]
	s_waitcnt vmcnt(10)
	ds_write_b128 v41, v[114:117] offset:13824
	s_waitcnt lgkmcnt(13)
	v_mfma_f32_16x16x32_f16 a[156:159], v[36:39], v[28:31], a[156:159]
	v_mfma_f32_16x16x32_f16 a[152:155], v[32:35], v[28:31], a[152:155]
	s_waitcnt vmcnt(7)
	ds_write_b128 v41, v[122:125] offset:18432
	v_mfma_f32_16x16x32_f16 a[148:151], v[24:27], v[28:31], a[148:151]
	v_mfma_f32_16x16x32_f16 a[144:147], v[16:19], v[28:31], a[144:147]
	s_waitcnt vmcnt(6)
	ds_write_b128 v41, v[144:147] offset:23040
	s_waitcnt lgkmcnt(14)
	v_mfma_f32_16x16x32_f16 a[124:127], v[36:39], v[12:15], a[124:127]
	v_mfma_f32_16x16x32_f16 a[120:123], v[32:35], v[12:15], a[120:123]
	s_waitcnt vmcnt(3)
	ds_write_b128 v41, v[148:151] offset:27648
	v_mfma_f32_16x16x32_f16 a[116:119], v[24:27], v[12:15], a[116:119]
	v_mfma_f32_16x16x32_f16 a[112:115], v[16:19], v[12:15], a[112:115]
	s_waitcnt vmcnt(2)
	ds_write_b128 v41, v[156:159] offset:32256
	s_waitcnt lgkmcnt(14)
	v_mfma_f32_16x16x32_f16 a[92:95], v[36:39], v[4:7], a[92:95]
	v_mfma_f32_16x16x32_f16 a[88:91], v[32:35], v[4:7], a[88:91]
	s_waitcnt vmcnt(7)
	ds_write_b128 v41, v[102:105] offset:36864
	v_mfma_f32_16x16x32_f16 a[84:87], v[24:27], v[4:7], a[84:87]
	v_mfma_f32_16x16x32_f16 a[80:83], v[16:19], v[4:7], a[80:83]
	s_waitcnt vmcnt(6)
	ds_write_b128 v41, v[110:113] offset:41472
	s_waitcnt lgkmcnt(14)
	v_mfma_f32_16x16x32_f16 a[60:63], v[36:39], v[0:3], a[60:63]
	v_mfma_f32_16x16x32_f16 a[56:59], v[32:35], v[0:3], a[56:59]
	s_waitcnt vmcnt(5)
	ds_write_b128 v41, v[118:121] offset:46080
	v_mfma_f32_16x16x32_f16 a[52:55], v[24:27], v[0:3], a[52:55]
	v_mfma_f32_16x16x32_f16 a[48:51], v[16:19], v[0:3], a[48:51]
	s_waitcnt vmcnt(4)
	ds_write_b128 v41, v[140:143] offset:50688
	s_waitcnt lgkmcnt(14)
	v_mfma_f32_16x16x32_f16 a[28:31], v[36:39], v[8:11], a[28:31]
	v_mfma_f32_16x16x32_f16 a[24:27], v[32:35], v[8:11], a[24:27]
	s_waitcnt vmcnt(3)
	ds_write_b128 v41, v[152:155] offset:55296
	v_mfma_f32_16x16x32_f16 a[20:23], v[24:27], v[8:11], a[20:23]
	v_mfma_f32_16x16x32_f16 a[16:19], v[16:19], v[8:11], a[16:19]
	s_waitcnt vmcnt(2)
	ds_write_b128 v41, v[160:163] offset:59904
	s_waitcnt lgkmcnt(14)
	v_mfma_f32_16x16x32_f16 a[12:15], v[36:39], v[20:23], a[12:15]
	v_mfma_f32_16x16x32_f16 a[8:11], v[32:35], v[20:23], a[8:11]
	s_waitcnt vmcnt(1)
	ds_write_b128 v41, v[164:167] offset:64512
	v_mfma_f32_16x16x32_f16 a[4:7], v[24:27], v[20:23], a[4:7]
	v_mfma_f32_16x16x32_f16 a[0:3], v[16:19], v[20:23], a[0:3]
	v_add_u32_e32 v16, v40, v135
	s_waitcnt vmcnt(0)
	ds_write_b128 v16, v[168:171]
	ds_read_b128 v[60:63], v64 offset:64
	ds_read_b128 v[52:55], v64 offset:2368
	ds_read_b128 v[48:51], v64 offset:4672
	ds_read_b128 v[40:43], v64 offset:6976
	ds_read_b128 v[36:39], v64 offset:9280
	ds_read_b128 v[32:35], v64 offset:11584
	ds_read_b128 v[24:27], v64 offset:13888
	ds_read_b128 v[16:19], v64 offset:16192
	ds_read_b128 v[64:67], v92 offset:36928
	ds_read_b128 v[68:71], v92 offset:39232
	ds_read_b128 v[72:75], v92 offset:41536
	ds_read_b128 v[76:79], v92 offset:43840
	s_cmpk_gt_u32 s14, 0x55
	s_cbranch_scc1 .Lgw16_nl
; #define MMA_BLK(afx, bfx, nh_) _Pragma("unroll") for (int mi = 0; mi < 8; ++mi) _Pragma("unroll") for (int ni = 0; ni < 4; ++ni) mfma16_acc(acc[mi][(nh_) * 4 + ni], bfx[ni], afx[mi])
; template <class Epi>
; __device__ __forceinline__ void gemm_run(const GemmArgs g, Epi epi, char* smem) {
;     ...
;       MMA_BLK(afA, bfB, 1);
;       __builtin_amdgcn_sched_barrier(0);
;       if (kt + 2 < nk) {
;         const int ko = (kt + 2) * 64;
; #pragma unroll
;         for (int i = 0; i < 8; ++i) { ra[i] = __builtin_amdgcn_raw_buffer_load_b128(Ars, aoff, i * astep + ko * 2, 0); rb[i] = __builtin_amdgcn_raw_buffer_load_b128(Brs, boff, i * bstep + ko * 2, 0); }
;       }
	s_waitcnt lgkmcnt(14)
	v_mfma_f32_16x16x32_f16 a[240:243], v[172:175], v[56:59], a[240:243]
	s_waitcnt lgkmcnt(14)
	v_mfma_f32_16x16x32_f16 a[252:255], v[88:91], v[56:59], a[252:255]
	s_waitcnt lgkmcnt(14)
	v_mfma_f32_16x16x32_f16 a[248:251], v[84:87], v[56:59], a[248:251]
	s_add_i32 s58, s54, 0xffd98000
	s_waitcnt lgkmcnt(14)
	v_mfma_f32_16x16x32_f16 a[244:247], v[80:83], v[56:59], a[244:247]
	s_mov_b32 s14, s10
	v_mfma_f32_16x16x32_f16 a[236:239], v[172:175], v[44:47], a[236:239]
	s_mov_b32 s15, s11
	v_mfma_f32_16x16x32_f16 a[232:235], v[88:91], v[44:47], a[232:235]
	s_add_i32 s59, s54, 0xffdf0000
	v_mfma_f32_16x16x32_f16 a[228:231], v[84:87], v[44:47], a[228:231]
	buffer_load_dwordx4 v[94:97], v128, s[8:11], s58 offen
	v_mfma_f32_16x16x32_f16 a[224:227], v[80:83], v[44:47], a[224:227]
	buffer_load_dwordx4 v[98:101], v128, s[8:11], s59 offen
	v_mfma_f32_16x16x32_f16 a[220:223], v[172:175], v[28:31], a[220:223]
	buffer_load_dwordx4 v[102:105], v128, s[12:15], s58 offen
	v_mfma_f32_16x16x32_f16 a[216:219], v[88:91], v[28:31], a[216:219]
	buffer_load_dwordx4 v[110:113], v128, s[12:15], s59 offen
	v_mfma_f32_16x16x32_f16 a[212:215], v[84:87], v[28:31], a[212:215]
	s_add_i32 s58, s54, 0xffe48000
	v_mfma_f32_16x16x32_f16 a[204:207], v[80:83], v[28:31], a[204:207]
	s_add_i32 s59, s54, 0xffea0000
	v_mfma_f32_16x16x32_f16 a[172:175], v[172:175], v[12:15], a[172:175]
	buffer_load_dwordx4 v[106:109], v128, s[8:11], s58 offen
	v_mfma_f32_16x16x32_f16 a[168:171], v[88:91], v[12:15], a[168:171]
	buffer_load_dwordx4 v[114:117], v128, s[8:11], s59 offen
	v_mfma_f32_16x16x32_f16 a[164:167], v[84:87], v[12:15], a[164:167]
	buffer_load_dwordx4 v[118:121], v128, s[12:15], s58 offen
	v_mfma_f32_16x16x32_f16 a[160:163], v[80:83], v[12:15], a[160:163]
	buffer_load_dwordx4 v[140:143], v128, s[12:15], s59 offen
	v_mfma_f32_16x16x32_f16 a[140:143], v[172:175], v[4:7], a[140:143]
	s_add_i32 s58, s54, 0xffef8000
	v_mfma_f32_16x16x32_f16 a[136:139], v[88:91], v[4:7], a[136:139]
	s_add_i32 s59, s54, 0xfff50000
	v_mfma_f32_16x16x32_f16 a[132:135], v[84:87], v[4:7], a[132:135]
	buffer_load_dwordx4 v[122:125], v128, s[8:11], s58 offen
	v_mfma_f32_16x16x32_f16 a[128:131], v[80:83], v[4:7], a[128:131]
	buffer_load_dwordx4 v[144:147], v128, s[8:11], s59 offen
	v_mfma_f32_16x16x32_f16 a[108:111], v[172:175], v[0:3], a[108:111]
	buffer_load_dwordx4 v[152:155], v128, s[12:15], s58 offen
	v_mfma_f32_16x16x32_f16 a[104:107], v[88:91], v[0:3], a[104:107]
	buffer_load_dwordx4 v[160:163], v128, s[12:15], s59 offen
	v_mfma_f32_16x16x32_f16 a[100:103], v[84:87], v[0:3], a[100:103]
	s_add_i32 s58, s54, 0xfffa8000
	v_mfma_f32_16x16x32_f16 a[96:99], v[80:83], v[0:3], a[96:99]
	buffer_load_dwordx4 v[148:151], v128, s[8:11], s58 offen
	v_mfma_f32_16x16x32_f16 a[76:79], v[172:175], v[8:11], a[76:79]
	buffer_load_dwordx4 v[156:159], v128, s[8:11], s54 offen
	v_mfma_f32_16x16x32_f16 a[72:75], v[88:91], v[8:11], a[72:75]
	buffer_load_dwordx4 v[164:167], v128, s[12:15], s58 offen
	v_mfma_f32_16x16x32_f16 a[68:71], v[84:87], v[8:11], a[68:71]
	buffer_load_dwordx4 v[168:171], v128, s[12:15], s54 offen
	v_mfma_f32_16x16x32_f16 a[64:67], v[80:83], v[8:11], a[64:67]
	v_mfma_f32_16x16x32_f16 a[44:47], v[172:175], v[20:23], a[44:47]
	v_mfma_f32_16x16x32_f16 a[40:43], v[88:91], v[20:23], a[40:43]
	v_mfma_f32_16x16x32_f16 a[36:39], v[84:87], v[20:23], a[36:39]
	v_mfma_f32_16x16x32_f16 a[32:35], v[80:83], v[20:23], a[32:35]
	s_branch .LBB0_2102

; #define LD_AF(dst, ks_) _Pragma("unroll") for (int i = 0; i < 8; ++i) dst[i] = *(const h8*)(sA + i * 16 * G_LD + (ks_) * 32)
; #define LD_BF(dst, ks_, nh_) _Pragma("unroll") for (int i = 0; i < 4; ++i) dst[i] = *(const h8*)(sB + ((nh_) * 4 + i) * 16 * G_LD + (ks_) * 32)
; #define MMA_BLK(afx, bfx, nh_) _Pragma("unroll") for (int mi = 0; mi < 8; ++mi) _Pragma("unroll") for (int ni = 0; ni < 4; ++ni) mfma16_acc(acc[mi][(nh_) * 4 + ni], bfx[ni], afx[mi])
; template <class Epi>
; __device__ __forceinline__ void gemm_run(const GemmArgs g, Epi epi, char* smem) {
;     ...
;       const hf* sA = sbase + (kt & 1) * G_STAGE + (wm * 128 + fr) * G_LD + fqs;
;       const hf* sB = sbase + (kt & 1) * G_STAGE + (256 + wn * 128 + fr) * G_LD + fqs;
;       hf* st = sbase + ((kt + 1) & 1) * G_STAGE;
;       h8 afA[8], afB[8], bfA[4], bfB[4];
;     ...
;       LD_AF(afA, 0); LD_BF(bfA, 0, 0);
;       if (kt + 1 < nk) {
; #pragma unroll
;         for (int i = 0; i < 8; ++i) *(u4*)(st + (lr + 32 * i) * G_LD + lcw) = ra[i];
;       }
;       __builtin_amdgcn_sched_barrier(0);
;       LD_BF(bfB, 0, 1);
;       MMA_BLK(afA, bfA, 0);
;       __builtin_amdgcn_sched_barrier(0);
;       if (kt + 1 < nk) {
; #pragma unroll
;         for (int i = 0; i < 8; ++i) *(u4*)(st + (256 + lr + 32 * i) * G_LD + lcw) = rb[i];
;       }
;       LD_AF(afB, 1); LD_BF(bfA, 1, 0);
.LBB0_2109:
	s_bitcmp1_b32 s37, 0
	s_cselect_b32 s15, 0x12000, 0
	s_add_i32 s15, s15, 16
	v_add3_u32 v106, s15, v96, v105
	v_add3_u32 v64, s15, v94, v105
	ds_read_b128 v[36:39], v106 offset:36864
	ds_read_b128 v[56:59], v64
	ds_read_b128 v[32:35], v106 offset:39168
	ds_read_b128 v[24:27], v106 offset:41472
	ds_read_b128 v[16:19], v106 offset:43776
	ds_read_b128 v[44:47], v64 offset:2304
	ds_read_b128 v[28:31], v64 offset:4608
	ds_read_b128 v[12:15], v64 offset:6912
	ds_read_b128 v[4:7], v64 offset:9216
	ds_read_b128 v[0:3], v64 offset:11520
	ds_read_b128 v[8:11], v64 offset:13824
	ds_read_b128 v[20:23], v64 offset:16128
	s_mov_b32 s14, s37
	s_add_i32 s37, s37, 1
	s_bitcmp1_b32 s37, 0
	s_cselect_b32 s59, 0x12000, 0
	v_add_u32_e32 v40, s59, v93
	v_add_u32_e32 v41, v40, v98
	ds_read_b128 v[172:175], v106 offset:46080
	ds_read_b128 v[88:91], v106 offset:48384
	ds_read_b128 v[84:87], v106 offset:50688
	ds_read_b128 v[80:83], v106 offset:52992
	s_waitcnt lgkmcnt(14)
	v_mfma_f32_16x16x32_f16 a[120:123], v[36:39], v[56:59], a[120:123]
	s_waitcnt lgkmcnt(13)
	v_mfma_f32_16x16x32_f16 a[116:119], v[32:35], v[56:59], a[116:119]
	s_waitcnt vmcnt(15)
	ds_write_b128 v41, v[108:111]
	s_waitcnt lgkmcnt(13)
	v_mfma_f32_16x16x32_f16 a[112:115], v[24:27], v[56:59], a[112:115]
	s_waitcnt lgkmcnt(12)
	v_mfma_f32_16x16x32_f16 a[160:163], v[16:19], v[56:59], a[160:163]
	s_waitcnt vmcnt(14)
	ds_write_b128 v41, v[112:115] offset:4608
	s_waitcnt lgkmcnt(12)
	v_mfma_f32_16x16x32_f16 a[152:155], v[36:39], v[44:47], a[152:155]
	v_mfma_f32_16x16x32_f16 a[148:151], v[32:35], v[44:47], a[148:151]
	s_waitcnt vmcnt(11)
	ds_write_b128 v41, v[120:123] offset:9216
	v_mfma_f32_16x16x32_f16 a[144:147], v[24:27], v[44:47], a[144:147]
	v_mfma_f32_16x16x32_f16 a[136:139], v[16:19], v[44:47], a[136:139]
	s_waitcnt vmcnt(10)
	ds_write_b128 v41, v[128:131] offset:13824
	s_waitcnt lgkmcnt(13)
	v_mfma_f32_16x16x32_f16 a[108:111], v[36:39], v[28:31], a[108:111]
	v_mfma_f32_16x16x32_f16 a[104:107], v[32:35], v[28:31], a[104:107]
	s_waitcnt vmcnt(7)
	ds_write_b128 v41, v[136:139] offset:18432
	v_mfma_f32_16x16x32_f16 a[100:103], v[24:27], v[28:31], a[100:103]
	v_mfma_f32_16x16x32_f16 a[92:95], v[16:19], v[28:31], a[92:95]
	s_waitcnt vmcnt(6)
	ds_write_b128 v41, v[144:147] offset:23040
	s_waitcnt lgkmcnt(14)
	v_mfma_f32_16x16x32_f16 a[76:79], v[36:39], v[12:15], a[76:79]
	v_mfma_f32_16x16x32_f16 a[72:75], v[32:35], v[12:15], a[72:75]
	s_waitcnt vmcnt(3)
	ds_write_b128 v41, v[148:151] offset:27648
	v_mfma_f32_16x16x32_f16 a[68:71], v[24:27], v[12:15], a[68:71]
	v_mfma_f32_16x16x32_f16 a[64:67], v[16:19], v[12:15], a[64:67]
	s_waitcnt vmcnt(2)
	ds_write_b128 v41, v[156:159] offset:32256
	s_waitcnt lgkmcnt(14)
	v_mfma_f32_16x16x32_f16 a[60:63], v[36:39], v[4:7], a[60:63]
	v_mfma_f32_16x16x32_f16 a[56:59], v[32:35], v[4:7], a[56:59]
	s_waitcnt vmcnt(7)
	ds_write_b128 v41, v[116:119] offset:36864
	v_mfma_f32_16x16x32_f16 a[52:55], v[24:27], v[4:7], a[52:55]
	v_mfma_f32_16x16x32_f16 a[48:51], v[16:19], v[4:7], a[48:51]
	s_waitcnt vmcnt(6)
	ds_write_b128 v41, v[124:127] offset:41472
	s_waitcnt lgkmcnt(14)
	v_mfma_f32_16x16x32_f16 a[44:47], v[36:39], v[0:3], a[44:47]
	v_mfma_f32_16x16x32_f16 a[40:43], v[32:35], v[0:3], a[40:43]
	s_waitcnt vmcnt(5)
	ds_write_b128 v41, v[132:135] offset:46080
	v_mfma_f32_16x16x32_f16 a[36:39], v[24:27], v[0:3], a[36:39]
	v_mfma_f32_16x16x32_f16 a[32:35], v[16:19], v[0:3], a[32:35]
	s_waitcnt vmcnt(4)
	ds_write_b128 v41, v[140:143] offset:50688
	s_waitcnt lgkmcnt(14)
	v_mfma_f32_16x16x32_f16 a[28:31], v[36:39], v[8:11], a[28:31]
	v_mfma_f32_16x16x32_f16 a[24:27], v[32:35], v[8:11], a[24:27]
	s_waitcnt vmcnt(3)
	ds_write_b128 v41, v[152:155] offset:55296
	v_mfma_f32_16x16x32_f16 a[20:23], v[24:27], v[8:11], a[20:23]
	v_mfma_f32_16x16x32_f16 a[16:19], v[16:19], v[8:11], a[16:19]
	s_waitcnt vmcnt(2)
	ds_write_b128 v41, v[160:163] offset:59904
	s_waitcnt lgkmcnt(14)
	v_mfma_f32_16x16x32_f16 a[12:15], v[36:39], v[20:23], a[12:15]
	v_mfma_f32_16x16x32_f16 a[8:11], v[32:35], v[20:23], a[8:11]
	s_waitcnt vmcnt(1)
	ds_write_b128 v41, v[164:167] offset:64512
	v_mfma_f32_16x16x32_f16 a[4:7], v[24:27], v[20:23], a[4:7]
	v_mfma_f32_16x16x32_f16 a[0:3], v[16:19], v[20:23], a[0:3]
	v_add_u32_e32 v16, v40, v99
	s_waitcnt vmcnt(0)
	ds_write_b128 v16, v[168:171]
	ds_read_b128 v[60:63], v64 offset:64
	ds_read_b128 v[52:55], v64 offset:2368
	ds_read_b128 v[48:51], v64 offset:4672
	ds_read_b128 v[40:43], v64 offset:6976
	ds_read_b128 v[36:39], v64 offset:9280
	ds_read_b128 v[32:35], v64 offset:11584
	ds_read_b128 v[24:27], v64 offset:13888
	ds_read_b128 v[16:19], v64 offset:16192
	ds_read_b128 v[64:67], v106 offset:36928
	ds_read_b128 v[68:71], v106 offset:39232
	ds_read_b128 v[72:75], v106 offset:41536
	ds_read_b128 v[76:79], v106 offset:43840
	s_cmp_gt_u32 s14, 29
	s_cbranch_scc1 .Lgw17_nl
; #define MMA_BLK(afx, bfx, nh_) _Pragma("unroll") for (int mi = 0; mi < 8; ++mi) _Pragma("unroll") for (int ni = 0; ni < 4; ++ni) mfma16_acc(acc[mi][(nh_) * 4 + ni], bfx[ni], afx[mi])
; template <class Epi>
; __device__ __forceinline__ void gemm_run(const GemmArgs g, Epi epi, char* smem) {
;     ...
;       MMA_BLK(afA, bfB, 1);
;       __builtin_amdgcn_sched_barrier(0);
;       if (kt + 2 < nk) {
;         const int ko = (kt + 2) * 64;
; #pragma unroll
;         for (int i = 0; i < 8; ++i) { ra[i] = __builtin_amdgcn_raw_buffer_load_b128(Ars, aoff, i * astep + ko * 2, 0); rb[i] = __builtin_amdgcn_raw_buffer_load_b128(Brs, boff, i * bstep + ko * 2, 0); }
;       }
	s_waitcnt lgkmcnt(14)
	v_mfma_f32_16x16x32_f16 a[252:255], v[172:175], v[56:59], a[252:255]
	s_waitcnt lgkmcnt(14)
	v_mfma_f32_16x16x32_f16 a[248:251], v[88:91], v[56:59], a[248:251]
	s_waitcnt lgkmcnt(14)
	v_mfma_f32_16x16x32_f16 a[244:247], v[84:87], v[56:59], a[244:247]
	s_add_i32 s59, s1, 0xfff20000
	s_waitcnt lgkmcnt(14)
	v_mfma_f32_16x16x32_f16 a[240:243], v[80:83], v[56:59], a[240:243]
	s_mov_b32 s14, s10
	v_mfma_f32_16x16x32_f16 a[236:239], v[172:175], v[44:47], a[236:239]
	s_mov_b32 s15, s11
	v_mfma_f32_16x16x32_f16 a[232:235], v[88:91], v[44:47], a[232:235]
	s_add_i32 s62, s1, 0xfff40000
	v_mfma_f32_16x16x32_f16 a[228:231], v[84:87], v[44:47], a[228:231]
	buffer_load_dwordx4 v[108:111], v92, s[8:11], s59 offen
	v_mfma_f32_16x16x32_f16 a[224:227], v[80:83], v[44:47], a[224:227]
	buffer_load_dwordx4 v[112:115], v92, s[8:11], s62 offen
	v_mfma_f32_16x16x32_f16 a[220:223], v[172:175], v[28:31], a[220:223]
	buffer_load_dwordx4 v[116:119], v92, s[12:15], s59 offen
	v_mfma_f32_16x16x32_f16 a[216:219], v[88:91], v[28:31], a[216:219]
	buffer_load_dwordx4 v[124:127], v92, s[12:15], s62 offen
	v_mfma_f32_16x16x32_f16 a[212:215], v[84:87], v[28:31], a[212:215]
	s_add_i32 s59, s1, 0xfff60000
	v_mfma_f32_16x16x32_f16 a[208:211], v[80:83], v[28:31], a[208:211]
	s_add_i32 s62, s1, 0xfff80000
	v_mfma_f32_16x16x32_f16 a[204:207], v[172:175], v[12:15], a[204:207]
	buffer_load_dwordx4 v[120:123], v92, s[8:11], s59 offen
	v_mfma_f32_16x16x32_f16 a[200:203], v[88:91], v[12:15], a[200:203]
	buffer_load_dwordx4 v[128:131], v92, s[8:11], s62 offen
	v_mfma_f32_16x16x32_f16 a[196:199], v[84:87], v[12:15], a[196:199]
	buffer_load_dwordx4 v[132:135], v92, s[12:15], s59 offen
	v_mfma_f32_16x16x32_f16 a[192:195], v[80:83], v[12:15], a[192:195]
	buffer_load_dwordx4 v[140:143], v92, s[12:15], s62 offen
	v_mfma_f32_16x16x32_f16 a[188:191], v[172:175], v[4:7], a[188:191]
	s_add_i32 s59, s1, 0xfffa0000
	v_mfma_f32_16x16x32_f16 a[184:187], v[88:91], v[4:7], a[184:187]
	s_add_i32 s62, s1, 0xfffc0000
	v_mfma_f32_16x16x32_f16 a[180:183], v[84:87], v[4:7], a[180:183]
	buffer_load_dwordx4 v[136:139], v92, s[8:11], s59 offen
	v_mfma_f32_16x16x32_f16 a[176:179], v[80:83], v[4:7], a[176:179]
	buffer_load_dwordx4 v[144:147], v92, s[8:11], s62 offen
	v_mfma_f32_16x16x32_f16 a[172:175], v[172:175], v[0:3], a[172:175]
	buffer_load_dwordx4 v[152:155], v92, s[12:15], s59 offen
	v_mfma_f32_16x16x32_f16 a[168:171], v[88:91], v[0:3], a[168:171]
	buffer_load_dwordx4 v[160:163], v92, s[12:15], s62 offen
	v_mfma_f32_16x16x32_f16 a[164:167], v[84:87], v[0:3], a[164:167]
	s_add_i32 s59, s1, 0xfffe0000
	v_mfma_f32_16x16x32_f16 a[156:159], v[80:83], v[0:3], a[156:159]
	buffer_load_dwordx4 v[148:151], v92, s[8:11], s59 offen
	v_mfma_f32_16x16x32_f16 a[140:143], v[172:175], v[8:11], a[140:143]
	buffer_load_dwordx4 v[156:159], v92, s[8:11], s1 offen
	v_mfma_f32_16x16x32_f16 a[132:135], v[88:91], v[8:11], a[132:135]
	buffer_load_dwordx4 v[164:167], v92, s[12:15], s59 offen
	v_mfma_f32_16x16x32_f16 a[128:131], v[84:87], v[8:11], a[128:131]
	buffer_load_dwordx4 v[168:171], v92, s[12:15], s1 offen
	v_mfma_f32_16x16x32_f16 a[124:127], v[80:83], v[8:11], a[124:127]
	v_mfma_f32_16x16x32_f16 a[96:99], v[172:175], v[20:23], a[96:99]
	v_mfma_f32_16x16x32_f16 a[88:91], v[88:91], v[20:23], a[88:91]
	v_mfma_f32_16x16x32_f16 a[84:87], v[84:87], v[20:23], a[84:87]
	v_mfma_f32_16x16x32_f16 a[80:83], v[80:83], v[20:23], a[80:83]
	s_branch .LBB0_2108

; #define LD_AF(dst, ks_) _Pragma("unroll") for (int i = 0; i < 8; ++i) dst[i] = *(const h8*)(sA + i * 16 * G_LD + (ks_) * 32)
; #define LD_BF(dst, ks_, nh_) _Pragma("unroll") for (int i = 0; i < 4; ++i) dst[i] = *(const h8*)(sB + ((nh_) * 4 + i) * 16 * G_LD + (ks_) * 32)
; #define MMA_BLK(afx, bfx, nh_) _Pragma("unroll") for (int mi = 0; mi < 8; ++mi) _Pragma("unroll") for (int ni = 0; ni < 4; ++ni) mfma16_acc(acc[mi][(nh_) * 4 + ni], bfx[ni], afx[mi])
; template <class Epi>
; __device__ __forceinline__ void gemm_run(const GemmArgs g, Epi epi, char* smem) {
;     ...
;       const hf* sA = sbase + (kt & 1) * G_STAGE + (wm * 128 + fr) * G_LD + fqs;
;       const hf* sB = sbase + (kt & 1) * G_STAGE + (256 + wn * 128 + fr) * G_LD + fqs;
;       hf* st = sbase + ((kt + 1) & 1) * G_STAGE;
;       h8 afA[8], afB[8], bfA[4], bfB[4];
;     ...
;       LD_AF(afA, 0); LD_BF(bfA, 0, 0);
;       if (kt + 1 < nk) {
; #pragma unroll
;         for (int i = 0; i < 8; ++i) *(u4*)(st + (lr + 32 * i) * G_LD + lcw) = ra[i];
;       }
;       __builtin_amdgcn_sched_barrier(0);
;       LD_BF(bfB, 0, 1);
;       MMA_BLK(afA, bfA, 0);
;       __builtin_amdgcn_sched_barrier(0);
;       if (kt + 1 < nk) {
; #pragma unroll
;         for (int i = 0; i < 8; ++i) *(u4*)(st + (256 + lr + 32 * i) * G_LD + lcw) = rb[i];
;       }
;       LD_AF(afB, 1); LD_BF(bfA, 1, 0);
.LBB0_2160:
	s_bitcmp1_b32 s55, 0
	s_cselect_b32 s15, 0x12000, 0
	s_add_i32 s15, s15, 16
	v_add3_u32 v92, s15, v130, v137
	v_add3_u32 v64, s15, v129, v137
	ds_read_b128 v[36:39], v92 offset:36864
	ds_read_b128 v[56:59], v64
	ds_read_b128 v[32:35], v92 offset:39168
	ds_read_b128 v[24:27], v92 offset:41472
	ds_read_b128 v[16:19], v92 offset:43776
	ds_read_b128 v[44:47], v64 offset:2304
	ds_read_b128 v[28:31], v64 offset:4608
	ds_read_b128 v[12:15], v64 offset:6912
	ds_read_b128 v[4:7], v64 offset:9216
	ds_read_b128 v[0:3], v64 offset:11520
	ds_read_b128 v[8:11], v64 offset:13824
	ds_read_b128 v[20:23], v64 offset:16128
	s_mov_b32 s14, s55
	s_add_i32 s55, s55, 1
	s_bitcmp1_b32 s55, 0
	s_cselect_b32 s58, 0x12000, 0
	v_add_u32_e32 v40, s58, v127
	v_add_u32_e32 v41, v40, v132
	ds_read_b128 v[170:173], v92 offset:46080
	ds_read_b128 v[88:91], v92 offset:48384
	ds_read_b128 v[84:87], v92 offset:50688
	ds_read_b128 v[80:83], v92 offset:52992
	s_waitcnt lgkmcnt(14)
	v_mfma_f32_16x16x32_f16 a[208:211], v[36:39], v[56:59], a[208:211]
	s_waitcnt lgkmcnt(13)
	v_mfma_f32_16x16x32_f16 a[200:203], v[32:35], v[56:59], a[200:203]
	s_waitcnt vmcnt(15)
	ds_write_b128 v41, v[94:97]
	s_waitcnt lgkmcnt(13)
	v_mfma_f32_16x16x32_f16 a[196:199], v[24:27], v[56:59], a[196:199]
	s_waitcnt lgkmcnt(12)
	v_mfma_f32_16x16x32_f16 a[192:195], v[16:19], v[56:59], a[192:195]
	s_waitcnt vmcnt(14)
	ds_write_b128 v41, v[98:101] offset:4608
	s_waitcnt lgkmcnt(12)
	v_mfma_f32_16x16x32_f16 a[188:191], v[36:39], v[44:47], a[188:191]
	v_mfma_f32_16x16x32_f16 a[184:187], v[32:35], v[44:47], a[184:187]
	s_waitcnt vmcnt(11)
	ds_write_b128 v41, v[106:109] offset:9216
	v_mfma_f32_16x16x32_f16 a[180:183], v[24:27], v[44:47], a[180:183]
	v_mfma_f32_16x16x32_f16 a[176:179], v[16:19], v[44:47], a[176:179]
	s_waitcnt vmcnt(10)
	ds_write_b128 v41, v[114:117] offset:13824
	s_waitcnt lgkmcnt(13)
	v_mfma_f32_16x16x32_f16 a[156:159], v[36:39], v[28:31], a[156:159]
	v_mfma_f32_16x16x32_f16 a[152:155], v[32:35], v[28:31], a[152:155]
	s_waitcnt vmcnt(7)
	ds_write_b128 v41, v[122:125] offset:18432
	v_mfma_f32_16x16x32_f16 a[148:151], v[24:27], v[28:31], a[148:151]
	v_mfma_f32_16x16x32_f16 a[144:147], v[16:19], v[28:31], a[144:147]
	s_waitcnt vmcnt(6)
	ds_write_b128 v41, v[142:145] offset:23040
	s_waitcnt lgkmcnt(14)
	v_mfma_f32_16x16x32_f16 a[124:127], v[36:39], v[12:15], a[124:127]
	v_mfma_f32_16x16x32_f16 a[120:123], v[32:35], v[12:15], a[120:123]
	s_waitcnt vmcnt(3)
	ds_write_b128 v41, v[146:149] offset:27648
	v_mfma_f32_16x16x32_f16 a[116:119], v[24:27], v[12:15], a[116:119]
	v_mfma_f32_16x16x32_f16 a[112:115], v[16:19], v[12:15], a[112:115]
	s_waitcnt vmcnt(2)
	ds_write_b128 v41, v[154:157] offset:32256
	s_waitcnt lgkmcnt(14)
	v_mfma_f32_16x16x32_f16 a[92:95], v[36:39], v[4:7], a[92:95]
	v_mfma_f32_16x16x32_f16 a[88:91], v[32:35], v[4:7], a[88:91]
	s_waitcnt vmcnt(7)
	ds_write_b128 v41, v[102:105] offset:36864
	v_mfma_f32_16x16x32_f16 a[84:87], v[24:27], v[4:7], a[84:87]
	v_mfma_f32_16x16x32_f16 a[80:83], v[16:19], v[4:7], a[80:83]
	s_waitcnt vmcnt(6)
	ds_write_b128 v41, v[110:113] offset:41472
	s_waitcnt lgkmcnt(14)
	v_mfma_f32_16x16x32_f16 a[60:63], v[36:39], v[0:3], a[60:63]
	v_mfma_f32_16x16x32_f16 a[56:59], v[32:35], v[0:3], a[56:59]
	s_waitcnt vmcnt(5)
	ds_write_b128 v41, v[118:121] offset:46080
	v_mfma_f32_16x16x32_f16 a[52:55], v[24:27], v[0:3], a[52:55]
	v_mfma_f32_16x16x32_f16 a[48:51], v[16:19], v[0:3], a[48:51]
	s_waitcnt vmcnt(4)
	ds_write_b128 v41, v[138:141] offset:50688
	s_waitcnt lgkmcnt(14)
	v_mfma_f32_16x16x32_f16 a[28:31], v[36:39], v[8:11], a[28:31]
	v_mfma_f32_16x16x32_f16 a[24:27], v[32:35], v[8:11], a[24:27]
	s_waitcnt vmcnt(3)
	ds_write_b128 v41, v[150:153] offset:55296
	v_mfma_f32_16x16x32_f16 a[20:23], v[24:27], v[8:11], a[20:23]
	v_mfma_f32_16x16x32_f16 a[16:19], v[16:19], v[8:11], a[16:19]
	s_waitcnt vmcnt(2)
	ds_write_b128 v41, v[158:161] offset:59904
	s_waitcnt lgkmcnt(14)
	v_mfma_f32_16x16x32_f16 a[12:15], v[36:39], v[20:23], a[12:15]
	v_mfma_f32_16x16x32_f16 a[8:11], v[32:35], v[20:23], a[8:11]
	s_waitcnt vmcnt(1)
	ds_write_b128 v41, v[162:165] offset:64512
	v_mfma_f32_16x16x32_f16 a[4:7], v[24:27], v[20:23], a[4:7]
	v_mfma_f32_16x16x32_f16 a[0:3], v[16:19], v[20:23], a[0:3]
	v_add_u32_e32 v16, v40, v133
	s_waitcnt vmcnt(0)
	ds_write_b128 v16, v[166:169]
	ds_read_b128 v[60:63], v64 offset:64
	ds_read_b128 v[52:55], v64 offset:2368
	ds_read_b128 v[48:51], v64 offset:4672
	ds_read_b128 v[40:43], v64 offset:6976
	ds_read_b128 v[36:39], v64 offset:9280
	ds_read_b128 v[32:35], v64 offset:11584
	ds_read_b128 v[24:27], v64 offset:13888
	ds_read_b128 v[16:19], v64 offset:16192
	ds_read_b128 v[64:67], v92 offset:36928
	ds_read_b128 v[68:71], v92 offset:39232
	ds_read_b128 v[72:75], v92 offset:41536
	ds_read_b128 v[76:79], v92 offset:43840
	s_cmpk_gt_u32 s14, 0x55
	s_cbranch_scc1 .Lgw18_nl
; #define MMA_BLK(afx, bfx, nh_) _Pragma("unroll") for (int mi = 0; mi < 8; ++mi) _Pragma("unroll") for (int ni = 0; ni < 4; ++ni) mfma16_acc(acc[mi][(nh_) * 4 + ni], bfx[ni], afx[mi])
; template <class Epi>
; __device__ __forceinline__ void gemm_run(const GemmArgs g, Epi epi, char* smem) {
;     ...
;       MMA_BLK(afA, bfB, 1);
;       __builtin_amdgcn_sched_barrier(0);
;       if (kt + 2 < nk) {
;         const int ko = (kt + 2) * 64;
; #pragma unroll
;         for (int i = 0; i < 8; ++i) { ra[i] = __builtin_amdgcn_raw_buffer_load_b128(Ars, aoff, i * astep + ko * 2, 0); rb[i] = __builtin_amdgcn_raw_buffer_load_b128(Brs, boff, i * bstep + ko * 2, 0); }
;       }
	s_waitcnt lgkmcnt(14)
	v_mfma_f32_16x16x32_f16 a[240:243], v[170:173], v[56:59], a[240:243]
	s_waitcnt lgkmcnt(14)
	v_mfma_f32_16x16x32_f16 a[252:255], v[88:91], v[56:59], a[252:255]
	s_waitcnt lgkmcnt(14)
	v_mfma_f32_16x16x32_f16 a[248:251], v[84:87], v[56:59], a[248:251]
	s_add_i32 s58, s54, 0xffd98000
	s_waitcnt lgkmcnt(14)
	v_mfma_f32_16x16x32_f16 a[244:247], v[80:83], v[56:59], a[244:247]
	s_mov_b32 s14, s10
	v_mfma_f32_16x16x32_f16 a[236:239], v[170:173], v[44:47], a[236:239]
	s_mov_b32 s15, s11
	v_mfma_f32_16x16x32_f16 a[232:235], v[88:91], v[44:47], a[232:235]
	s_add_i32 s59, s54, 0xffdf0000
	v_mfma_f32_16x16x32_f16 a[228:231], v[84:87], v[44:47], a[228:231]
	buffer_load_dwordx4 v[94:97], v126, s[8:11], s58 offen
	v_mfma_f32_16x16x32_f16 a[224:227], v[80:83], v[44:47], a[224:227]
	buffer_load_dwordx4 v[98:101], v126, s[8:11], s59 offen
	v_mfma_f32_16x16x32_f16 a[220:223], v[170:173], v[28:31], a[220:223]
	buffer_load_dwordx4 v[102:105], v126, s[12:15], s58 offen
	v_mfma_f32_16x16x32_f16 a[216:219], v[88:91], v[28:31], a[216:219]
	buffer_load_dwordx4 v[110:113], v126, s[12:15], s59 offen
	v_mfma_f32_16x16x32_f16 a[212:215], v[84:87], v[28:31], a[212:215]
	s_add_i32 s58, s54, 0xffe48000
	v_mfma_f32_16x16x32_f16 a[204:207], v[80:83], v[28:31], a[204:207]
	s_add_i32 s59, s54, 0xffea0000
	v_mfma_f32_16x16x32_f16 a[172:175], v[170:173], v[12:15], a[172:175]
	buffer_load_dwordx4 v[106:109], v126, s[8:11], s58 offen
	v_mfma_f32_16x16x32_f16 a[168:171], v[88:91], v[12:15], a[168:171]
	buffer_load_dwordx4 v[114:117], v126, s[8:11], s59 offen
	v_mfma_f32_16x16x32_f16 a[164:167], v[84:87], v[12:15], a[164:167]
	buffer_load_dwordx4 v[118:121], v126, s[12:15], s58 offen
	v_mfma_f32_16x16x32_f16 a[160:163], v[80:83], v[12:15], a[160:163]
	buffer_load_dwordx4 v[138:141], v126, s[12:15], s59 offen
	v_mfma_f32_16x16x32_f16 a[140:143], v[170:173], v[4:7], a[140:143]
	s_add_i32 s58, s54, 0xffef8000
	v_mfma_f32_16x16x32_f16 a[136:139], v[88:91], v[4:7], a[136:139]
	s_add_i32 s59, s54, 0xfff50000
	v_mfma_f32_16x16x32_f16 a[132:135], v[84:87], v[4:7], a[132:135]
	buffer_load_dwordx4 v[122:125], v126, s[8:11], s58 offen
	v_mfma_f32_16x16x32_f16 a[128:131], v[80:83], v[4:7], a[128:131]
	buffer_load_dwordx4 v[142:145], v126, s[8:11], s59 offen
	v_mfma_f32_16x16x32_f16 a[108:111], v[170:173], v[0:3], a[108:111]
	buffer_load_dwordx4 v[150:153], v126, s[12:15], s58 offen
	v_mfma_f32_16x16x32_f16 a[104:107], v[88:91], v[0:3], a[104:107]
	buffer_load_dwordx4 v[158:161], v126, s[12:15], s59 offen
	v_mfma_f32_16x16x32_f16 a[100:103], v[84:87], v[0:3], a[100:103]
	s_add_i32 s58, s54, 0xfffa8000
	v_mfma_f32_16x16x32_f16 a[96:99], v[80:83], v[0:3], a[96:99]
	buffer_load_dwordx4 v[146:149], v126, s[8:11], s58 offen
	v_mfma_f32_16x16x32_f16 a[76:79], v[170:173], v[8:11], a[76:79]
	buffer_load_dwordx4 v[154:157], v126, s[8:11], s54 offen
	v_mfma_f32_16x16x32_f16 a[72:75], v[88:91], v[8:11], a[72:75]
	buffer_load_dwordx4 v[162:165], v126, s[12:15], s58 offen
	v_mfma_f32_16x16x32_f16 a[68:71], v[84:87], v[8:11], a[68:71]
	buffer_load_dwordx4 v[166:169], v126, s[12:15], s54 offen
	v_mfma_f32_16x16x32_f16 a[64:67], v[80:83], v[8:11], a[64:67]
	v_mfma_f32_16x16x32_f16 a[44:47], v[170:173], v[20:23], a[44:47]
	v_mfma_f32_16x16x32_f16 a[40:43], v[88:91], v[20:23], a[40:43]
	v_mfma_f32_16x16x32_f16 a[36:39], v[84:87], v[20:23], a[36:39]
	v_mfma_f32_16x16x32_f16 a[32:35], v[80:83], v[20:23], a[32:35]
	s_branch .LBB0_2159
.Lgw18_nl:
	s_waitcnt lgkmcnt(14)
	v_mfma_f32_16x16x32_f16 a[240:243], v[170:173], v[56:59], a[240:243]
	s_waitcnt lgkmcnt(14)
	v_mfma_f32_16x16x32_f16 a[252:255], v[88:91], v[56:59], a[252:255]
	s_waitcnt lgkmcnt(14)
	v_mfma_f32_16x16x32_f16 a[248:251], v[84:87], v[56:59], a[248:251]
	s_waitcnt lgkmcnt(14)
	v_mfma_f32_16x16x32_f16 a[244:247], v[80:83], v[56:59], a[244:247]
	v_mfma_f32_16x16x32_f16 a[236:239], v[170:173], v[44:47], a[236:239]
	v_mfma_f32_16x16x32_f16 a[232:235], v[88:91], v[44:47], a[232:235]
	v_mfma_f32_16x16x32_f16 a[228:231], v[84:87], v[44:47], a[228:231]
	v_mfma_f32_16x16x32_f16 a[224:227], v[80:83], v[44:47], a[224:227]
	v_mfma_f32_16x16x32_f16 a[220:223], v[170:173], v[28:31], a[220:223]
	v_mfma_f32_16x16x32_f16 a[216:219], v[88:91], v[28:31], a[216:219]
	v_mfma_f32_16x16x32_f16 a[212:215], v[84:87], v[28:31], a[212:215]
	v_mfma_f32_16x16x32_f16 a[204:207], v[80:83], v[28:31], a[204:207]
	v_mfma_f32_16x16x32_f16 a[172:175], v[170:173], v[12:15], a[172:175]
	v_mfma_f32_16x16x32_f16 a[168:171], v[88:91], v[12:15], a[168:171]
	v_mfma_f32_16x16x32_f16 a[164:167], v[84:87], v[12:15], a[164:167]
	v_mfma_f32_16x16x32_f16 a[160:163], v[80:83], v[12:15], a[160:163]
	v_mfma_f32_16x16x32_f16 a[140:143], v[170:173], v[4:7], a[140:143]
	v_mfma_f32_16x16x32_f16 a[136:139], v[88:91], v[4:7], a[136:139]
	v_mfma_f32_16x16x32_f16 a[132:135], v[84:87], v[4:7], a[132:135]
	v_mfma_f32_16x16x32_f16 a[128:131], v[80:83], v[4:7], a[128:131]
	v_mfma_f32_16x16x32_f16 a[108:111], v[170:173], v[0:3], a[108:111]
	v_mfma_f32_16x16x32_f16 a[104:107], v[88:91], v[0:3], a[104:107]
	v_mfma_f32_16x16x32_f16 a[100:103], v[84:87], v[0:3], a[100:103]
	v_mfma_f32_16x16x32_f16 a[96:99], v[80:83], v[0:3], a[96:99]
	v_mfma_f32_16x16x32_f16 a[76:79], v[170:173], v[8:11], a[76:79]
	v_mfma_f32_16x16x32_f16 a[72:75], v[88:91], v[8:11], a[72:75]
	v_mfma_f32_16x16x32_f16 a[68:71], v[84:87], v[8:11], a[68:71]
	v_mfma_f32_16x16x32_f16 a[64:67], v[80:83], v[8:11], a[64:67]
	v_mfma_f32_16x16x32_f16 a[44:47], v[170:173], v[20:23], a[44:47]
	v_mfma_f32_16x16x32_f16 a[40:43], v[88:91], v[20:23], a[40:43]
	v_mfma_f32_16x16x32_f16 a[36:39], v[84:87], v[20:23], a[36:39]
	v_mfma_f32_16x16x32_f16 a[32:35], v[80:83], v[20:23], a[32:35]
	s_branch .LBB0_2159

; #define LD_AF(dst, ks_) _Pragma("unroll") for (int i = 0; i < 8; ++i) dst[i] = *(const h8*)(sA + i * 16 * G_LD + (ks_) * 32)
; #define LD_BF(dst, ks_, nh_) _Pragma("unroll") for (int i = 0; i < 4; ++i) dst[i] = *(const h8*)(sB + ((nh_) * 4 + i) * 16 * G_LD + (ks_) * 32)
; #define MMA_BLK(afx, bfx, nh_) _Pragma("unroll") for (int mi = 0; mi < 8; ++mi) _Pragma("unroll") for (int ni = 0; ni < 4; ++ni) mfma16_acc(acc[mi][(nh_) * 4 + ni], bfx[ni], afx[mi])
; template <class Epi>
; __device__ __forceinline__ void gemm_run(const GemmArgs g, Epi epi, char* smem) {
;     ...
;       const hf* sA = sbase + (kt & 1) * G_STAGE + (wm * 128 + fr) * G_LD + fqs;
;       const hf* sB = sbase + (kt & 1) * G_STAGE + (256 + wn * 128 + fr) * G_LD + fqs;
;       hf* st = sbase + ((kt + 1) & 1) * G_STAGE;
;       h8 afA[8], afB[8], bfA[4], bfB[4];
;     ...
;       LD_AF(afA, 0); LD_BF(bfA, 0, 0);
;       if (kt + 1 < nk) {
; #pragma unroll
;         for (int i = 0; i < 8; ++i) *(u4*)(st + (lr + 32 * i) * G_LD + lcw) = ra[i];
;       }
;       __builtin_amdgcn_sched_barrier(0);
;       LD_BF(bfB, 0, 1);
;       MMA_BLK(afA, bfA, 0);
;       __builtin_amdgcn_sched_barrier(0);
;       if (kt + 1 < nk) {
; #pragma unroll
;         for (int i = 0; i < 8; ++i) *(u4*)(st + (256 + lr + 32 * i) * G_LD + lcw) = rb[i];
;       }
;       LD_AF(afB, 1); LD_BF(bfA, 1, 0);
.LBB0_2166:
	s_bitcmp1_b32 s5, 0
	s_mov_b32 s14, s5
	s_cselect_b32 s5, 0x12000, 0
	s_add_i32 s15, s5, 16
	v_add3_u32 v106, s15, v96, v105
	v_add3_u32 v64, s15, v94, v105
	ds_read_b128 v[36:39], v106 offset:36864
	ds_read_b128 v[56:59], v64
	ds_read_b128 v[32:35], v106 offset:39168
	ds_read_b128 v[24:27], v106 offset:41472
	ds_read_b128 v[16:19], v106 offset:43776
	ds_read_b128 v[44:47], v64 offset:2304
	ds_read_b128 v[28:31], v64 offset:4608
	ds_read_b128 v[12:15], v64 offset:6912
	ds_read_b128 v[4:7], v64 offset:9216
	ds_read_b128 v[0:3], v64 offset:11520
	ds_read_b128 v[8:11], v64 offset:13824
	ds_read_b128 v[20:23], v64 offset:16128
	s_add_i32 s5, s14, 1
	s_bitcmp1_b32 s5, 0
	s_cselect_b32 s55, 0x12000, 0
	v_add_u32_e32 v40, s55, v93
	v_add_u32_e32 v41, v40, v98
	ds_read_b128 v[172:175], v106 offset:46080
	ds_read_b128 v[88:91], v106 offset:48384
	ds_read_b128 v[84:87], v106 offset:50688
	ds_read_b128 v[80:83], v106 offset:52992
	s_waitcnt lgkmcnt(14)
	v_mfma_f32_16x16x32_f16 a[120:123], v[36:39], v[56:59], a[120:123]
	s_waitcnt lgkmcnt(13)
	v_mfma_f32_16x16x32_f16 a[116:119], v[32:35], v[56:59], a[116:119]
	s_waitcnt vmcnt(15)
	ds_write_b128 v41, v[108:111]
	s_waitcnt lgkmcnt(13)
	v_mfma_f32_16x16x32_f16 a[112:115], v[24:27], v[56:59], a[112:115]
	s_waitcnt lgkmcnt(12)
	v_mfma_f32_16x16x32_f16 a[160:163], v[16:19], v[56:59], a[160:163]
	s_waitcnt vmcnt(14)
	ds_write_b128 v41, v[112:115] offset:4608
	s_waitcnt lgkmcnt(12)
	v_mfma_f32_16x16x32_f16 a[152:155], v[36:39], v[44:47], a[152:155]
	v_mfma_f32_16x16x32_f16 a[148:151], v[32:35], v[44:47], a[148:151]
	s_waitcnt vmcnt(11)
	ds_write_b128 v41, v[120:123] offset:9216
	v_mfma_f32_16x16x32_f16 a[144:147], v[24:27], v[44:47], a[144:147]
	v_mfma_f32_16x16x32_f16 a[136:139], v[16:19], v[44:47], a[136:139]
	s_waitcnt vmcnt(10)
	ds_write_b128 v41, v[128:131] offset:13824
	s_waitcnt lgkmcnt(13)
	v_mfma_f32_16x16x32_f16 a[108:111], v[36:39], v[28:31], a[108:111]
	v_mfma_f32_16x16x32_f16 a[104:107], v[32:35], v[28:31], a[104:107]
	s_waitcnt vmcnt(7)
	ds_write_b128 v41, v[136:139] offset:18432
	v_mfma_f32_16x16x32_f16 a[100:103], v[24:27], v[28:31], a[100:103]
	v_mfma_f32_16x16x32_f16 a[92:95], v[16:19], v[28:31], a[92:95]
	s_waitcnt vmcnt(6)
	ds_write_b128 v41, v[144:147] offset:23040
	s_waitcnt lgkmcnt(14)
	v_mfma_f32_16x16x32_f16 a[76:79], v[36:39], v[12:15], a[76:79]
	v_mfma_f32_16x16x32_f16 a[72:75], v[32:35], v[12:15], a[72:75]
	s_waitcnt vmcnt(3)
	ds_write_b128 v41, v[148:151] offset:27648
	v_mfma_f32_16x16x32_f16 a[68:71], v[24:27], v[12:15], a[68:71]
	v_mfma_f32_16x16x32_f16 a[64:67], v[16:19], v[12:15], a[64:67]
	s_waitcnt vmcnt(2)
	ds_write_b128 v41, v[156:159] offset:32256
	s_waitcnt lgkmcnt(14)
	v_mfma_f32_16x16x32_f16 a[60:63], v[36:39], v[4:7], a[60:63]
	v_mfma_f32_16x16x32_f16 a[56:59], v[32:35], v[4:7], a[56:59]
	s_waitcnt vmcnt(7)
	ds_write_b128 v41, v[116:119] offset:36864
	v_mfma_f32_16x16x32_f16 a[52:55], v[24:27], v[4:7], a[52:55]
	v_mfma_f32_16x16x32_f16 a[48:51], v[16:19], v[4:7], a[48:51]
	s_waitcnt vmcnt(6)
	ds_write_b128 v41, v[124:127] offset:41472
	s_waitcnt lgkmcnt(14)
	v_mfma_f32_16x16x32_f16 a[44:47], v[36:39], v[0:3], a[44:47]
	v_mfma_f32_16x16x32_f16 a[40:43], v[32:35], v[0:3], a[40:43]
	s_waitcnt vmcnt(5)
	ds_write_b128 v41, v[132:135] offset:46080
	v_mfma_f32_16x16x32_f16 a[36:39], v[24:27], v[0:3], a[36:39]
	v_mfma_f32_16x16x32_f16 a[32:35], v[16:19], v[0:3], a[32:35]
	s_waitcnt vmcnt(4)
	ds_write_b128 v41, v[140:143] offset:50688
	s_waitcnt lgkmcnt(14)
	v_mfma_f32_16x16x32_f16 a[28:31], v[36:39], v[8:11], a[28:31]
	v_mfma_f32_16x16x32_f16 a[24:27], v[32:35], v[8:11], a[24:27]
	s_waitcnt vmcnt(3)
	ds_write_b128 v41, v[152:155] offset:55296
	v_mfma_f32_16x16x32_f16 a[20:23], v[24:27], v[8:11], a[20:23]
	v_mfma_f32_16x16x32_f16 a[16:19], v[16:19], v[8:11], a[16:19]
	s_waitcnt vmcnt(2)
	ds_write_b128 v41, v[160:163] offset:59904
	s_waitcnt lgkmcnt(14)
	v_mfma_f32_16x16x32_f16 a[12:15], v[36:39], v[20:23], a[12:15]
	v_mfma_f32_16x16x32_f16 a[8:11], v[32:35], v[20:23], a[8:11]
	s_waitcnt vmcnt(1)
	ds_write_b128 v41, v[164:167] offset:64512
	v_mfma_f32_16x16x32_f16 a[4:7], v[24:27], v[20:23], a[4:7]
	v_mfma_f32_16x16x32_f16 a[0:3], v[16:19], v[20:23], a[0:3]
	v_add_u32_e32 v16, v40, v99
	s_waitcnt vmcnt(0)
	ds_write_b128 v16, v[168:171]
	ds_read_b128 v[60:63], v64 offset:64
	ds_read_b128 v[52:55], v64 offset:2368
	ds_read_b128 v[48:51], v64 offset:4672
	ds_read_b128 v[40:43], v64 offset:6976
	ds_read_b128 v[36:39], v64 offset:9280
	ds_read_b128 v[32:35], v64 offset:11584
	ds_read_b128 v[24:27], v64 offset:13888
	ds_read_b128 v[16:19], v64 offset:16192
	ds_read_b128 v[64:67], v106 offset:36928
	ds_read_b128 v[68:71], v106 offset:39232
	ds_read_b128 v[72:75], v106 offset:41536
	ds_read_b128 v[76:79], v106 offset:43840
	s_cmp_gt_u32 s14, 29
	s_cbranch_scc1 .Lgw19_nl
; #define MMA_BLK(afx, bfx, nh_) _Pragma("unroll") for (int mi = 0; mi < 8; ++mi) _Pragma("unroll") for (int ni = 0; ni < 4; ++ni) mfma16_acc(acc[mi][(nh_) * 4 + ni], bfx[ni], afx[mi])
; template <class Epi>
; __device__ __forceinline__ void gemm_run(const GemmArgs g, Epi epi, char* smem) {
;     ...
;       MMA_BLK(afA, bfB, 1);
;       __builtin_amdgcn_sched_barrier(0);
;       if (kt + 2 < nk) {
;         const int ko = (kt + 2) * 64;
; #pragma unroll
;         for (int i = 0; i < 8; ++i) { ra[i] = __builtin_amdgcn_raw_buffer_load_b128(Ars, aoff, i * astep + ko * 2, 0); rb[i] = __builtin_amdgcn_raw_buffer_load_b128(Brs, boff, i * bstep + ko * 2, 0); }
;       }
	s_waitcnt lgkmcnt(14)
	v_mfma_f32_16x16x32_f16 a[252:255], v[172:175], v[56:59], a[252:255]
	s_waitcnt lgkmcnt(14)
	v_mfma_f32_16x16x32_f16 a[248:251], v[88:91], v[56:59], a[248:251]
	s_waitcnt lgkmcnt(14)
	v_mfma_f32_16x16x32_f16 a[244:247], v[84:87], v[56:59], a[244:247]
	s_add_i32 s55, s1, 0xfff20000
	s_waitcnt lgkmcnt(14)
	v_mfma_f32_16x16x32_f16 a[240:243], v[80:83], v[56:59], a[240:243]
	s_mov_b32 s14, s10
	v_mfma_f32_16x16x32_f16 a[236:239], v[172:175], v[44:47], a[236:239]
	s_mov_b32 s15, s11
	v_mfma_f32_16x16x32_f16 a[232:235], v[88:91], v[44:47], a[232:235]
	s_add_i32 s58, s1, 0xfff40000
	v_mfma_f32_16x16x32_f16 a[228:231], v[84:87], v[44:47], a[228:231]
	buffer_load_dwordx4 v[108:111], v92, s[8:11], s55 offen
	v_mfma_f32_16x16x32_f16 a[224:227], v[80:83], v[44:47], a[224:227]
	buffer_load_dwordx4 v[112:115], v92, s[8:11], s58 offen
	v_mfma_f32_16x16x32_f16 a[220:223], v[172:175], v[28:31], a[220:223]
	buffer_load_dwordx4 v[116:119], v92, s[12:15], s55 offen
	v_mfma_f32_16x16x32_f16 a[216:219], v[88:91], v[28:31], a[216:219]
	buffer_load_dwordx4 v[124:127], v92, s[12:15], s58 offen
	v_mfma_f32_16x16x32_f16 a[212:215], v[84:87], v[28:31], a[212:215]
	s_add_i32 s55, s1, 0xfff60000
	v_mfma_f32_16x16x32_f16 a[208:211], v[80:83], v[28:31], a[208:211]
	s_add_i32 s58, s1, 0xfff80000
	v_mfma_f32_16x16x32_f16 a[204:207], v[172:175], v[12:15], a[204:207]
	buffer_load_dwordx4 v[120:123], v92, s[8:11], s55 offen
	v_mfma_f32_16x16x32_f16 a[200:203], v[88:91], v[12:15], a[200:203]
	buffer_load_dwordx4 v[128:131], v92, s[8:11], s58 offen
	v_mfma_f32_16x16x32_f16 a[196:199], v[84:87], v[12:15], a[196:199]
	buffer_load_dwordx4 v[132:135], v92, s[12:15], s55 offen
	v_mfma_f32_16x16x32_f16 a[192:195], v[80:83], v[12:15], a[192:195]
	buffer_load_dwordx4 v[140:143], v92, s[12:15], s58 offen
	v_mfma_f32_16x16x32_f16 a[188:191], v[172:175], v[4:7], a[188:191]
	s_add_i32 s55, s1, 0xfffa0000
	v_mfma_f32_16x16x32_f16 a[184:187], v[88:91], v[4:7], a[184:187]
	s_add_i32 s58, s1, 0xfffc0000
	v_mfma_f32_16x16x32_f16 a[180:183], v[84:87], v[4:7], a[180:183]
	buffer_load_dwordx4 v[136:139], v92, s[8:11], s55 offen
	v_mfma_f32_16x16x32_f16 a[176:179], v[80:83], v[4:7], a[176:179]
	buffer_load_dwordx4 v[144:147], v92, s[8:11], s58 offen
	v_mfma_f32_16x16x32_f16 a[172:175], v[172:175], v[0:3], a[172:175]
	buffer_load_dwordx4 v[152:155], v92, s[12:15], s55 offen
	v_mfma_f32_16x16x32_f16 a[168:171], v[88:91], v[0:3], a[168:171]
	buffer_load_dwordx4 v[160:163], v92, s[12:15], s58 offen
	v_mfma_f32_16x16x32_f16 a[164:167], v[84:87], v[0:3], a[164:167]
	s_add_i32 s55, s1, 0xfffe0000
	v_mfma_f32_16x16x32_f16 a[156:159], v[80:83], v[0:3], a[156:159]
	buffer_load_dwordx4 v[148:151], v92, s[8:11], s55 offen
	v_mfma_f32_16x16x32_f16 a[140:143], v[172:175], v[8:11], a[140:143]
	buffer_load_dwordx4 v[156:159], v92, s[8:11], s1 offen
	v_mfma_f32_16x16x32_f16 a[132:135], v[88:91], v[8:11], a[132:135]
	buffer_load_dwordx4 v[164:167], v92, s[12:15], s55 offen
	v_mfma_f32_16x16x32_f16 a[128:131], v[84:87], v[8:11], a[128:131]
	buffer_load_dwordx4 v[168:171], v92, s[12:15], s1 offen
	v_mfma_f32_16x16x32_f16 a[124:127], v[80:83], v[8:11], a[124:127]
	v_mfma_f32_16x16x32_f16 a[96:99], v[172:175], v[20:23], a[96:99]
	v_mfma_f32_16x16x32_f16 a[88:91], v[88:91], v[20:23], a[88:91]
	v_mfma_f32_16x16x32_f16 a[84:87], v[84:87], v[20:23], a[84:87]
	v_mfma_f32_16x16x32_f16 a[80:83], v[80:83], v[20:23], a[80:83]
	s_branch .LBB0_2165

; #define LD_AF(dst, ks_) _Pragma("unroll") for (int i = 0; i < 8; ++i) dst[i] = *(const h8*)(sA + i * 16 * G_LD + (ks_) * 32)
; #define LD_BF(dst, ks_, nh_) _Pragma("unroll") for (int i = 0; i < 4; ++i) dst[i] = *(const h8*)(sB + ((nh_) * 4 + i) * 16 * G_LD + (ks_) * 32)
; #define MMA_BLK(afx, bfx, nh_) _Pragma("unroll") for (int mi = 0; mi < 8; ++mi) _Pragma("unroll") for (int ni = 0; ni < 4; ++ni) mfma16_acc(acc[mi][(nh_) * 4 + ni], bfx[ni], afx[mi])
; template <class Epi>
; __device__ __forceinline__ void gemm_run(const GemmArgs g, Epi epi, char* smem) {
;     ...
;       const hf* sA = sbase + (kt & 1) * G_STAGE + (wm * 128 + fr) * G_LD + fqs;
;       const hf* sB = sbase + (kt & 1) * G_STAGE + (256 + wn * 128 + fr) * G_LD + fqs;
;       hf* st = sbase + ((kt + 1) & 1) * G_STAGE;
;       h8 afA[8], afB[8], bfA[4], bfB[4];
;     ...
;       LD_AF(afA, 0); LD_BF(bfA, 0, 0);
;       if (kt + 1 < nk) {
; #pragma unroll
;         for (int i = 0; i < 8; ++i) *(u4*)(st + (lr + 32 * i) * G_LD + lcw) = ra[i];
;       }
;       __builtin_amdgcn_sched_barrier(0);
;       LD_BF(bfB, 0, 1);
;       MMA_BLK(afA, bfA, 0);
;       __builtin_amdgcn_sched_barrier(0);
;       if (kt + 1 < nk) {
; #pragma unroll
;         for (int i = 0; i < 8; ++i) *(u4*)(st + (256 + lr + 32 * i) * G_LD + lcw) = rb[i];
;       }
;       LD_AF(afB, 1); LD_BF(bfA, 1, 0);
.LBB0_2217:
	s_bitcmp1_b32 s38, 0
	s_cselect_b32 s11, 0x12000, 0
	s_add_i32 s11, s11, 16
	v_add3_u32 v92, s11, v130, v137
	v_add3_u32 v64, s11, v129, v137
	ds_read_b128 v[36:39], v92 offset:36864
	ds_read_b128 v[56:59], v64
	ds_read_b128 v[32:35], v92 offset:39168
	ds_read_b128 v[24:27], v92 offset:41472
	ds_read_b128 v[16:19], v92 offset:43776
	ds_read_b128 v[44:47], v64 offset:2304
	ds_read_b128 v[28:31], v64 offset:4608
	ds_read_b128 v[12:15], v64 offset:6912
	ds_read_b128 v[4:7], v64 offset:9216
	ds_read_b128 v[0:3], v64 offset:11520
	ds_read_b128 v[8:11], v64 offset:13824
	ds_read_b128 v[20:23], v64 offset:16128
	s_mov_b32 s10, s38
	s_add_i32 s38, s38, 1
	s_bitcmp1_b32 s38, 0
	s_cselect_b32 s39, 0x12000, 0
	v_add_u32_e32 v40, s39, v127
	v_add_u32_e32 v41, v40, v132
	ds_read_b128 v[170:173], v92 offset:46080
	ds_read_b128 v[88:91], v92 offset:48384
	ds_read_b128 v[84:87], v92 offset:50688
	ds_read_b128 v[80:83], v92 offset:52992
	s_waitcnt lgkmcnt(14)
	v_mfma_f32_16x16x32_f16 a[208:211], v[36:39], v[56:59], a[208:211]
	s_waitcnt lgkmcnt(13)
	v_mfma_f32_16x16x32_f16 a[200:203], v[32:35], v[56:59], a[200:203]
	s_waitcnt vmcnt(15)
	ds_write_b128 v41, v[94:97]
	s_waitcnt lgkmcnt(13)
	v_mfma_f32_16x16x32_f16 a[196:199], v[24:27], v[56:59], a[196:199]
	s_waitcnt lgkmcnt(12)
	v_mfma_f32_16x16x32_f16 a[192:195], v[16:19], v[56:59], a[192:195]
	s_waitcnt vmcnt(14)
	ds_write_b128 v41, v[98:101] offset:4608
	s_waitcnt lgkmcnt(12)
	v_mfma_f32_16x16x32_f16 a[188:191], v[36:39], v[44:47], a[188:191]
	v_mfma_f32_16x16x32_f16 a[184:187], v[32:35], v[44:47], a[184:187]
	s_waitcnt vmcnt(11)
	ds_write_b128 v41, v[106:109] offset:9216
	v_mfma_f32_16x16x32_f16 a[180:183], v[24:27], v[44:47], a[180:183]
	v_mfma_f32_16x16x32_f16 a[176:179], v[16:19], v[44:47], a[176:179]
	s_waitcnt vmcnt(10)
	ds_write_b128 v41, v[114:117] offset:13824
	s_waitcnt lgkmcnt(13)
	v_mfma_f32_16x16x32_f16 a[156:159], v[36:39], v[28:31], a[156:159]
	v_mfma_f32_16x16x32_f16 a[152:155], v[32:35], v[28:31], a[152:155]
	s_waitcnt vmcnt(7)
	ds_write_b128 v41, v[122:125] offset:18432
	v_mfma_f32_16x16x32_f16 a[148:151], v[24:27], v[28:31], a[148:151]
	v_mfma_f32_16x16x32_f16 a[144:147], v[16:19], v[28:31], a[144:147]
	s_waitcnt vmcnt(6)
	ds_write_b128 v41, v[142:145] offset:23040
	s_waitcnt lgkmcnt(14)
	v_mfma_f32_16x16x32_f16 a[124:127], v[36:39], v[12:15], a[124:127]
	v_mfma_f32_16x16x32_f16 a[120:123], v[32:35], v[12:15], a[120:123]
	s_waitcnt vmcnt(3)
	ds_write_b128 v41, v[146:149] offset:27648
	v_mfma_f32_16x16x32_f16 a[116:119], v[24:27], v[12:15], a[116:119]
	v_mfma_f32_16x16x32_f16 a[112:115], v[16:19], v[12:15], a[112:115]
	s_waitcnt vmcnt(2)
	ds_write_b128 v41, v[154:157] offset:32256
	s_waitcnt lgkmcnt(14)
	v_mfma_f32_16x16x32_f16 a[92:95], v[36:39], v[4:7], a[92:95]
	v_mfma_f32_16x16x32_f16 a[88:91], v[32:35], v[4:7], a[88:91]
	s_waitcnt vmcnt(7)
	ds_write_b128 v41, v[102:105] offset:36864
	v_mfma_f32_16x16x32_f16 a[84:87], v[24:27], v[4:7], a[84:87]
	v_mfma_f32_16x16x32_f16 a[80:83], v[16:19], v[4:7], a[80:83]
	s_waitcnt vmcnt(6)
	ds_write_b128 v41, v[110:113] offset:41472
	s_waitcnt lgkmcnt(14)
	v_mfma_f32_16x16x32_f16 a[60:63], v[36:39], v[0:3], a[60:63]
	v_mfma_f32_16x16x32_f16 a[56:59], v[32:35], v[0:3], a[56:59]
	s_waitcnt vmcnt(5)
	ds_write_b128 v41, v[118:121] offset:46080
	v_mfma_f32_16x16x32_f16 a[52:55], v[24:27], v[0:3], a[52:55]
	v_mfma_f32_16x16x32_f16 a[48:51], v[16:19], v[0:3], a[48:51]
	s_waitcnt vmcnt(4)
	ds_write_b128 v41, v[138:141] offset:50688
	s_waitcnt lgkmcnt(14)
	v_mfma_f32_16x16x32_f16 a[28:31], v[36:39], v[8:11], a[28:31]
	v_mfma_f32_16x16x32_f16 a[24:27], v[32:35], v[8:11], a[24:27]
	s_waitcnt vmcnt(3)
	ds_write_b128 v41, v[150:153] offset:55296
	v_mfma_f32_16x16x32_f16 a[20:23], v[24:27], v[8:11], a[20:23]
	v_mfma_f32_16x16x32_f16 a[16:19], v[16:19], v[8:11], a[16:19]
	s_waitcnt vmcnt(2)
	ds_write_b128 v41, v[158:161] offset:59904
	s_waitcnt lgkmcnt(14)
	v_mfma_f32_16x16x32_f16 a[12:15], v[36:39], v[20:23], a[12:15]
	v_mfma_f32_16x16x32_f16 a[8:11], v[32:35], v[20:23], a[8:11]
	s_waitcnt vmcnt(1)
	ds_write_b128 v41, v[162:165] offset:64512
	v_mfma_f32_16x16x32_f16 a[4:7], v[24:27], v[20:23], a[4:7]
	v_mfma_f32_16x16x32_f16 a[0:3], v[16:19], v[20:23], a[0:3]
	v_add_u32_e32 v16, v40, v133
	s_waitcnt vmcnt(0)
	ds_write_b128 v16, v[166:169]
	ds_read_b128 v[60:63], v64 offset:64
	ds_read_b128 v[52:55], v64 offset:2368
	ds_read_b128 v[48:51], v64 offset:4672
	ds_read_b128 v[40:43], v64 offset:6976
	ds_read_b128 v[36:39], v64 offset:9280
	ds_read_b128 v[32:35], v64 offset:11584
	ds_read_b128 v[24:27], v64 offset:13888
	ds_read_b128 v[16:19], v64 offset:16192
	ds_read_b128 v[64:67], v92 offset:36928
	ds_read_b128 v[68:71], v92 offset:39232
	ds_read_b128 v[72:75], v92 offset:41536
	ds_read_b128 v[76:79], v92 offset:43840
	s_cmpk_gt_u32 s10, 0x55
	s_cbranch_scc1 .Lgw20_nl
; #define MMA_BLK(afx, bfx, nh_) _Pragma("unroll") for (int mi = 0; mi < 8; ++mi) _Pragma("unroll") for (int ni = 0; ni < 4; ++ni) mfma16_acc(acc[mi][(nh_) * 4 + ni], bfx[ni], afx[mi])
; template <class Epi>
; __device__ __forceinline__ void gemm_run(const GemmArgs g, Epi epi, char* smem) {
;     ...
;       MMA_BLK(afA, bfB, 1);
;       __builtin_amdgcn_sched_barrier(0);
;       if (kt + 2 < nk) {
;         const int ko = (kt + 2) * 64;
; #pragma unroll
;         for (int i = 0; i < 8; ++i) { ra[i] = __builtin_amdgcn_raw_buffer_load_b128(Ars, aoff, i * astep + ko * 2, 0); rb[i] = __builtin_amdgcn_raw_buffer_load_b128(Brs, boff, i * bstep + ko * 2, 0); }
;       }
	s_waitcnt lgkmcnt(14)
	v_mfma_f32_16x16x32_f16 a[240:243], v[170:173], v[56:59], a[240:243]
	s_waitcnt lgkmcnt(14)
	v_mfma_f32_16x16x32_f16 a[252:255], v[88:91], v[56:59], a[252:255]
	s_waitcnt lgkmcnt(14)
	v_mfma_f32_16x16x32_f16 a[248:251], v[84:87], v[56:59], a[248:251]
	s_add_i32 s39, s37, 0xffd98000
	s_waitcnt lgkmcnt(14)
	v_mfma_f32_16x16x32_f16 a[244:247], v[80:83], v[56:59], a[244:247]
	s_mov_b32 s10, s6
	v_mfma_f32_16x16x32_f16 a[236:239], v[170:173], v[44:47], a[236:239]
	s_mov_b32 s11, s7
	v_mfma_f32_16x16x32_f16 a[232:235], v[88:91], v[44:47], a[232:235]
	s_add_i32 s40, s37, 0xffdf0000
	v_mfma_f32_16x16x32_f16 a[228:231], v[84:87], v[44:47], a[228:231]
	buffer_load_dwordx4 v[94:97], v126, s[4:7], s39 offen
	v_mfma_f32_16x16x32_f16 a[224:227], v[80:83], v[44:47], a[224:227]
	buffer_load_dwordx4 v[98:101], v126, s[4:7], s40 offen
	v_mfma_f32_16x16x32_f16 a[220:223], v[170:173], v[28:31], a[220:223]
	buffer_load_dwordx4 v[102:105], v126, s[8:11], s39 offen
	v_mfma_f32_16x16x32_f16 a[216:219], v[88:91], v[28:31], a[216:219]
	buffer_load_dwordx4 v[110:113], v126, s[8:11], s40 offen
	v_mfma_f32_16x16x32_f16 a[212:215], v[84:87], v[28:31], a[212:215]
	s_add_i32 s39, s37, 0xffe48000
	v_mfma_f32_16x16x32_f16 a[204:207], v[80:83], v[28:31], a[204:207]
	s_add_i32 s40, s37, 0xffea0000
	v_mfma_f32_16x16x32_f16 a[172:175], v[170:173], v[12:15], a[172:175]
	buffer_load_dwordx4 v[106:109], v126, s[4:7], s39 offen
	v_mfma_f32_16x16x32_f16 a[168:171], v[88:91], v[12:15], a[168:171]
	buffer_load_dwordx4 v[114:117], v126, s[4:7], s40 offen
	v_mfma_f32_16x16x32_f16 a[164:167], v[84:87], v[12:15], a[164:167]
	buffer_load_dwordx4 v[118:121], v126, s[8:11], s39 offen
	v_mfma_f32_16x16x32_f16 a[160:163], v[80:83], v[12:15], a[160:163]
	buffer_load_dwordx4 v[138:141], v126, s[8:11], s40 offen
	v_mfma_f32_16x16x32_f16 a[140:143], v[170:173], v[4:7], a[140:143]
	s_add_i32 s39, s37, 0xffef8000
	v_mfma_f32_16x16x32_f16 a[136:139], v[88:91], v[4:7], a[136:139]
	s_add_i32 s40, s37, 0xfff50000
	v_mfma_f32_16x16x32_f16 a[132:135], v[84:87], v[4:7], a[132:135]
	buffer_load_dwordx4 v[122:125], v126, s[4:7], s39 offen
	v_mfma_f32_16x16x32_f16 a[128:131], v[80:83], v[4:7], a[128:131]
	buffer_load_dwordx4 v[142:145], v126, s[4:7], s40 offen
	v_mfma_f32_16x16x32_f16 a[108:111], v[170:173], v[0:3], a[108:111]
	buffer_load_dwordx4 v[150:153], v126, s[8:11], s39 offen
	v_mfma_f32_16x16x32_f16 a[104:107], v[88:91], v[0:3], a[104:107]
	buffer_load_dwordx4 v[158:161], v126, s[8:11], s40 offen
	v_mfma_f32_16x16x32_f16 a[100:103], v[84:87], v[0:3], a[100:103]
	s_add_i32 s39, s37, 0xfffa8000
	v_mfma_f32_16x16x32_f16 a[96:99], v[80:83], v[0:3], a[96:99]
	buffer_load_dwordx4 v[146:149], v126, s[4:7], s39 offen
	v_mfma_f32_16x16x32_f16 a[76:79], v[170:173], v[8:11], a[76:79]
	buffer_load_dwordx4 v[154:157], v126, s[4:7], s37 offen
	v_mfma_f32_16x16x32_f16 a[72:75], v[88:91], v[8:11], a[72:75]
	buffer_load_dwordx4 v[162:165], v126, s[8:11], s39 offen
	v_mfma_f32_16x16x32_f16 a[68:71], v[84:87], v[8:11], a[68:71]
	buffer_load_dwordx4 v[166:169], v126, s[8:11], s37 offen
	v_mfma_f32_16x16x32_f16 a[64:67], v[80:83], v[8:11], a[64:67]
	v_mfma_f32_16x16x32_f16 a[44:47], v[170:173], v[20:23], a[44:47]
	v_mfma_f32_16x16x32_f16 a[40:43], v[88:91], v[20:23], a[40:43]
	v_mfma_f32_16x16x32_f16 a[36:39], v[84:87], v[20:23], a[36:39]
	v_mfma_f32_16x16x32_f16 a[32:35], v[80:83], v[20:23], a[32:35]
	s_branch .LBB0_2216
